# a+b plus code placement: 11 s_nop 0 pads so every 32-MFMA block of the K-loops starts at address 4 mod 8
# baseline (speedup 1.0000x reference)
; #define PG8_STAGE(bufoff, gbase, voff) do { const char* _gb = (const char*)(gbase); asm volatile("" : "+s"(_gb)); _Pragma("unroll") for (int _i = 0; _i < 2; ++_i) { asm volatile("" : "+v"((voff)[_i])); \
;         __builtin_amdgcn_global_load_lds((const unsigned*)(_gb + (voff)[_i]), (PG8_LAS unsigned*)(lds + (bufoff) + ldsw + _i * 8192), 16, 0, 0); } } while (0)
; #define PG8_LDA(dst, b, h) do { _Pragma("unroll") for (int m = 0; m < 4; ++m) _Pragma("unroll") for (int k = 0; k < 2; ++k) dst[m][k] = *(const PG8_LAS bf16x8*)(lds + PG8_SA(b, h) + aoff + m * 2048 + k * 1024); } while (0)
; #define PG8_LDB(dst, b, h) do { _Pragma("unroll") for (int n = 0; n < 2; ++n) _Pragma("unroll") for (int k = 0; k < 2; ++k) dst[n][k] = *(const PG8_LAS bf16x8*)(lds + PG8_SB(b, h) + boff + n * 2048 + k * 1024); } while (0)
; #define PG8_WAIT_V(n) asm volatile("s_waitcnt vmcnt(" #n ")" ::: "memory")
; #define PG8_WAIT_L(n) asm volatile("s_waitcnt lgkmcnt(" #n ")" ::: "memory")
; #define PG8_BAR __builtin_amdgcn_s_barrier()
; #define PG8_SCHED __builtin_amdgcn_sched_barrier(0)
; #define PG8_STAGE(bufoff, gbase, voff) do { const char* _gb = (const char*)(gbase); asm volatile("" : "+s"(_gb)); _Pragma("unroll") for (int _i = 0; _i < 2; ++_i) { asm volatile("" : "+v"((voff)[_i])); \
;         __builtin_amdgcn_global_load_lds((const unsigned*)(_gb + (voff)[_i]), (PG8_LAS unsigned*)(lds + (bufoff) + ldsw + _i * 8192), 16, 0, 0); } } while (0)
; #define PG8_LDA(dst, b, h) do { _Pragma("unroll") for (int m = 0; m < 4; ++m) _Pragma("unroll") for (int k = 0; k < 2; ++k) dst[m][k] = *(const PG8_LAS bf16x8*)(lds + PG8_SA(b, h) + aoff + m * 2048 + k * 1024); } while (0)
; #define PG8_WAIT_V(n) asm volatile("s_waitcnt vmcnt(" #n ")" ::: "memory")
; template <class Epi, class Sched, bool ALIGN_EPI = false, bool SP2 = false>
; __device__ __forceinline__ void gemm_phase(PG8_LAS unsigned char* lds, const Gemm g, const Sched& S, const Epi& E) {
;     ...
;             PG8_LDB(B0, 0, 0); PG8_LDB(B1, 0, 1); PG8_SCHED; PG8_LDA(At, 0, 0); PG8_STAGE(PG8_SA(1, 1), a1 + hstep, voffA);
;             PG8_WAIT_V(8); PG8_WAIT_L(0); PG8_BAR; PG8_MMA2(0); PG8_BAR; PG8_SCHED;
;             PG8_LDA(At, 0, 1); PG8_STAGE(PG8_SB(0, 0), b2, voffB); PG8_STAGE(PG8_SB(0, 1), b2 + hstep, voffB); PG8_STAGE(PG8_SA(0, 0), a2, voffA);
;             PG8_WAIT_V(8); PG8_WAIT_L(0); PG8_BAR; PG8_MMA2(1); PG8_BAR; PG8_SCHED;
.LBB0_313:
	ds_read_b128 v[136:139], v150
	ds_read_b128 v[140:143], v150 offset:1024
	ds_read_b128 v[154:157], v150 offset:2048
	ds_read_b128 v[158:161], v150 offset:3072
	ds_read_b128 v[162:165], v151
	ds_read_b128 v[166:169], v151 offset:1024
	ds_read_b128 v[170:173], v151 offset:2048
	ds_read_b128 v[174:177], v151 offset:3072
	s_add_u32 s14, s8, 0x100
	s_addc_u32 s15, s9, 0
	s_cmp_eq_u32 s43, 60
	s_cselect_b32 s24, s13, s14
	s_cselect_b32 s25, s11, s15
	s_cselect_b32 s16, s36, s37
	s_cselect_b32 s17, s33, s42
	s_add_u32 s2, s24, 0x80
	s_addc_u32 s3, s25, 0
	s_add_u32 s8, s8, 0x100080
	s_addc_u32 s9, s9, 0
	s_add_i32 m0, s63, 0xc000
	ds_read_b128 v[178:181], v152
	ds_read_b128 v[182:185], v152 offset:1024
	ds_read_b128 v[186:189], v152 offset:2048
	ds_read_b128 v[190:193], v152 offset:3072
	ds_read_b128 v[194:197], v152 offset:4096
	ds_read_b128 v[198:201], v152 offset:5120
	ds_read_b128 v[202:205], v152 offset:6144
	ds_read_b128 v[206:209], v152 offset:7168
	s_nop 0
	global_load_lds_dwordx4 v1, s[8:9]
	s_add_i32 m0, s63, 0xe000
	s_nop 0
	global_load_lds_dwordx4 v145, s[8:9]
	s_waitcnt vmcnt(8)
	s_waitcnt lgkmcnt(0)
	s_setprio 1
	s_waitcnt lgkmcnt(0)
	s_barrier
	v_mfma_f32_16x16x32_bf16 v[126:129], v[136:139], v[178:181], v[126:129]
	v_mfma_f32_16x16x32_bf16 v[122:125], v[154:157], v[178:181], v[122:125]
	v_mfma_f32_16x16x32_bf16 v[110:113], v[136:139], v[186:189], v[110:113]
	v_mfma_f32_16x16x32_bf16 v[106:109], v[154:157], v[186:189], v[106:109]
	v_mfma_f32_16x16x32_bf16 v[94:97], v[136:139], v[194:197], v[94:97]
	v_mfma_f32_16x16x32_bf16 v[90:93], v[154:157], v[194:197], v[90:93]
	v_mfma_f32_16x16x32_bf16 v[78:81], v[136:139], v[202:205], v[78:81]
	v_mfma_f32_16x16x32_bf16 v[74:77], v[154:157], v[202:205], v[74:77]
	v_mfma_f32_16x16x32_bf16 v[118:121], v[162:165], v[178:181], v[118:121]
	v_mfma_f32_16x16x32_bf16 v[114:117], v[170:173], v[178:181], v[114:117]
	v_mfma_f32_16x16x32_bf16 v[102:105], v[162:165], v[186:189], v[102:105]
	v_mfma_f32_16x16x32_bf16 v[98:101], v[170:173], v[186:189], v[98:101]
	v_mfma_f32_16x16x32_bf16 v[86:89], v[162:165], v[194:197], v[86:89]
	v_mfma_f32_16x16x32_bf16 v[82:85], v[170:173], v[194:197], v[82:85]
	v_mfma_f32_16x16x32_bf16 v[70:73], v[162:165], v[202:205], v[70:73]
	v_mfma_f32_16x16x32_bf16 v[66:69], v[170:173], v[202:205], v[66:69]
	v_mfma_f32_16x16x32_bf16 v[126:129], v[140:143], v[182:185], v[126:129]
	v_mfma_f32_16x16x32_bf16 v[122:125], v[158:161], v[182:185], v[122:125]
	v_mfma_f32_16x16x32_bf16 v[110:113], v[140:143], v[190:193], v[110:113]
	v_mfma_f32_16x16x32_bf16 v[106:109], v[158:161], v[190:193], v[106:109]
	v_mfma_f32_16x16x32_bf16 v[94:97], v[140:143], v[198:201], v[94:97]
	v_mfma_f32_16x16x32_bf16 v[90:93], v[158:161], v[198:201], v[90:93]
	v_mfma_f32_16x16x32_bf16 v[78:81], v[140:143], v[206:209], v[78:81]
	v_mfma_f32_16x16x32_bf16 v[74:77], v[158:161], v[206:209], v[74:77]
	v_mfma_f32_16x16x32_bf16 v[118:121], v[166:169], v[182:185], v[118:121]
	v_mfma_f32_16x16x32_bf16 v[114:117], v[174:177], v[182:185], v[114:117]
	v_mfma_f32_16x16x32_bf16 v[102:105], v[166:169], v[190:193], v[102:105]
	v_mfma_f32_16x16x32_bf16 v[98:101], v[174:177], v[190:193], v[98:101]
	v_mfma_f32_16x16x32_bf16 v[86:89], v[166:169], v[198:201], v[86:89]
	v_mfma_f32_16x16x32_bf16 v[82:85], v[174:177], v[198:201], v[82:85]
	v_mfma_f32_16x16x32_bf16 v[70:73], v[166:169], v[206:209], v[70:73]
	v_mfma_f32_16x16x32_bf16 v[66:69], v[174:177], v[206:209], v[66:69]
	s_setprio 0
	s_barrier
	s_add_i32 s44, s95, s61
	s_mov_b64 s[8:9], s[16:17]
	s_mov_b32 m0, s44
	ds_read_b128 v[178:181], v152 offset:16384
	ds_read_b128 v[182:185], v152 offset:17408
	ds_read_b128 v[186:189], v152 offset:18432
	ds_read_b128 v[190:193], v152 offset:19456
	ds_read_b128 v[194:197], v152 offset:20480
	ds_read_b128 v[198:201], v152 offset:21504
	ds_read_b128 v[202:205], v152 offset:22528
	ds_read_b128 v[206:209], v152 offset:23552
	s_nop 0
	global_load_lds_dwordx4 v144, s[8:9]
	s_add_i32 m0, s44, 0x2000
	s_nop 0
	global_load_lds_dwordx4 v146, s[8:9]
	s_add_u32 s8, s16, 0x100000
	s_addc_u32 s9, s17, 0
	s_add_i32 s44, s96, s61
	s_mov_b32 m0, s44
	s_nop 0
	global_load_lds_dwordx4 v144, s[8:9]
	s_add_i32 m0, s44, 0x2000
	s_nop 0
	global_load_lds_dwordx4 v146, s[8:9]
	s_mov_b64 s[8:9], s[24:25]
	s_mov_b32 m0, s63
	s_nop 0
	global_load_lds_dwordx4 v1, s[8:9]
	s_mov_b32 m0, s65
	s_nop 0
	global_load_lds_dwordx4 v145, s[8:9]
	s_waitcnt vmcnt(8)
	s_waitcnt lgkmcnt(0)
	s_setprio 1
	s_waitcnt lgkmcnt(0)
	s_barrier
	v_mfma_f32_16x16x32_bf16 v[62:65], v[136:139], v[178:181], v[62:65]
	v_mfma_f32_16x16x32_bf16 v[58:61], v[154:157], v[178:181], v[58:61]
	v_mfma_f32_16x16x32_bf16 v[46:49], v[136:139], v[186:189], v[46:49]
	v_mfma_f32_16x16x32_bf16 v[42:45], v[154:157], v[186:189], v[42:45]
	v_mfma_f32_16x16x32_bf16 v[30:33], v[136:139], v[194:197], v[30:33]
	v_mfma_f32_16x16x32_bf16 v[26:29], v[154:157], v[194:197], v[26:29]
	v_mfma_f32_16x16x32_bf16 v[14:17], v[136:139], v[202:205], v[14:17]
	v_mfma_f32_16x16x32_bf16 v[10:13], v[154:157], v[202:205], v[10:13]
	v_mfma_f32_16x16x32_bf16 v[54:57], v[162:165], v[178:181], v[54:57]
	v_mfma_f32_16x16x32_bf16 v[50:53], v[170:173], v[178:181], v[50:53]
	v_mfma_f32_16x16x32_bf16 v[38:41], v[162:165], v[186:189], v[38:41]
	v_mfma_f32_16x16x32_bf16 v[34:37], v[170:173], v[186:189], v[34:37]
	v_mfma_f32_16x16x32_bf16 v[22:25], v[162:165], v[194:197], v[22:25]
	v_mfma_f32_16x16x32_bf16 v[18:21], v[170:173], v[194:197], v[18:21]
	v_mfma_f32_16x16x32_bf16 v[6:9], v[162:165], v[202:205], v[6:9]
	v_mfma_f32_16x16x32_bf16 v[2:5], v[170:173], v[202:205], v[2:5]
	v_mfma_f32_16x16x32_bf16 v[62:65], v[140:143], v[182:185], v[62:65]
	v_mfma_f32_16x16x32_bf16 v[58:61], v[158:161], v[182:185], v[58:61]
	v_mfma_f32_16x16x32_bf16 v[46:49], v[140:143], v[190:193], v[46:49]
	v_mfma_f32_16x16x32_bf16 v[42:45], v[158:161], v[190:193], v[42:45]
	v_mfma_f32_16x16x32_bf16 v[30:33], v[140:143], v[198:201], v[30:33]
	v_mfma_f32_16x16x32_bf16 v[26:29], v[158:161], v[198:201], v[26:29]
	v_mfma_f32_16x16x32_bf16 v[14:17], v[140:143], v[206:209], v[14:17]
	v_mfma_f32_16x16x32_bf16 v[10:13], v[158:161], v[206:209], v[10:13]
	v_mfma_f32_16x16x32_bf16 v[54:57], v[166:169], v[182:185], v[54:57]
	v_mfma_f32_16x16x32_bf16 v[50:53], v[174:177], v[182:185], v[50:53]
	v_mfma_f32_16x16x32_bf16 v[38:41], v[166:169], v[190:193], v[38:41]
	v_mfma_f32_16x16x32_bf16 v[34:37], v[174:177], v[190:193], v[34:37]
	v_mfma_f32_16x16x32_bf16 v[22:25], v[166:169], v[198:201], v[22:25]
	v_mfma_f32_16x16x32_bf16 v[18:21], v[174:177], v[198:201], v[18:21]
	v_mfma_f32_16x16x32_bf16 v[6:9], v[166:169], v[206:209], v[6:9]
	v_mfma_f32_16x16x32_bf16 v[2:5], v[174:177], v[206:209], v[2:5]
	s_setprio 0
	s_barrier
; #define PG8_STAGE(bufoff, gbase, voff) do { const char* _gb = (const char*)(gbase); asm volatile("" : "+s"(_gb)); _Pragma("unroll") for (int _i = 0; _i < 2; ++_i) { asm volatile("" : "+v"((voff)[_i])); \
;         __builtin_amdgcn_global_load_lds((const unsigned*)(_gb + (voff)[_i]), (PG8_LAS unsigned*)(lds + (bufoff) + ldsw + _i * 8192), 16, 0, 0); } } while (0)
; #define PG8_LDA(dst, b, h) do { _Pragma("unroll") for (int m = 0; m < 4; ++m) _Pragma("unroll") for (int k = 0; k < 2; ++k) dst[m][k] = *(const PG8_LAS bf16x8*)(lds + PG8_SA(b, h) + aoff + m * 2048 + k * 1024); } while (0)
; #define PG8_LDB(dst, b, h) do { _Pragma("unroll") for (int n = 0; n < 2; ++n) _Pragma("unroll") for (int k = 0; k < 2; ++k) dst[n][k] = *(const PG8_LAS bf16x8*)(lds + PG8_SB(b, h) + boff + n * 2048 + k * 1024); } while (0)
; #define PG8_WAIT_V(n) asm volatile("s_waitcnt vmcnt(" #n ")" ::: "memory")
; #define PG8_WAIT_L(n) asm volatile("s_waitcnt lgkmcnt(" #n ")" ::: "memory")
; #define PG8_BAR __builtin_amdgcn_s_barrier()
; #define PG8_SCHED __builtin_amdgcn_sched_barrier(0)
; #define PG8_STAGE(bufoff, gbase, voff) do { const char* _gb = (const char*)(gbase); asm volatile("" : "+s"(_gb)); _Pragma("unroll") for (int _i = 0; _i < 2; ++_i) { asm volatile("" : "+v"((voff)[_i])); \
;         __builtin_amdgcn_global_load_lds((const unsigned*)(_gb + (voff)[_i]), (PG8_LAS unsigned*)(lds + (bufoff) + ldsw + _i * 8192), 16, 0, 0); } } while (0)
; #define PG8_LDA(dst, b, h) do { _Pragma("unroll") for (int m = 0; m < 4; ++m) _Pragma("unroll") for (int k = 0; k < 2; ++k) dst[m][k] = *(const PG8_LAS bf16x8*)(lds + PG8_SA(b, h) + aoff + m * 2048 + k * 1024); } while (0)
; #define PG8_WAIT_V(n) asm volatile("s_waitcnt vmcnt(" #n ")" ::: "memory")
; template <class Epi, class Sched, bool ALIGN_EPI = false, bool SP2 = false>
; __device__ __forceinline__ void gemm_phase(PG8_LAS unsigned char* lds, const Gemm g, const Sched& S, const Epi& E) {
;     ...
;             PG8_LDB(B0, 1, 0); PG8_LDB(B1, 1, 1); PG8_SCHED; PG8_LDA(At, 1, 0); PG8_STAGE(PG8_SA(0, 1), a2 + hstep, voffA);
;             PG8_WAIT_V(8); PG8_WAIT_L(0); PG8_BAR; PG8_MMA2(0); PG8_BAR; PG8_SCHED;
;             PG8_LDA(At, 1, 1); PG8_STAGE(PG8_SB(1, 0), b3, voffB); PG8_STAGE(PG8_SB(1, 1), b3 + hstep, voffB); PG8_STAGE(PG8_SA(1, 0), a3, voffA);
;             PG8_WAIT_V(8); PG8_WAIT_L(0); PG8_BAR; PG8_MMA2(1); PG8_BAR; PG8_SCHED;
	s_add_i32 s44, 0, 0x18000
	v_add_u32_e32 v135, s44, v148
	s_add_i32 s45, 0, 0x1c000
	ds_read_b128 v[136:139], v135
	ds_read_b128 v[140:143], v135 offset:1024
	ds_read_b128 v[154:157], v135 offset:2048
	ds_read_b128 v[158:161], v135 offset:3072
	v_add_u32_e32 v135, s45, v148
	ds_read_b128 v[162:165], v135
	ds_read_b128 v[166:169], v135 offset:1024
	ds_read_b128 v[170:173], v135 offset:2048
	ds_read_b128 v[174:177], v135 offset:3072
	s_add_u32 s8, s24, 0x100000
	s_addc_u32 s9, s25, 0
	s_mov_b32 m0, s88
	ds_read_b128 v[178:181], v152 offset:32768
	ds_read_b128 v[182:185], v152 offset:33792
	ds_read_b128 v[186:189], v152 offset:34816
	ds_read_b128 v[190:193], v152 offset:35840
	ds_read_b128 v[194:197], v152 offset:36864
	ds_read_b128 v[198:201], v152 offset:37888
	ds_read_b128 v[202:205], v152 offset:38912
	ds_read_b128 v[206:209], v152 offset:39936
	s_nop 0
	global_load_lds_dwordx4 v1, s[8:9]
	s_mov_b32 m0, s89
	s_nop 0
	global_load_lds_dwordx4 v145, s[8:9]
	s_waitcnt vmcnt(8)
	s_waitcnt lgkmcnt(0)
	s_setprio 1
	s_waitcnt lgkmcnt(0)
	s_barrier
	v_mfma_f32_16x16x32_bf16 v[126:129], v[136:139], v[178:181], v[126:129]
	v_mfma_f32_16x16x32_bf16 v[122:125], v[154:157], v[178:181], v[122:125]
	v_mfma_f32_16x16x32_bf16 v[110:113], v[136:139], v[186:189], v[110:113]
	v_mfma_f32_16x16x32_bf16 v[106:109], v[154:157], v[186:189], v[106:109]
	v_mfma_f32_16x16x32_bf16 v[94:97], v[136:139], v[194:197], v[94:97]
	v_mfma_f32_16x16x32_bf16 v[90:93], v[154:157], v[194:197], v[90:93]
	v_mfma_f32_16x16x32_bf16 v[78:81], v[136:139], v[202:205], v[78:81]
	v_mfma_f32_16x16x32_bf16 v[74:77], v[154:157], v[202:205], v[74:77]
	v_mfma_f32_16x16x32_bf16 v[118:121], v[162:165], v[178:181], v[118:121]
	v_mfma_f32_16x16x32_bf16 v[114:117], v[170:173], v[178:181], v[114:117]
	v_mfma_f32_16x16x32_bf16 v[102:105], v[162:165], v[186:189], v[102:105]
	v_mfma_f32_16x16x32_bf16 v[98:101], v[170:173], v[186:189], v[98:101]
	v_mfma_f32_16x16x32_bf16 v[86:89], v[162:165], v[194:197], v[86:89]
	v_mfma_f32_16x16x32_bf16 v[82:85], v[170:173], v[194:197], v[82:85]
	v_mfma_f32_16x16x32_bf16 v[70:73], v[162:165], v[202:205], v[70:73]
	v_mfma_f32_16x16x32_bf16 v[66:69], v[170:173], v[202:205], v[66:69]
	v_mfma_f32_16x16x32_bf16 v[126:129], v[140:143], v[182:185], v[126:129]
	v_mfma_f32_16x16x32_bf16 v[122:125], v[158:161], v[182:185], v[122:125]
	v_mfma_f32_16x16x32_bf16 v[110:113], v[140:143], v[190:193], v[110:113]
	v_mfma_f32_16x16x32_bf16 v[106:109], v[158:161], v[190:193], v[106:109]
	v_mfma_f32_16x16x32_bf16 v[94:97], v[140:143], v[198:201], v[94:97]
	v_mfma_f32_16x16x32_bf16 v[90:93], v[158:161], v[198:201], v[90:93]
	v_mfma_f32_16x16x32_bf16 v[78:81], v[140:143], v[206:209], v[78:81]
	v_mfma_f32_16x16x32_bf16 v[74:77], v[158:161], v[206:209], v[74:77]
	v_mfma_f32_16x16x32_bf16 v[118:121], v[166:169], v[182:185], v[118:121]
	v_mfma_f32_16x16x32_bf16 v[114:117], v[174:177], v[182:185], v[114:117]
	v_mfma_f32_16x16x32_bf16 v[102:105], v[166:169], v[190:193], v[102:105]
	v_mfma_f32_16x16x32_bf16 v[98:101], v[174:177], v[190:193], v[98:101]
	v_mfma_f32_16x16x32_bf16 v[86:89], v[166:169], v[198:201], v[86:89]
	v_mfma_f32_16x16x32_bf16 v[82:85], v[174:177], v[198:201], v[82:85]
	v_mfma_f32_16x16x32_bf16 v[70:73], v[166:169], v[206:209], v[70:73]
	v_mfma_f32_16x16x32_bf16 v[66:69], v[174:177], v[206:209], v[66:69]
	s_setprio 0
	s_barrier
	s_nop 0
	s_add_u32 s8, s16, 0x80
	s_addc_u32 s9, s17, 0
	s_add_i32 s24, s44, s61
	s_mov_b32 m0, s24
	ds_read_b128 v[178:181], v152 offset:49152
	ds_read_b128 v[182:185], v152 offset:50176
	ds_read_b128 v[186:189], v152 offset:51200
	ds_read_b128 v[190:193], v152 offset:52224
	ds_read_b128 v[194:197], v152 offset:53248
	ds_read_b128 v[198:201], v152 offset:54272
	ds_read_b128 v[202:205], v152 offset:55296
	ds_read_b128 v[206:209], v152 offset:56320
	s_nop 0
	global_load_lds_dwordx4 v144, s[8:9]
	s_add_i32 m0, s24, 0x2000
	s_nop 0
	global_load_lds_dwordx4 v146, s[8:9]
	s_add_u32 s8, s16, 0x100080
	s_addc_u32 s9, s17, 0
	s_add_i32 s16, s45, s61
	s_mov_b32 m0, s16
	s_nop 0
	global_load_lds_dwordx4 v144, s[8:9]
	s_add_i32 m0, s16, 0x2000
	s_nop 0
	global_load_lds_dwordx4 v146, s[8:9]
	s_mov_b32 m0, s91
	s_nop 0
	global_load_lds_dwordx4 v1, s[2:3]
	s_mov_b32 m0, s92
	s_nop 0
	global_load_lds_dwordx4 v145, s[2:3]
	s_waitcnt vmcnt(8)
	s_waitcnt lgkmcnt(0)
	s_setprio 1
	s_waitcnt lgkmcnt(0)
	s_barrier
	v_mfma_f32_16x16x32_bf16 v[62:65], v[136:139], v[178:181], v[62:65]
	v_mfma_f32_16x16x32_bf16 v[58:61], v[154:157], v[178:181], v[58:61]
	v_mfma_f32_16x16x32_bf16 v[46:49], v[136:139], v[186:189], v[46:49]
	v_mfma_f32_16x16x32_bf16 v[42:45], v[154:157], v[186:189], v[42:45]
	v_mfma_f32_16x16x32_bf16 v[30:33], v[136:139], v[194:197], v[30:33]
	v_mfma_f32_16x16x32_bf16 v[26:29], v[154:157], v[194:197], v[26:29]
	v_mfma_f32_16x16x32_bf16 v[14:17], v[136:139], v[202:205], v[14:17]
	v_mfma_f32_16x16x32_bf16 v[10:13], v[154:157], v[202:205], v[10:13]
	v_mfma_f32_16x16x32_bf16 v[54:57], v[162:165], v[178:181], v[54:57]
	v_mfma_f32_16x16x32_bf16 v[50:53], v[170:173], v[178:181], v[50:53]
	v_mfma_f32_16x16x32_bf16 v[38:41], v[162:165], v[186:189], v[38:41]
	v_mfma_f32_16x16x32_bf16 v[34:37], v[170:173], v[186:189], v[34:37]
	v_mfma_f32_16x16x32_bf16 v[22:25], v[162:165], v[194:197], v[22:25]
	v_mfma_f32_16x16x32_bf16 v[18:21], v[170:173], v[194:197], v[18:21]
	v_mfma_f32_16x16x32_bf16 v[6:9], v[162:165], v[202:205], v[6:9]
	v_mfma_f32_16x16x32_bf16 v[2:5], v[170:173], v[202:205], v[2:5]
	v_mfma_f32_16x16x32_bf16 v[62:65], v[140:143], v[182:185], v[62:65]
	v_mfma_f32_16x16x32_bf16 v[58:61], v[158:161], v[182:185], v[58:61]
	v_mfma_f32_16x16x32_bf16 v[46:49], v[140:143], v[190:193], v[46:49]
	v_mfma_f32_16x16x32_bf16 v[42:45], v[158:161], v[190:193], v[42:45]
	v_mfma_f32_16x16x32_bf16 v[30:33], v[140:143], v[198:201], v[30:33]
	v_mfma_f32_16x16x32_bf16 v[26:29], v[158:161], v[198:201], v[26:29]
	v_mfma_f32_16x16x32_bf16 v[14:17], v[140:143], v[206:209], v[14:17]
	v_mfma_f32_16x16x32_bf16 v[10:13], v[158:161], v[206:209], v[10:13]
	v_mfma_f32_16x16x32_bf16 v[54:57], v[166:169], v[182:185], v[54:57]
	v_mfma_f32_16x16x32_bf16 v[50:53], v[174:177], v[182:185], v[50:53]
	v_mfma_f32_16x16x32_bf16 v[38:41], v[166:169], v[190:193], v[38:41]
	v_mfma_f32_16x16x32_bf16 v[34:37], v[174:177], v[190:193], v[34:37]
	v_mfma_f32_16x16x32_bf16 v[22:25], v[166:169], v[198:201], v[22:25]
	v_mfma_f32_16x16x32_bf16 v[18:21], v[174:177], v[198:201], v[18:21]
	v_mfma_f32_16x16x32_bf16 v[6:9], v[166:169], v[206:209], v[6:9]
	v_mfma_f32_16x16x32_bf16 v[2:5], v[174:177], v[206:209], v[2:5]
	s_setprio 0
	s_barrier
	s_add_i32 s43, s43, 2
	s_add_u32 s37, s37, 0x100
	s_addc_u32 s42, s42, 0
	s_cmp_gt_u32 s43, 61
	s_mov_b64 s[8:9], s[14:15]
	s_cbranch_scc0 .LBB0_313
	s_and_b64 vcc, exec, s[58:59]
	s_cbranch_vccz .LBB0_333
	s_barrier
	s_cmp_lt_i32 s12, 24
	s_cbranch_scc0 .LBB0_334

; template <class Epi, class Sched>
; __device__ __forceinline__ void gemm_phase_dual(PG8_LAS unsigned char* lds, const Gemm g  , const bf16_t* A0, const bf16_t* Bt0, int K0, const Sched& S, const Epi& E) {
;     ...
; #pragma unroll
;         for (int a = 0; a < 2; ++a)
; #pragma unroll
;             for (int b = 0; b < 2; ++b)
; #pragma unroll
;                 for (int m = 0; m < 4; ++m)
; #pragma unroll
;                     for (int n = 0; n < 2; ++n) acc[a][b][m][n] = (f32x4){0.f, 0.f, 0.f, 0.f};
;         cur = nxt; cA = nA; cB = nB; ++ui;
.LBB0_745:
	s_ashr_i32 s5, s4, 31
	s_lshl_b64 s[0:1], s[4:5], 21
	s_add_u32 s30, s51, s0
	s_addc_u32 s31, s52, s1
	s_ashr_i32 s21, s20, 31
	s_lshl_b64 s[34:35], s[20:21], 21
	s_add_u32 s78, s53, s34
	s_addc_u32 s79, s54, s35
	s_add_u32 s0, s29, s38
	s_addc_u32 s1, s42, s39
	s_add_u32 s5, s68, s40
	v_mov_b32_e32 v2, 0
	s_addc_u32 s21, s69, s41
	s_mov_b32 s33, -2
	v_mov_b32_e32 v3, v2
	v_mov_b32_e32 v4, v2
	v_mov_b32_e32 v5, v2
	v_mov_b32_e32 v6, v2
	v_mov_b32_e32 v7, v2
	v_mov_b32_e32 v8, v2
	v_mov_b32_e32 v9, v2
	v_mov_b32_e32 v14, v2
	v_mov_b32_e32 v15, v2
	v_mov_b32_e32 v16, v2
	v_mov_b32_e32 v17, v2
	v_mov_b32_e32 v22, v2
	v_mov_b32_e32 v23, v2
	v_mov_b32_e32 v24, v2
	v_mov_b32_e32 v25, v2
	v_mov_b32_e32 v54, v2
	v_mov_b32_e32 v55, v2
	v_mov_b32_e32 v56, v2
	v_mov_b32_e32 v57, v2
	v_mov_b32_e32 v66, v2
	v_mov_b32_e32 v67, v2
	v_mov_b32_e32 v68, v2
	v_mov_b32_e32 v69, v2
	v_mov_b32_e32 v86, v2
	v_mov_b32_e32 v87, v2
	v_mov_b32_e32 v88, v2
	v_mov_b32_e32 v89, v2
	v_mov_b32_e32 v94, v2
	v_mov_b32_e32 v95, v2
	v_mov_b32_e32 v96, v2
	v_mov_b32_e32 v97, v2
	v_mov_b32_e32 v10, v2
	v_mov_b32_e32 v11, v2
	v_mov_b32_e32 v12, v2
	v_mov_b32_e32 v13, v2
	v_mov_b32_e32 v18, v2
	v_mov_b32_e32 v19, v2
	v_mov_b32_e32 v20, v2
	v_mov_b32_e32 v21, v2
	v_mov_b32_e32 v38, v2
	v_mov_b32_e32 v39, v2
	v_mov_b32_e32 v40, v2
	v_mov_b32_e32 v41, v2
	v_mov_b32_e32 v42, v2
	v_mov_b32_e32 v43, v2
	v_mov_b32_e32 v44, v2
	v_mov_b32_e32 v45, v2
	v_mov_b32_e32 v70, v2
	v_mov_b32_e32 v71, v2
	v_mov_b32_e32 v72, v2
	v_mov_b32_e32 v73, v2
	v_mov_b32_e32 v74, v2
	v_mov_b32_e32 v75, v2
	v_mov_b32_e32 v76, v2
	v_mov_b32_e32 v77, v2
	v_mov_b32_e32 v98, v2
	v_mov_b32_e32 v99, v2
	v_mov_b32_e32 v100, v2
	v_mov_b32_e32 v101, v2
	v_mov_b32_e32 v102, v2
	v_mov_b32_e32 v103, v2
	v_mov_b32_e32 v104, v2
	v_mov_b32_e32 v105, v2
	v_mov_b32_e32 v126, v2
	v_mov_b32_e32 v127, v2
	v_mov_b32_e32 v128, v2
	v_mov_b32_e32 v129, v2
	v_mov_b32_e32 v122, v2
	v_mov_b32_e32 v123, v2
	v_mov_b32_e32 v124, v2
	v_mov_b32_e32 v125, v2
	v_mov_b32_e32 v106, v2
	v_mov_b32_e32 v107, v2
	v_mov_b32_e32 v108, v2
	v_mov_b32_e32 v109, v2
	v_mov_b32_e32 v110, v2
	v_mov_b32_e32 v111, v2
	v_mov_b32_e32 v112, v2
	v_mov_b32_e32 v113, v2
	v_mov_b32_e32 v82, v2
	v_mov_b32_e32 v83, v2
	v_mov_b32_e32 v84, v2
	v_mov_b32_e32 v85, v2
	v_mov_b32_e32 v58, v2
	v_mov_b32_e32 v59, v2
	v_mov_b32_e32 v60, v2
	v_mov_b32_e32 v61, v2
	v_mov_b32_e32 v50, v2
	v_mov_b32_e32 v51, v2
	v_mov_b32_e32 v52, v2
	v_mov_b32_e32 v53, v2
	v_mov_b32_e32 v26, v2
	v_mov_b32_e32 v27, v2
	v_mov_b32_e32 v28, v2
	v_mov_b32_e32 v29, v2
	v_mov_b32_e32 v114, v2
	v_mov_b32_e32 v115, v2
	v_mov_b32_e32 v116, v2
	v_mov_b32_e32 v117, v2
	v_mov_b32_e32 v130, v2
	v_mov_b32_e32 v131, v2
	v_mov_b32_e32 v132, v2
	v_mov_b32_e32 v133, v2
	v_mov_b32_e32 v90, v2
	v_mov_b32_e32 v91, v2
	v_mov_b32_e32 v92, v2
	v_mov_b32_e32 v93, v2
	v_mov_b32_e32 v78, v2
	v_mov_b32_e32 v79, v2
	v_mov_b32_e32 v80, v2
	v_mov_b32_e32 v81, v2
	v_mov_b32_e32 v62, v2
	v_mov_b32_e32 v63, v2
	v_mov_b32_e32 v64, v2
	v_mov_b32_e32 v65, v2
	v_mov_b32_e32 v46, v2
	v_mov_b32_e32 v47, v2
	v_mov_b32_e32 v48, v2
	v_mov_b32_e32 v49, v2
	v_mov_b32_e32 v30, v2
	v_mov_b32_e32 v31, v2
	v_mov_b32_e32 v32, v2
	v_mov_b32_e32 v33, v2
	v_mov_b32_e32 v34, v2
	v_mov_b32_e32 v35, v2
	v_mov_b32_e32 v36, v2
	v_mov_b32_e32 v37, v2
	s_nop 0
.LBB0_746:
	ds_read_b128 v[118:121], v172
	ds_read_b128 v[134:137], v172 offset:1024
	ds_read_b128 v[138:141], v172 offset:2048
	ds_read_b128 v[142:145], v172 offset:3072
	ds_read_b128 v[146:149], v173
	ds_read_b128 v[150:153], v173 offset:1024
	ds_read_b128 v[154:157], v173 offset:2048
	ds_read_b128 v[176:179], v173 offset:3072
	s_add_u32 s16, s0, 0x100
	s_addc_u32 s17, s1, 0
	s_cmp_eq_u32 s33, 28
	s_cselect_b32 s26, s30, s16
	s_cselect_b32 s27, s31, s17
	s_cselect_b32 s24, s78, s5
	s_cselect_b32 s25, s79, s21
	s_add_u32 s2, s26, 0x80
	s_addc_u32 s3, s27, 0
	s_add_u32 s0, s0, 0x100080
	s_addc_u32 s1, s1, 0
	s_add_i32 s76, s46, 0xc000
	s_mov_b32 m0, s76
	s_add_i32 s77, s46, 0xe000
	ds_read_b128 v[180:183], v174
	ds_read_b128 v[184:187], v174 offset:1024
	ds_read_b128 v[188:191], v174 offset:2048
	ds_read_b128 v[192:195], v174 offset:3072
	ds_read_b128 v[196:199], v174 offset:4096
	ds_read_b128 v[200:203], v174 offset:5120
	ds_read_b128 v[204:207], v174 offset:6144
	ds_read_b128 v[208:211], v174 offset:7168
	s_nop 0
	global_load_lds_dwordx4 v1, s[0:1]
	s_mov_b32 m0, s77
	s_nop 0
	global_load_lds_dwordx4 v165, s[0:1]
	s_waitcnt vmcnt(8)
	s_waitcnt lgkmcnt(0)
	s_setprio 1
	s_waitcnt lgkmcnt(0)
	s_barrier
	v_mfma_f32_16x16x32_bf16 v[34:37], v[118:121], v[180:183], v[34:37]
	v_mfma_f32_16x16x32_bf16 v[30:33], v[138:141], v[180:183], v[30:33]
	v_mfma_f32_16x16x32_bf16 v[46:49], v[118:121], v[188:191], v[46:49]
	v_mfma_f32_16x16x32_bf16 v[62:65], v[138:141], v[188:191], v[62:65]
	v_mfma_f32_16x16x32_bf16 v[78:81], v[118:121], v[196:199], v[78:81]
	v_mfma_f32_16x16x32_bf16 v[90:93], v[138:141], v[196:199], v[90:93]
	v_mfma_f32_16x16x32_bf16 v[130:133], v[118:121], v[204:207], v[130:133]
	v_mfma_f32_16x16x32_bf16 v[114:117], v[138:141], v[204:207], v[114:117]
	v_mfma_f32_16x16x32_bf16 v[26:29], v[146:149], v[180:183], v[26:29]
	v_mfma_f32_16x16x32_bf16 v[50:53], v[154:157], v[180:183], v[50:53]
	v_mfma_f32_16x16x32_bf16 v[58:61], v[146:149], v[188:191], v[58:61]
	v_mfma_f32_16x16x32_bf16 v[82:85], v[154:157], v[188:191], v[82:85]
	v_mfma_f32_16x16x32_bf16 v[110:113], v[146:149], v[196:199], v[110:113]
	v_mfma_f32_16x16x32_bf16 v[106:109], v[154:157], v[196:199], v[106:109]
	v_mfma_f32_16x16x32_bf16 v[122:125], v[146:149], v[204:207], v[122:125]
	v_mfma_f32_16x16x32_bf16 v[126:129], v[154:157], v[204:207], v[126:129]
	v_mfma_f32_16x16x32_bf16 v[34:37], v[134:137], v[184:187], v[34:37]
	v_mfma_f32_16x16x32_bf16 v[30:33], v[142:145], v[184:187], v[30:33]
	v_mfma_f32_16x16x32_bf16 v[46:49], v[134:137], v[192:195], v[46:49]
	v_mfma_f32_16x16x32_bf16 v[62:65], v[142:145], v[192:195], v[62:65]
	v_mfma_f32_16x16x32_bf16 v[78:81], v[134:137], v[200:203], v[78:81]
	v_mfma_f32_16x16x32_bf16 v[90:93], v[142:145], v[200:203], v[90:93]
	v_mfma_f32_16x16x32_bf16 v[130:133], v[134:137], v[208:211], v[130:133]
	v_mfma_f32_16x16x32_bf16 v[114:117], v[142:145], v[208:211], v[114:117]
	v_mfma_f32_16x16x32_bf16 v[26:29], v[150:153], v[184:187], v[26:29]
	v_mfma_f32_16x16x32_bf16 v[50:53], v[176:179], v[184:187], v[50:53]
	v_mfma_f32_16x16x32_bf16 v[58:61], v[150:153], v[192:195], v[58:61]
	v_mfma_f32_16x16x32_bf16 v[82:85], v[176:179], v[192:195], v[82:85]
	v_mfma_f32_16x16x32_bf16 v[110:113], v[150:153], v[200:203], v[110:113]
	v_mfma_f32_16x16x32_bf16 v[106:109], v[176:179], v[200:203], v[106:109]
	v_mfma_f32_16x16x32_bf16 v[122:125], v[150:153], v[208:211], v[122:125]
	v_mfma_f32_16x16x32_bf16 v[126:129], v[176:179], v[208:211], v[126:129]
	s_setprio 0
	s_barrier
	s_add_i32 s80, s72, s45
	s_mov_b64 s[0:1], s[24:25]
	s_mov_b32 m0, s80
	s_add_i32 s81, s80, 0x2000
	ds_read_b128 v[180:183], v174 offset:16384
	ds_read_b128 v[184:187], v174 offset:17408
	ds_read_b128 v[188:191], v174 offset:18432
	ds_read_b128 v[192:195], v174 offset:19456
	ds_read_b128 v[196:199], v174 offset:20480
	ds_read_b128 v[200:203], v174 offset:21504
	ds_read_b128 v[204:207], v174 offset:22528
	ds_read_b128 v[208:211], v174 offset:23552
	s_nop 0
	global_load_lds_dwordx4 v164, s[0:1]
	s_mov_b32 m0, s81
	s_nop 0
	global_load_lds_dwordx4 v166, s[0:1]
	s_add_u32 s0, s24, 0x100000
	s_addc_u32 s1, s25, 0
	s_add_i32 s82, s73, s45
	s_mov_b32 m0, s82
	s_add_i32 s83, s82, 0x2000
	s_nop 0
	global_load_lds_dwordx4 v164, s[0:1]
	s_mov_b32 m0, s83
	s_nop 0
	global_load_lds_dwordx4 v166, s[0:1]
	s_mov_b64 s[0:1], s[26:27]
	s_mov_b32 m0, s46
	s_nop 0
	global_load_lds_dwordx4 v1, s[0:1]
	s_mov_b32 m0, s47
	s_nop 0
	global_load_lds_dwordx4 v165, s[0:1]
	s_waitcnt vmcnt(8)
	s_waitcnt lgkmcnt(0)
	s_setprio 1
	s_waitcnt lgkmcnt(0)
	s_barrier
	v_mfma_f32_16x16x32_bf16 v[102:105], v[118:121], v[180:183], v[102:105]
	v_mfma_f32_16x16x32_bf16 v[98:101], v[138:141], v[180:183], v[98:101]
	v_mfma_f32_16x16x32_bf16 v[74:77], v[118:121], v[188:191], v[74:77]
	v_mfma_f32_16x16x32_bf16 v[70:73], v[138:141], v[188:191], v[70:73]
	v_mfma_f32_16x16x32_bf16 v[42:45], v[118:121], v[196:199], v[42:45]
	v_mfma_f32_16x16x32_bf16 v[38:41], v[138:141], v[196:199], v[38:41]
	v_mfma_f32_16x16x32_bf16 v[18:21], v[118:121], v[204:207], v[18:21]
	v_mfma_f32_16x16x32_bf16 v[10:13], v[138:141], v[204:207], v[10:13]
	v_mfma_f32_16x16x32_bf16 v[94:97], v[146:149], v[180:183], v[94:97]
	v_mfma_f32_16x16x32_bf16 v[86:89], v[154:157], v[180:183], v[86:89]
	v_mfma_f32_16x16x32_bf16 v[66:69], v[146:149], v[188:191], v[66:69]
	v_mfma_f32_16x16x32_bf16 v[54:57], v[154:157], v[188:191], v[54:57]
	v_mfma_f32_16x16x32_bf16 v[22:25], v[146:149], v[196:199], v[22:25]
	v_mfma_f32_16x16x32_bf16 v[14:17], v[154:157], v[196:199], v[14:17]
	v_mfma_f32_16x16x32_bf16 v[6:9], v[146:149], v[204:207], v[6:9]
	v_mfma_f32_16x16x32_bf16 v[2:5], v[154:157], v[204:207], v[2:5]
	v_mfma_f32_16x16x32_bf16 v[102:105], v[134:137], v[184:187], v[102:105]
	v_mfma_f32_16x16x32_bf16 v[98:101], v[142:145], v[184:187], v[98:101]
	v_mfma_f32_16x16x32_bf16 v[74:77], v[134:137], v[192:195], v[74:77]
	v_mfma_f32_16x16x32_bf16 v[70:73], v[142:145], v[192:195], v[70:73]
	v_mfma_f32_16x16x32_bf16 v[42:45], v[134:137], v[200:203], v[42:45]
	v_mfma_f32_16x16x32_bf16 v[38:41], v[142:145], v[200:203], v[38:41]
	v_mfma_f32_16x16x32_bf16 v[18:21], v[134:137], v[208:211], v[18:21]
	v_mfma_f32_16x16x32_bf16 v[10:13], v[142:145], v[208:211], v[10:13]
	v_mfma_f32_16x16x32_bf16 v[94:97], v[150:153], v[184:187], v[94:97]
	v_mfma_f32_16x16x32_bf16 v[86:89], v[176:179], v[184:187], v[86:89]
	v_mfma_f32_16x16x32_bf16 v[66:69], v[150:153], v[192:195], v[66:69]
	v_mfma_f32_16x16x32_bf16 v[54:57], v[176:179], v[192:195], v[54:57]
	v_mfma_f32_16x16x32_bf16 v[22:25], v[150:153], v[200:203], v[22:25]
	v_mfma_f32_16x16x32_bf16 v[14:17], v[176:179], v[200:203], v[14:17]
	v_mfma_f32_16x16x32_bf16 v[6:9], v[150:153], v[208:211], v[6:9]
	v_mfma_f32_16x16x32_bf16 v[2:5], v[176:179], v[208:211], v[2:5]
	s_setprio 0
	s_barrier
	s_add_i32 s84, 0, 0x18000
	s_add_i32 s86, 0, 0x1c000
	v_add_u32_e32 v175, s84, v170
	v_add_u32_e32 v176, s86, v170
	ds_read_b128 v[118:121], v175
	ds_read_b128 v[134:137], v175 offset:1024
	ds_read_b128 v[138:141], v175 offset:2048
	ds_read_b128 v[142:145], v175 offset:3072
	ds_read_b128 v[146:149], v176
	ds_read_b128 v[150:153], v176 offset:1024
	ds_read_b128 v[154:157], v176 offset:2048
	ds_read_b128 v[178:181], v176 offset:3072
	s_add_u32 s0, s26, 0x100000
	s_addc_u32 s1, s27, 0
	s_mov_b32 m0, s48
	ds_read_b128 v[182:185], v174 offset:32768
	ds_read_b128 v[186:189], v174 offset:33792
	ds_read_b128 v[190:193], v174 offset:34816
	ds_read_b128 v[194:197], v174 offset:35840
	ds_read_b128 v[198:201], v174 offset:36864
	ds_read_b128 v[202:205], v174 offset:37888
	ds_read_b128 v[206:209], v174 offset:38912
	ds_read_b128 v[210:213], v174 offset:39936
	s_nop 0
	global_load_lds_dwordx4 v1, s[0:1]
	s_mov_b32 m0, s49
	s_nop 0
	global_load_lds_dwordx4 v165, s[0:1]
	s_waitcnt vmcnt(8)
	s_waitcnt lgkmcnt(0)
	s_setprio 1
	s_waitcnt lgkmcnt(0)
	s_barrier
	v_mfma_f32_16x16x32_bf16 v[34:37], v[118:121], v[182:185], v[34:37]
	v_mfma_f32_16x16x32_bf16 v[30:33], v[138:141], v[182:185], v[30:33]
	v_mfma_f32_16x16x32_bf16 v[46:49], v[118:121], v[190:193], v[46:49]
	v_mfma_f32_16x16x32_bf16 v[62:65], v[138:141], v[190:193], v[62:65]
	v_mfma_f32_16x16x32_bf16 v[78:81], v[118:121], v[198:201], v[78:81]
	v_mfma_f32_16x16x32_bf16 v[90:93], v[138:141], v[198:201], v[90:93]
	v_mfma_f32_16x16x32_bf16 v[130:133], v[118:121], v[206:209], v[130:133]
	v_mfma_f32_16x16x32_bf16 v[114:117], v[138:141], v[206:209], v[114:117]
	v_mfma_f32_16x16x32_bf16 v[26:29], v[146:149], v[182:185], v[26:29]
	v_mfma_f32_16x16x32_bf16 v[50:53], v[154:157], v[182:185], v[50:53]
	v_mfma_f32_16x16x32_bf16 v[58:61], v[146:149], v[190:193], v[58:61]
	v_mfma_f32_16x16x32_bf16 v[82:85], v[154:157], v[190:193], v[82:85]
	v_mfma_f32_16x16x32_bf16 v[110:113], v[146:149], v[198:201], v[110:113]
	v_mfma_f32_16x16x32_bf16 v[106:109], v[154:157], v[198:201], v[106:109]
	v_mfma_f32_16x16x32_bf16 v[122:125], v[146:149], v[206:209], v[122:125]
	v_mfma_f32_16x16x32_bf16 v[126:129], v[154:157], v[206:209], v[126:129]
	v_mfma_f32_16x16x32_bf16 v[34:37], v[134:137], v[186:189], v[34:37]
	v_mfma_f32_16x16x32_bf16 v[30:33], v[142:145], v[186:189], v[30:33]
	v_mfma_f32_16x16x32_bf16 v[46:49], v[134:137], v[194:197], v[46:49]
	v_mfma_f32_16x16x32_bf16 v[62:65], v[142:145], v[194:197], v[62:65]
	v_mfma_f32_16x16x32_bf16 v[78:81], v[134:137], v[202:205], v[78:81]
	v_mfma_f32_16x16x32_bf16 v[90:93], v[142:145], v[202:205], v[90:93]
	v_mfma_f32_16x16x32_bf16 v[130:133], v[134:137], v[210:213], v[130:133]
	v_mfma_f32_16x16x32_bf16 v[114:117], v[142:145], v[210:213], v[114:117]
	v_mfma_f32_16x16x32_bf16 v[26:29], v[150:153], v[186:189], v[26:29]
	v_mfma_f32_16x16x32_bf16 v[50:53], v[178:181], v[186:189], v[50:53]
	v_mfma_f32_16x16x32_bf16 v[58:61], v[150:153], v[194:197], v[58:61]
	v_mfma_f32_16x16x32_bf16 v[82:85], v[178:181], v[194:197], v[82:85]
	v_mfma_f32_16x16x32_bf16 v[110:113], v[150:153], v[202:205], v[110:113]
	v_mfma_f32_16x16x32_bf16 v[106:109], v[178:181], v[202:205], v[106:109]
	v_mfma_f32_16x16x32_bf16 v[122:125], v[150:153], v[210:213], v[122:125]
	v_mfma_f32_16x16x32_bf16 v[126:129], v[178:181], v[210:213], v[126:129]
	s_setprio 0
	s_barrier
	s_nop 0
	s_add_u32 s0, s24, 0x80
	s_addc_u32 s1, s25, 0
	s_add_i32 s84, s84, s45
	s_mov_b32 m0, s84
	s_add_i32 s85, s84, 0x2000
	ds_read_b128 v[182:185], v174 offset:49152
	ds_read_b128 v[186:189], v174 offset:50176
	ds_read_b128 v[190:193], v174 offset:51200
	ds_read_b128 v[194:197], v174 offset:52224
	ds_read_b128 v[198:201], v174 offset:53248
	ds_read_b128 v[202:205], v174 offset:54272
	ds_read_b128 v[206:209], v174 offset:55296
	ds_read_b128 v[210:213], v174 offset:56320
	s_nop 0
	global_load_lds_dwordx4 v164, s[0:1]
	s_mov_b32 m0, s85
	s_nop 0
	global_load_lds_dwordx4 v166, s[0:1]
	s_add_u32 s0, s24, 0x100080
	s_addc_u32 s1, s25, 0
	s_add_i32 s86, s86, s45
	s_mov_b32 m0, s86
	s_add_i32 s87, s86, 0x2000
	s_nop 0
	global_load_lds_dwordx4 v164, s[0:1]
	s_mov_b32 m0, s87
	s_nop 0
	global_load_lds_dwordx4 v166, s[0:1]
	s_mov_b32 m0, s57
	s_nop 0
	global_load_lds_dwordx4 v1, s[2:3]
	s_mov_b32 m0, s62
	s_nop 0
	global_load_lds_dwordx4 v165, s[2:3]
	s_waitcnt vmcnt(8)
	s_waitcnt lgkmcnt(0)
	s_setprio 1
	s_waitcnt lgkmcnt(0)
	s_barrier
	v_mfma_f32_16x16x32_bf16 v[102:105], v[118:121], v[182:185], v[102:105]
	v_mfma_f32_16x16x32_bf16 v[98:101], v[138:141], v[182:185], v[98:101]
	v_mfma_f32_16x16x32_bf16 v[74:77], v[118:121], v[190:193], v[74:77]
	v_mfma_f32_16x16x32_bf16 v[70:73], v[138:141], v[190:193], v[70:73]
	v_mfma_f32_16x16x32_bf16 v[42:45], v[118:121], v[198:201], v[42:45]
	v_mfma_f32_16x16x32_bf16 v[38:41], v[138:141], v[198:201], v[38:41]
	v_mfma_f32_16x16x32_bf16 v[18:21], v[118:121], v[206:209], v[18:21]
	v_mfma_f32_16x16x32_bf16 v[10:13], v[138:141], v[206:209], v[10:13]
	v_mfma_f32_16x16x32_bf16 v[94:97], v[146:149], v[182:185], v[94:97]
	v_mfma_f32_16x16x32_bf16 v[86:89], v[154:157], v[182:185], v[86:89]
	v_mfma_f32_16x16x32_bf16 v[66:69], v[146:149], v[190:193], v[66:69]
	v_mfma_f32_16x16x32_bf16 v[54:57], v[154:157], v[190:193], v[54:57]
	v_mfma_f32_16x16x32_bf16 v[22:25], v[146:149], v[198:201], v[22:25]
	v_mfma_f32_16x16x32_bf16 v[14:17], v[154:157], v[198:201], v[14:17]
	v_mfma_f32_16x16x32_bf16 v[6:9], v[146:149], v[206:209], v[6:9]
	v_mfma_f32_16x16x32_bf16 v[2:5], v[154:157], v[206:209], v[2:5]
	v_mfma_f32_16x16x32_bf16 v[102:105], v[134:137], v[186:189], v[102:105]
	v_mfma_f32_16x16x32_bf16 v[98:101], v[142:145], v[186:189], v[98:101]
	v_mfma_f32_16x16x32_bf16 v[74:77], v[134:137], v[194:197], v[74:77]
	v_mfma_f32_16x16x32_bf16 v[70:73], v[142:145], v[194:197], v[70:73]
	v_mfma_f32_16x16x32_bf16 v[42:45], v[134:137], v[202:205], v[42:45]
	v_mfma_f32_16x16x32_bf16 v[38:41], v[142:145], v[202:205], v[38:41]
	v_mfma_f32_16x16x32_bf16 v[18:21], v[134:137], v[210:213], v[18:21]
	v_mfma_f32_16x16x32_bf16 v[10:13], v[142:145], v[210:213], v[10:13]
	v_mfma_f32_16x16x32_bf16 v[94:97], v[150:153], v[186:189], v[94:97]
	v_mfma_f32_16x16x32_bf16 v[86:89], v[178:181], v[186:189], v[86:89]
	v_mfma_f32_16x16x32_bf16 v[66:69], v[150:153], v[194:197], v[66:69]
	v_mfma_f32_16x16x32_bf16 v[54:57], v[178:181], v[194:197], v[54:57]
	v_mfma_f32_16x16x32_bf16 v[22:25], v[150:153], v[202:205], v[22:25]
	v_mfma_f32_16x16x32_bf16 v[14:17], v[178:181], v[202:205], v[14:17]
	v_mfma_f32_16x16x32_bf16 v[6:9], v[150:153], v[210:213], v[6:9]
	v_mfma_f32_16x16x32_bf16 v[2:5], v[178:181], v[210:213], v[2:5]
	s_setprio 0
	s_barrier
; __device__ __forceinline__ float bf_lo(unsigned w) { return __uint_as_float(w << 16); }
; __device__ __forceinline__ float bf_hi(unsigned w) { return __uint_as_float(w & 0xffff0000u); }
;     __device__ __forceinline__ void mid(f32x4 (&acc)[2][2][4][2], const Unit& u, int wr, int wc, int fr, int fq) const {
;     ...
;             for (int m = 0; m < 4; ++m) { const size_t off = (size_t)(row0 + ai * HALF + m * 16) * 4096 + col0;
; #pragma unroll
;                 for (int bj = 0; bj < 2; ++bj) { const u32x4 ga = *(const u32x4*)(SGA + off + bj * HALF), gb = *(const u32x4*)(SGB + off + bj * HALF);
;                     const unsigned wa[4] = {ga.x, ga.y, ga.z, ga.w}, wb[4] = {gb.x, gb.y, gb.z, gb.w};
; #pragma unroll
;                     for (int p = 0; p < 4; ++p) { const float rl = bf_lo(wa[p]) * __builtin_amdgcn_rcpf(fmaxf(bf_lo(wb[p]), 1e-20f)), rh = bf_hi(wa[p]) * __builtin_amdgcn_rcpf(fmaxf(bf_hi(wb[p]), 1e-20f));
;                         acc[ai][bj][m][p >> 1][(p & 1) * 2] *= rl; acc[ai][bj][m][p >> 1][(p & 1) * 2 + 1] *= rh; } }
	s_add_i32 s33, s33, 2
	s_add_u32 s5, s5, 0x100
	s_addc_u32 s21, s21, 0
	s_cmp_gt_u32 s33, 29
	s_mov_b64 s[0:1], s[16:17]
	s_cbranch_scc0 .LBB0_746
	v_mov_b32_e32 v119, v167
	v_mov_b32_e32 v118, v168
	s_lshl_b32 s89, s20, 8
	s_lshl_b32 s88, s4, 8
	s_or_b32 s0, s89, s56
	v_lshl_add_u32 v118, v118, 3, s0
	s_add_i32 s0, s88, s55
	v_add_u32_e32 v120, s0, v119
	v_ashrrev_i32_e32 v121, 31, v120
	v_ashrrev_i32_e32 v119, 31, v118
	v_lshlrev_b64 v[120:121], 12, v[120:121]
	v_lshl_add_u64 v[118:119], v[120:121], 0, v[118:119]
	v_lshlrev_b64 v[162:163], 1, v[118:119]
	v_lshl_add_u64 v[138:139], s[12:13], 0, v[162:163]
	global_load_dwordx4 v[134:137], v[138:139], off
	v_lshl_add_u64 v[140:141], s[10:11], 0, v[162:163]
	global_load_dwordx4 v[118:121], v[140:141], off
	global_load_dwordx4 v[150:153], v[138:139], off offset:256
	global_load_dwordx4 v[146:149], v[140:141], off offset:256
	s_mov_b64 s[0:1], 0x20000
	v_lshl_add_u64 v[138:139], v[162:163], 0, s[0:1]
	v_lshl_add_u64 v[154:155], s[10:11], 0, v[138:139]
	v_lshl_add_u64 v[156:157], s[12:13], 0, v[138:139]
	global_load_dwordx4 v[138:141], v[154:155], off
	global_load_dwordx4 v[142:145], v[156:157], off
	s_mov_b64 s[0:1], 0x40000
	s_add_i32 s50, s50, 1
	v_readlane_b32 s2, v238, 45
	s_waitcnt vmcnt(0)
	v_lshlrev_b32_e32 v178, 16, v118
	v_and_b32_e32 v180, 0xffff0000, v134
	v_lshlrev_b32_e32 v181, 16, v135
	v_and_b32_e32 v182, 0xffff0000, v135
	v_lshlrev_b32_e32 v183, 16, v136
	v_and_b32_e32 v184, 0xffff0000, v136
	v_lshlrev_b32_e32 v185, 16, v137
	v_and_b32_e32 v186, 0xffff0000, v137
	v_lshlrev_b32_e32 v187, 16, v150
	v_and_b32_e32 v150, 0xffff0000, v150
	v_lshlrev_b32_e32 v188, 16, v151
	v_and_b32_e32 v151, 0xffff0000, v151
	v_max_f32_e32 v180, v180, v180
	v_max_f32_e32 v181, v181, v181
	v_max_f32_e32 v182, v182, v182
	v_max_f32_e32 v183, v183, v183
	v_max_f32_e32 v184, v184, v184
	v_max_f32_e32 v185, v185, v185
	v_max_f32_e32 v186, v186, v186
	v_max_f32_e32 v187, v187, v187
	v_max_f32_e32 v150, v150, v150
	v_max_f32_e32 v188, v188, v188
	v_max_f32_e32 v151, v151, v151
	v_max_f32_e32 v180, 0x1e3ce508, v180
	v_max_f32_e32 v181, 0x1e3ce508, v181
	v_max_f32_e32 v182, 0x1e3ce508, v182
	v_max_f32_e32 v183, 0x1e3ce508, v183
	v_max_f32_e32 v184, 0x1e3ce508, v184
	v_max_f32_e32 v185, 0x1e3ce508, v185
	v_max_f32_e32 v186, 0x1e3ce508, v186
	v_max_f32_e32 v187, 0x1e3ce508, v187
	v_max_f32_e32 v189, 0x1e3ce508, v150
	v_max_f32_e32 v188, 0x1e3ce508, v188
	v_max_f32_e32 v190, 0x1e3ce508, v151
	v_rcp_f32_e32 v151, v180
	v_rcp_f32_e32 v180, v181
	v_rcp_f32_e32 v181, v182
	v_rcp_f32_e32 v182, v183
	v_rcp_f32_e32 v183, v184
	v_rcp_f32_e32 v184, v185
	v_rcp_f32_e32 v185, v186
	v_rcp_f32_e32 v186, v187
	v_rcp_f32_e32 v187, v189
	v_rcp_f32_e32 v188, v188
	v_rcp_f32_e32 v189, v190
	v_and_b32_e32 v179, 0xffff0000, v118
	v_lshlrev_b32_e32 v118, 16, v119
	v_and_b32_e32 v119, 0xffff0000, v119
	v_lshlrev_b32_e32 v177, 16, v134
	v_lshlrev_b32_e32 v134, 16, v120
	v_and_b32_e32 v135, 0xffff0000, v120
	v_lshlrev_b32_e32 v120, 16, v121
	v_and_b32_e32 v121, 0xffff0000, v121
	v_lshlrev_b32_e32 v136, 16, v146
	v_and_b32_e32 v137, 0xffff0000, v146
	v_lshlrev_b32_e32 v146, 16, v147
	v_and_b32_e32 v147, 0xffff0000, v147
	v_pk_mul_f32 v[118:119], v[180:181], v[118:119]
	v_pk_mul_f32 v[134:135], v[182:183], v[134:135]
	v_pk_mul_f32 v[120:121], v[184:185], v[120:121]
	v_pk_mul_f32 v[36:37], v[36:37], v[118:119]
	v_pk_mul_f32 v[118:119], v[188:189], v[146:147]
	v_pk_mul_f32 v[30:31], v[30:31], v[134:135]
	v_pk_mul_f32 v[32:33], v[32:33], v[120:121]
	v_pk_mul_f32 v[28:29], v[28:29], v[118:119]
	global_load_dwordx4 v[118:121], v[156:157], off offset:256
	v_lshlrev_b32_e32 v134, 16, v152
	v_max_f32_e32 v134, v134, v134
	v_max_f32_e32 v134, 0x1e3ce508, v134
	v_rcp_f32_e32 v146, v134
	v_and_b32_e32 v134, 0xffff0000, v152
	v_max_f32_e32 v134, v134, v134
	v_pk_mul_f32 v[136:137], v[186:187], v[136:137]
	v_max_f32_e32 v134, 0x1e3ce508, v134
	v_pk_mul_f32 v[26:27], v[26:27], v[136:137]
	v_rcp_f32_e32 v147, v134
	global_load_dwordx4 v[134:137], v[154:155], off offset:256
	v_max_f32_e32 v177, v177, v177
	v_max_f32_e32 v177, 0x1e3ce508, v177
	v_rcp_f32_e32 v150, v177
	s_nop 0
	v_pk_mul_f32 v[150:151], v[150:151], v[178:179]
	s_nop 0
	v_pk_mul_f32 v[34:35], v[34:35], v[150:151]
	v_lshlrev_b32_e32 v150, 16, v148
	v_and_b32_e32 v151, 0xffff0000, v148
	v_lshlrev_b32_e32 v148, 16, v153
	v_max_f32_e32 v148, v148, v148
	v_max_f32_e32 v148, 0x1e3ce508, v148
	v_pk_mul_f32 v[146:147], v[146:147], v[150:151]
	v_rcp_f32_e32 v150, v148
	v_and_b32_e32 v148, 0xffff0000, v153
	v_max_f32_e32 v148, v148, v148
	v_max_f32_e32 v148, 0x1e3ce508, v148
	v_rcp_f32_e32 v151, v148
	v_pk_mul_f32 v[50:51], v[50:51], v[146:147]
	v_lshlrev_b32_e32 v146, 16, v149
	v_and_b32_e32 v147, 0xffff0000, v149
	v_pk_mul_f32 v[146:147], v[150:151], v[146:147]
	v_lshlrev_b32_e32 v148, 16, v142
	v_and_b32_e32 v142, 0xffff0000, v142
	v_pk_mul_f32 v[52:53], v[52:53], v[146:147]
	v_lshlrev_b32_e32 v146, 16, v138
	v_and_b32_e32 v147, 0xffff0000, v138
	v_lshlrev_b32_e32 v138, 16, v143
	v_max_f32_e32 v148, v148, v148
	v_max_f32_e32 v142, v142, v142
	v_max_f32_e32 v138, v138, v138
	v_max_f32_e32 v148, 0x1e3ce508, v148
	v_max_f32_e32 v142, 0x1e3ce508, v142
	v_max_f32_e32 v138, 0x1e3ce508, v138
	v_rcp_f32_e32 v148, v148
	v_rcp_f32_e32 v149, v142
	v_rcp_f32_e32 v142, v138
	v_and_b32_e32 v138, 0xffff0000, v143
	v_max_f32_e32 v138, v138, v138
	v_max_f32_e32 v138, 0x1e3ce508, v138
	v_rcp_f32_e32 v143, v138
	v_lshl_add_u64 v[150:151], v[162:163], 0, s[0:1]
	v_pk_mul_f32 v[146:147], v[148:149], v[146:147]
	v_lshl_add_u64 v[154:155], s[12:13], 0, v[150:151]
	v_pk_mul_f32 v[46:47], v[46:47], v[146:147]
	global_load_dwordx4 v[146:149], v[154:155], off
	v_lshlrev_b32_e32 v138, 16, v139
	v_and_b32_e32 v139, 0xffff0000, v139
	v_pk_mul_f32 v[138:139], v[142:143], v[138:139]
	v_lshlrev_b32_e32 v142, 16, v144
	v_max_f32_e32 v142, v142, v142
	v_max_f32_e32 v142, 0x1e3ce508, v142
	v_rcp_f32_e32 v156, v142
	v_lshl_add_u64 v[142:143], s[10:11], 0, v[150:151]
	global_load_dwordx4 v[150:153], v[142:143], off
	v_and_b32_e32 v144, 0xffff0000, v144
	v_pk_mul_f32 v[48:49], v[48:49], v[138:139]
	v_lshlrev_b32_e32 v138, 16, v140
	v_and_b32_e32 v139, 0xffff0000, v140
	v_lshlrev_b32_e32 v140, 16, v145
	v_max_f32_e32 v144, v144, v144
	v_max_f32_e32 v140, v140, v140
	v_max_f32_e32 v144, 0x1e3ce508, v144
	v_max_f32_e32 v140, 0x1e3ce508, v140
	v_rcp_f32_e32 v157, v144
	v_rcp_f32_e32 v144, v140
	v_and_b32_e32 v140, 0xffff0000, v145
	v_max_f32_e32 v140, v140, v140
	v_max_f32_e32 v140, 0x1e3ce508, v140
	v_rcp_f32_e32 v145, v140
	s_waitcnt vmcnt(3)
; __device__ __forceinline__ float bf_lo(unsigned w) { return __uint_as_float(w << 16); }
; __device__ __forceinline__ float bf_hi(unsigned w) { return __uint_as_float(w & 0xffff0000u); }
;     __device__ __forceinline__ void mid(f32x4 (&acc)[2][2][4][2], const Unit& u, int wr, int wc, int fr, int fq) const {
;     ...
;             for (int m = 0; m < 4; ++m) { const size_t off = (size_t)(row0 + ai * HALF + m * 16) * 4096 + col0;
; #pragma unroll
;                 for (int bj = 0; bj < 2; ++bj) { const u32x4 ga = *(const u32x4*)(SGA + off + bj * HALF), gb = *(const u32x4*)(SGB + off + bj * HALF);
;                     const unsigned wa[4] = {ga.x, ga.y, ga.z, ga.w}, wb[4] = {gb.x, gb.y, gb.z, gb.w};
; #pragma unroll
;                     for (int p = 0; p < 4; ++p) { const float rl = bf_lo(wa[p]) * __builtin_amdgcn_rcpf(fmaxf(bf_lo(wb[p]), 1e-20f)), rh = bf_hi(wa[p]) * __builtin_amdgcn_rcpf(fmaxf(bf_hi(wb[p]), 1e-20f));
;                         acc[ai][bj][m][p >> 1][(p & 1) * 2] *= rl; acc[ai][bj][m][p >> 1][(p & 1) * 2 + 1] *= rh; } }
	v_lshlrev_b32_e32 v140, 16, v118
	v_and_b32_e32 v118, 0xffff0000, v118
	v_max_f32_e32 v140, v140, v140
	v_max_f32_e32 v118, v118, v118
	v_pk_mul_f32 v[138:139], v[156:157], v[138:139]
	v_max_f32_e32 v140, 0x1e3ce508, v140
	v_max_f32_e32 v118, 0x1e3ce508, v118
	v_pk_mul_f32 v[62:63], v[62:63], v[138:139]
	v_lshlrev_b32_e32 v138, 16, v141
	v_and_b32_e32 v139, 0xffff0000, v141
	v_rcp_f32_e32 v140, v140
	v_rcp_f32_e32 v141, v118
	v_pk_mul_f32 v[138:139], v[144:145], v[138:139]
	global_load_dwordx4 v[142:145], v[142:143], off offset:256
	v_pk_mul_f32 v[64:65], v[64:65], v[138:139]
	s_waitcnt vmcnt(3)
	v_lshlrev_b32_e32 v138, 16, v134
	v_and_b32_e32 v139, 0xffff0000, v134
	v_pk_mul_f32 v[138:139], v[140:141], v[138:139]
	v_lshlrev_b32_e32 v118, 16, v119
	v_pk_mul_f32 v[58:59], v[58:59], v[138:139]
	global_load_dwordx4 v[138:141], v[154:155], off offset:256
	v_and_b32_e32 v119, 0xffff0000, v119
	v_max_f32_e32 v118, v118, v118
	v_max_f32_e32 v119, v119, v119
	v_max_f32_e32 v118, 0x1e3ce508, v118
	v_max_f32_e32 v119, 0x1e3ce508, v119
	v_rcp_f32_e32 v118, v118
	v_rcp_f32_e32 v119, v119
	v_lshlrev_b32_e32 v134, 16, v135
	v_and_b32_e32 v135, 0xffff0000, v135
	s_mov_b64 s[0:1], 0x60000
	v_pk_mul_f32 v[118:119], v[118:119], v[134:135]
	v_lshlrev_b32_e32 v134, 16, v136
	v_pk_mul_f32 v[60:61], v[60:61], v[118:119]
	v_lshlrev_b32_e32 v118, 16, v120
	v_and_b32_e32 v119, 0xffff0000, v120
	v_max_f32_e32 v118, v118, v118
	v_max_f32_e32 v119, v119, v119
	v_max_f32_e32 v118, 0x1e3ce508, v118
	v_max_f32_e32 v119, 0x1e3ce508, v119
	v_lshlrev_b32_e32 v120, 16, v121
	v_and_b32_e32 v121, 0xffff0000, v121
	v_rcp_f32_e32 v118, v118
	v_rcp_f32_e32 v119, v119
	v_max_f32_e32 v120, v120, v120
	v_max_f32_e32 v121, v121, v121
	v_max_f32_e32 v120, 0x1e3ce508, v120
	v_max_f32_e32 v121, 0x1e3ce508, v121
	v_rcp_f32_e32 v120, v120
	v_rcp_f32_e32 v121, v121
	v_and_b32_e32 v135, 0xffff0000, v136
	v_pk_mul_f32 v[118:119], v[118:119], v[134:135]
	s_nop 0
	v_pk_mul_f32 v[82:83], v[82:83], v[118:119]
	v_lshlrev_b32_e32 v118, 16, v137
	v_and_b32_e32 v119, 0xffff0000, v137
	v_pk_mul_f32 v[118:119], v[120:121], v[118:119]
	s_waitcnt vmcnt(3)
	v_lshlrev_b32_e32 v120, 16, v146
	v_and_b32_e32 v121, 0xffff0000, v146
	v_max_f32_e32 v120, v120, v120
	v_max_f32_e32 v121, v121, v121
	v_max_f32_e32 v120, 0x1e3ce508, v120
	v_max_f32_e32 v121, 0x1e3ce508, v121
	v_rcp_f32_e32 v120, v120
	v_rcp_f32_e32 v121, v121
	v_pk_mul_f32 v[84:85], v[84:85], v[118:119]
	s_waitcnt vmcnt(2)
	v_lshlrev_b32_e32 v118, 16, v150
	v_and_b32_e32 v119, 0xffff0000, v150
	v_pk_mul_f32 v[118:119], v[120:121], v[118:119]
	v_lshlrev_b32_e32 v150, 16, v151
	v_pk_mul_f32 v[78:79], v[78:79], v[118:119]
	v_lshlrev_b32_e32 v118, 16, v147
	v_and_b32_e32 v119, 0xffff0000, v147
	v_lshl_add_u64 v[146:147], v[162:163], 0, s[0:1]
	v_lshl_add_u64 v[120:121], s[12:13], 0, v[146:147]
	v_max_f32_e32 v118, v118, v118
	v_max_f32_e32 v119, v119, v119
	global_load_dwordx4 v[134:137], v[120:121], off
	v_max_f32_e32 v118, 0x1e3ce508, v118
	v_max_f32_e32 v119, 0x1e3ce508, v119
	v_rcp_f32_e32 v118, v118
	v_rcp_f32_e32 v119, v119
	v_and_b32_e32 v151, 0xffff0000, v151
	s_mov_b64 s[0:1], 0x120000
	v_pk_mul_f32 v[150:151], v[118:119], v[150:151]
	v_lshlrev_b32_e32 v118, 16, v148
	v_max_f32_e32 v118, v118, v118
	v_max_f32_e32 v118, 0x1e3ce508, v118
	v_rcp_f32_e32 v178, v118
	v_lshl_add_u64 v[118:119], s[10:11], 0, v[146:147]
	global_load_dwordx4 v[154:157], v[118:119], off
	v_and_b32_e32 v146, 0xffff0000, v148
	v_max_f32_e32 v146, v146, v146
	v_max_f32_e32 v146, 0x1e3ce508, v146
	v_lshlrev_b32_e32 v148, 16, v149
	v_and_b32_e32 v149, 0xffff0000, v149
	v_rcp_f32_e32 v179, v146
	v_max_f32_e32 v148, v148, v148
	v_max_f32_e32 v149, v149, v149
	v_max_f32_e32 v148, 0x1e3ce508, v148
	v_max_f32_e32 v149, 0x1e3ce508, v149
	v_rcp_f32_e32 v148, v148
	v_rcp_f32_e32 v149, v149
	v_lshlrev_b32_e32 v146, 16, v152
	v_and_b32_e32 v147, 0xffff0000, v152
	v_pk_mul_f32 v[146:147], v[178:179], v[146:147]
	v_pk_mul_f32 v[80:81], v[80:81], v[150:151]
	v_pk_mul_f32 v[90:91], v[90:91], v[146:147]
	v_lshlrev_b32_e32 v146, 16, v153
	v_and_b32_e32 v147, 0xffff0000, v153
	v_pk_mul_f32 v[146:147], v[148:149], v[146:147]
	s_waitcnt vmcnt(2)
	v_lshlrev_b32_e32 v148, 16, v138
	v_and_b32_e32 v138, 0xffff0000, v138
	v_max_f32_e32 v148, v148, v148
	v_max_f32_e32 v138, v138, v138
	v_max_f32_e32 v148, 0x1e3ce508, v148
	v_max_f32_e32 v138, 0x1e3ce508, v138
	global_load_dwordx4 v[150:153], v[120:121], off offset:256
	v_rcp_f32_e32 v148, v148
	v_rcp_f32_e32 v149, v138
	v_pk_mul_f32 v[92:93], v[92:93], v[146:147]
	v_lshlrev_b32_e32 v146, 16, v142
	v_and_b32_e32 v147, 0xffff0000, v142
	v_pk_mul_f32 v[146:147], v[148:149], v[146:147]
	v_lshlrev_b32_e32 v138, 16, v139
	v_pk_mul_f32 v[110:111], v[110:111], v[146:147]
	global_load_dwordx4 v[146:149], v[118:119], off offset:256
	v_and_b32_e32 v139, 0xffff0000, v139
	v_max_f32_e32 v138, v138, v138
	v_max_f32_e32 v139, v139, v139
	v_max_f32_e32 v138, 0x1e3ce508, v138
	v_max_f32_e32 v120, 0x1e3ce508, v139
	v_rcp_f32_e32 v138, v138
	v_rcp_f32_e32 v139, v120
	v_lshlrev_b32_e32 v120, 16, v143
	v_and_b32_e32 v121, 0xffff0000, v143
	v_and_b32_e32 v119, 0xffff0000, v140
	v_pk_mul_f32 v[120:121], v[138:139], v[120:121]
	v_lshlrev_b32_e32 v138, 16, v140
	v_max_f32_e32 v138, v138, v138
	v_max_f32_e32 v119, v119, v119
	v_max_f32_e32 v118, 0x1e3ce508, v138
	v_max_f32_e32 v119, 0x1e3ce508, v119
	v_rcp_f32_e32 v118, v118
	v_rcp_f32_e32 v119, v119
	v_pk_mul_f32 v[112:113], v[112:113], v[120:121]
	v_lshlrev_b32_e32 v120, 16, v144
	v_and_b32_e32 v121, 0xffff0000, v144
	v_pk_mul_f32 v[118:119], v[118:119], v[120:121]
	v_lshlrev_b32_e32 v120, 16, v141
	v_and_b32_e32 v121, 0xffff0000, v141
	v_max_f32_e32 v120, v120, v120
	v_max_f32_e32 v121, v121, v121
	v_max_f32_e32 v120, 0x1e3ce508, v120
	v_max_f32_e32 v121, 0x1e3ce508, v121
	v_rcp_f32_e32 v120, v120
	v_rcp_f32_e32 v121, v121
	v_pk_mul_f32 v[118:119], v[106:107], v[118:119]
	v_lshlrev_b32_e32 v106, 16, v145
	v_and_b32_e32 v107, 0xffff0000, v145
	v_pk_mul_f32 v[106:107], v[120:121], v[106:107]
	s_waitcnt vmcnt(3)
; __device__ __forceinline__ float bf_lo(unsigned w) { return __uint_as_float(w << 16); }
; __device__ __forceinline__ float bf_hi(unsigned w) { return __uint_as_float(w & 0xffff0000u); }
;     __device__ __forceinline__ void mid(f32x4 (&acc)[2][2][4][2], const Unit& u, int wr, int wc, int fr, int fq) const {
;     ...
;             for (int m = 0; m < 4; ++m) { const size_t off = (size_t)(row0 + ai * HALF + m * 16) * 4096 + col0;
; #pragma unroll
;                 for (int bj = 0; bj < 2; ++bj) { const u32x4 ga = *(const u32x4*)(SGA + off + bj * HALF), gb = *(const u32x4*)(SGB + off + bj * HALF);
;                     const unsigned wa[4] = {ga.x, ga.y, ga.z, ga.w}, wb[4] = {gb.x, gb.y, gb.z, gb.w};
; #pragma unroll
;                     for (int p = 0; p < 4; ++p) { const float rl = bf_lo(wa[p]) * __builtin_amdgcn_rcpf(fmaxf(bf_lo(wb[p]), 1e-20f)), rh = bf_hi(wa[p]) * __builtin_amdgcn_rcpf(fmaxf(bf_hi(wb[p]), 1e-20f));
;                         acc[ai][bj][m][p >> 1][(p & 1) * 2] *= rl; acc[ai][bj][m][p >> 1][(p & 1) * 2 + 1] *= rh; } }
	v_lshlrev_b32_e32 v120, 16, v134
	v_max_f32_e32 v120, v120, v120
	v_max_f32_e32 v120, 0x1e3ce508, v120
	v_rcp_f32_e32 v138, v120
	v_and_b32_e32 v120, 0xffff0000, v134
	v_max_f32_e32 v120, v120, v120
	v_max_f32_e32 v120, 0x1e3ce508, v120
	v_rcp_f32_e32 v139, v120
	v_pk_mul_f32 v[120:121], v[108:109], v[106:107]
	v_lshlrev_b32_e32 v108, 16, v135
	v_and_b32_e32 v109, 0xffff0000, v135
	v_max_f32_e32 v108, v108, v108
	v_max_f32_e32 v109, v109, v109
	v_max_f32_e32 v108, 0x1e3ce508, v108
	v_max_f32_e32 v109, 0x1e3ce508, v109
	v_rcp_f32_e32 v108, v108
	v_rcp_f32_e32 v109, v109
	s_waitcnt vmcnt(2)
	v_lshlrev_b32_e32 v106, 16, v154
	v_and_b32_e32 v107, 0xffff0000, v154
	v_pk_mul_f32 v[106:107], v[138:139], v[106:107]
	v_lshl_add_u64 v[140:141], v[162:163], 0, s[0:1]
	v_pk_mul_f32 v[106:107], v[130:131], v[106:107]
	v_lshlrev_b32_e32 v130, 16, v155
	v_and_b32_e32 v131, 0xffff0000, v155
	v_pk_mul_f32 v[108:109], v[108:109], v[130:131]
	v_lshlrev_b32_e32 v130, 16, v136
	v_and_b32_e32 v131, 0xffff0000, v136
	v_max_f32_e32 v130, v130, v130
	v_max_f32_e32 v131, v131, v131
	v_max_f32_e32 v130, 0x1e3ce508, v130
	v_max_f32_e32 v131, 0x1e3ce508, v131
	v_rcp_f32_e32 v130, v130
	v_rcp_f32_e32 v131, v131
	v_pk_mul_f32 v[108:109], v[132:133], v[108:109]
	v_lshlrev_b32_e32 v132, 16, v156
	v_and_b32_e32 v133, 0xffff0000, v156
	v_pk_mul_f32 v[130:131], v[130:131], v[132:133]
	v_lshlrev_b32_e32 v132, 16, v137
	v_and_b32_e32 v133, 0xffff0000, v137
	v_max_f32_e32 v132, v132, v132
	v_max_f32_e32 v133, v133, v133
	v_max_f32_e32 v132, 0x1e3ce508, v132
	v_max_f32_e32 v133, 0x1e3ce508, v133
	v_rcp_f32_e32 v132, v132
	v_rcp_f32_e32 v133, v133
	v_pk_mul_f32 v[114:115], v[114:115], v[130:131]
	v_lshlrev_b32_e32 v130, 16, v157
	v_and_b32_e32 v131, 0xffff0000, v157
	v_pk_mul_f32 v[130:131], v[132:133], v[130:131]
	s_waitcnt vmcnt(1)
	v_lshlrev_b32_e32 v132, 16, v150
	v_and_b32_e32 v133, 0xffff0000, v150
	v_max_f32_e32 v132, v132, v132
	v_max_f32_e32 v133, v133, v133
	v_max_f32_e32 v132, 0x1e3ce508, v132
	v_max_f32_e32 v133, 0x1e3ce508, v133
	v_rcp_f32_e32 v132, v132
	v_rcp_f32_e32 v133, v133
	v_pk_mul_f32 v[116:117], v[116:117], v[130:131]
	s_waitcnt vmcnt(0)
	v_lshlrev_b32_e32 v130, 16, v146
	v_and_b32_e32 v131, 0xffff0000, v146
	v_pk_mul_f32 v[130:131], v[132:133], v[130:131]
	v_lshlrev_b32_e32 v132, 16, v151
	v_and_b32_e32 v133, 0xffff0000, v151
	v_max_f32_e32 v132, v132, v132
	v_max_f32_e32 v133, v133, v133
	v_max_f32_e32 v132, 0x1e3ce508, v132
	v_max_f32_e32 v133, 0x1e3ce508, v133
	v_rcp_f32_e32 v132, v132
	v_rcp_f32_e32 v133, v133
	v_pk_mul_f32 v[122:123], v[122:123], v[130:131]
	v_lshlrev_b32_e32 v130, 16, v147
	v_and_b32_e32 v131, 0xffff0000, v147
	v_pk_mul_f32 v[130:131], v[132:133], v[130:131]
	v_lshlrev_b32_e32 v132, 16, v152
	v_and_b32_e32 v133, 0xffff0000, v152
	v_max_f32_e32 v132, v132, v132
	v_max_f32_e32 v133, v133, v133
	v_max_f32_e32 v132, 0x1e3ce508, v132
	v_max_f32_e32 v133, 0x1e3ce508, v133
	v_rcp_f32_e32 v132, v132
	v_rcp_f32_e32 v133, v133
	v_pk_mul_f32 v[124:125], v[124:125], v[130:131]
	v_lshlrev_b32_e32 v130, 16, v148
	v_and_b32_e32 v131, 0xffff0000, v148
	v_pk_mul_f32 v[130:131], v[132:133], v[130:131]
	v_lshlrev_b32_e32 v132, 16, v153
	v_and_b32_e32 v133, 0xffff0000, v153
	v_max_f32_e32 v132, v132, v132
	v_max_f32_e32 v133, v133, v133
	v_max_f32_e32 v132, 0x1e3ce508, v132
	v_max_f32_e32 v133, 0x1e3ce508, v133
	v_rcp_f32_e32 v132, v132
	v_rcp_f32_e32 v133, v133
	v_pk_mul_f32 v[126:127], v[126:127], v[130:131]
	v_lshlrev_b32_e32 v130, 16, v149
	v_and_b32_e32 v131, 0xffff0000, v149
	v_pk_mul_f32 v[130:131], v[132:133], v[130:131]
	v_lshl_add_u64 v[154:155], s[12:13], 0, v[140:141]
	v_pk_mul_f32 v[128:129], v[128:129], v[130:131]
	v_lshl_add_u64 v[130:131], v[162:163], 0, s[8:9]
	v_lshl_add_u64 v[132:133], s[12:13], 0, v[130:131]
	global_load_dwordx4 v[150:153], v[132:133], off
	v_lshl_add_u64 v[130:131], s[10:11], 0, v[130:131]
	global_load_dwordx4 v[146:149], v[130:131], off
	global_load_dwordx4 v[142:145], v[132:133], off offset:256
	global_load_dwordx4 v[134:137], v[130:131], off offset:256
	s_mov_b64 s[0:1], 0x140000
	s_waitcnt vmcnt(3)
	v_lshlrev_b32_e32 v130, 16, v150
	v_and_b32_e32 v131, 0xffff0000, v150
	v_max_f32_e32 v130, v130, v130
	v_max_f32_e32 v131, v131, v131
	v_max_f32_e32 v130, 0x1e3ce508, v130
	v_max_f32_e32 v131, 0x1e3ce508, v131
	v_rcp_f32_e32 v130, v130
	v_rcp_f32_e32 v131, v131
	s_waitcnt vmcnt(2)
	v_lshlrev_b32_e32 v132, 16, v146
	v_and_b32_e32 v133, 0xffff0000, v146
	v_lshlrev_b32_e32 v146, 16, v147
	v_pk_mul_f32 v[130:131], v[130:131], v[132:133]
	v_and_b32_e32 v147, 0xffff0000, v147
	v_pk_mul_f32 v[102:103], v[102:103], v[130:131]
	v_lshlrev_b32_e32 v130, 16, v151
	v_max_f32_e32 v130, v130, v130
	v_max_f32_e32 v130, 0x1e3ce508, v130
	v_rcp_f32_e32 v138, v130
	v_and_b32_e32 v130, 0xffff0000, v151
	v_max_f32_e32 v130, v130, v130
	v_max_f32_e32 v130, 0x1e3ce508, v130
	v_rcp_f32_e32 v139, v130
	global_load_dwordx4 v[130:133], v[154:155], off
	v_lshl_add_u64 v[150:151], s[10:11], 0, v[140:141]
	v_pk_mul_f32 v[146:147], v[138:139], v[146:147]
	v_lshlrev_b32_e32 v138, 16, v152
	v_max_f32_e32 v138, v138, v138
	v_max_f32_e32 v138, 0x1e3ce508, v138
	v_rcp_f32_e32 v156, v138
	global_load_dwordx4 v[138:141], v[150:151], off
	v_and_b32_e32 v152, 0xffff0000, v152
	v_pk_mul_f32 v[104:105], v[104:105], v[146:147]
	v_lshlrev_b32_e32 v146, 16, v148
	v_and_b32_e32 v147, 0xffff0000, v148
	v_lshlrev_b32_e32 v148, 16, v153
	v_max_f32_e32 v152, v152, v152
	v_max_f32_e32 v148, v148, v148
	v_max_f32_e32 v152, 0x1e3ce508, v152
	v_max_f32_e32 v148, 0x1e3ce508, v148
	v_rcp_f32_e32 v157, v152
	v_rcp_f32_e32 v152, v148
	v_and_b32_e32 v148, 0xffff0000, v153
	v_max_f32_e32 v148, v148, v148
	v_max_f32_e32 v148, 0x1e3ce508, v148
	v_rcp_f32_e32 v153, v148
	s_waitcnt vmcnt(3)
; __device__ __forceinline__ float bf_lo(unsigned w) { return __uint_as_float(w << 16); }
; __device__ __forceinline__ float bf_hi(unsigned w) { return __uint_as_float(w & 0xffff0000u); }
;     __device__ __forceinline__ void mid(f32x4 (&acc)[2][2][4][2], const Unit& u, int wr, int wc, int fr, int fq) const {
;     ...
;             for (int m = 0; m < 4; ++m) { const size_t off = (size_t)(row0 + ai * HALF + m * 16) * 4096 + col0;
; #pragma unroll
;                 for (int bj = 0; bj < 2; ++bj) { const u32x4 ga = *(const u32x4*)(SGA + off + bj * HALF), gb = *(const u32x4*)(SGB + off + bj * HALF);
;                     const unsigned wa[4] = {ga.x, ga.y, ga.z, ga.w}, wb[4] = {gb.x, gb.y, gb.z, gb.w};
; #pragma unroll
;                     for (int p = 0; p < 4; ++p) { const float rl = bf_lo(wa[p]) * __builtin_amdgcn_rcpf(fmaxf(bf_lo(wb[p]), 1e-20f)), rh = bf_hi(wa[p]) * __builtin_amdgcn_rcpf(fmaxf(bf_hi(wb[p]), 1e-20f));
;                         acc[ai][bj][m][p >> 1][(p & 1) * 2] *= rl; acc[ai][bj][m][p >> 1][(p & 1) * 2 + 1] *= rh; } }
	v_lshlrev_b32_e32 v148, 16, v142
	v_and_b32_e32 v142, 0xffff0000, v142
	v_max_f32_e32 v148, v148, v148
	v_max_f32_e32 v142, v142, v142
	v_pk_mul_f32 v[146:147], v[156:157], v[146:147]
	v_max_f32_e32 v148, 0x1e3ce508, v148
	v_max_f32_e32 v142, 0x1e3ce508, v142
	v_pk_mul_f32 v[98:99], v[98:99], v[146:147]
	v_lshlrev_b32_e32 v146, 16, v149
	v_and_b32_e32 v147, 0xffff0000, v149
	v_rcp_f32_e32 v148, v148
	v_rcp_f32_e32 v149, v142
	v_pk_mul_f32 v[146:147], v[152:153], v[146:147]
	global_load_dwordx4 v[150:153], v[150:151], off offset:256
	v_pk_mul_f32 v[100:101], v[100:101], v[146:147]
	s_waitcnt vmcnt(3)
	v_lshlrev_b32_e32 v146, 16, v134
	v_and_b32_e32 v147, 0xffff0000, v134
	v_pk_mul_f32 v[146:147], v[148:149], v[146:147]
	v_lshlrev_b32_e32 v134, 16, v143
	v_pk_mul_f32 v[94:95], v[94:95], v[146:147]
	global_load_dwordx4 v[146:149], v[154:155], off offset:256
	v_max_f32_e32 v134, v134, v134
	v_max_f32_e32 v134, 0x1e3ce508, v134
	v_rcp_f32_e32 v142, v134
	v_and_b32_e32 v134, 0xffff0000, v143
	v_max_f32_e32 v134, v134, v134
	v_max_f32_e32 v134, 0x1e3ce508, v134
	v_rcp_f32_e32 v143, v134
	v_lshlrev_b32_e32 v134, 16, v135
	v_and_b32_e32 v135, 0xffff0000, v135
	v_pk_mul_f32 v[134:135], v[142:143], v[134:135]
	s_nop 0
	v_pk_mul_f32 v[96:97], v[96:97], v[134:135]
	v_lshlrev_b32_e32 v134, 16, v144
	v_and_b32_e32 v135, 0xffff0000, v144
	v_max_f32_e32 v134, v134, v134
	v_max_f32_e32 v135, v135, v135
	v_max_f32_e32 v134, 0x1e3ce508, v134
	v_max_f32_e32 v135, 0x1e3ce508, v135
	v_rcp_f32_e32 v134, v134
	v_rcp_f32_e32 v135, v135
	v_lshlrev_b32_e32 v142, 16, v136
	v_and_b32_e32 v143, 0xffff0000, v136
	v_lshlrev_b32_e32 v136, 16, v145
	v_max_f32_e32 v136, v136, v136
	v_max_f32_e32 v136, 0x1e3ce508, v136
	v_pk_mul_f32 v[134:135], v[134:135], v[142:143]
	v_rcp_f32_e32 v142, v136
	v_and_b32_e32 v136, 0xffff0000, v145
	v_max_f32_e32 v136, v136, v136
	v_max_f32_e32 v136, 0x1e3ce508, v136
	v_rcp_f32_e32 v143, v136
	v_pk_mul_f32 v[86:87], v[86:87], v[134:135]
	v_lshlrev_b32_e32 v134, 16, v137
	v_and_b32_e32 v135, 0xffff0000, v137
	v_pk_mul_f32 v[134:135], v[142:143], v[134:135]
	s_waitcnt vmcnt(3)
	v_lshlrev_b32_e32 v136, 16, v130
	v_and_b32_e32 v130, 0xffff0000, v130
	v_max_f32_e32 v130, v130, v130
	v_max_f32_e32 v130, 0x1e3ce508, v130
	v_rcp_f32_e32 v137, v130
	v_lshlrev_b32_e32 v130, 16, v131
	v_max_f32_e32 v136, v136, v136
	v_max_f32_e32 v130, v130, v130
	v_max_f32_e32 v136, 0x1e3ce508, v136
	v_max_f32_e32 v130, 0x1e3ce508, v130
	v_rcp_f32_e32 v136, v136
	v_rcp_f32_e32 v142, v130
	v_and_b32_e32 v130, 0xffff0000, v131
	v_max_f32_e32 v130, v130, v130
	v_max_f32_e32 v130, 0x1e3ce508, v130
	v_pk_mul_f32 v[88:89], v[88:89], v[134:135]
	s_waitcnt vmcnt(2)
	v_lshlrev_b32_e32 v134, 16, v138
	v_and_b32_e32 v135, 0xffff0000, v138
	v_rcp_f32_e32 v143, v130
	v_lshl_add_u64 v[144:145], v[162:163], 0, s[0:1]
	v_pk_mul_f32 v[134:135], v[136:137], v[134:135]
	v_lshl_add_u64 v[130:131], s[12:13], 0, v[144:145]
	v_pk_mul_f32 v[74:75], v[74:75], v[134:135]
	global_load_dwordx4 v[134:137], v[130:131], off
	v_lshlrev_b32_e32 v138, 16, v139
	v_and_b32_e32 v139, 0xffff0000, v139
	v_pk_mul_f32 v[154:155], v[142:143], v[138:139]
	v_lshlrev_b32_e32 v138, 16, v132
	v_max_f32_e32 v138, v138, v138
	v_and_b32_e32 v132, 0xffff0000, v132
	v_max_f32_e32 v138, 0x1e3ce508, v138
	v_max_f32_e32 v132, v132, v132
	v_rcp_f32_e32 v156, v138
	v_lshl_add_u64 v[138:139], s[10:11], 0, v[144:145]
	v_max_f32_e32 v132, 0x1e3ce508, v132
	global_load_dwordx4 v[142:145], v[138:139], off
	v_rcp_f32_e32 v157, v132
	v_lshlrev_b32_e32 v132, 16, v133
	v_and_b32_e32 v133, 0xffff0000, v133
	v_max_f32_e32 v132, v132, v132
	v_max_f32_e32 v133, v133, v133
	v_max_f32_e32 v132, 0x1e3ce508, v132
	v_max_f32_e32 v133, 0x1e3ce508, v133
	v_rcp_f32_e32 v132, v132
	v_rcp_f32_e32 v133, v133
	v_pk_mul_f32 v[76:77], v[76:77], v[154:155]
	v_lshlrev_b32_e32 v154, 16, v140
	v_and_b32_e32 v155, 0xffff0000, v140
	v_lshlrev_b32_e32 v140, 16, v141
	v_and_b32_e32 v141, 0xffff0000, v141
	v_pk_mul_f32 v[132:133], v[132:133], v[140:141]
	s_waitcnt vmcnt(2)
	v_lshlrev_b32_e32 v140, 16, v146
	v_and_b32_e32 v141, 0xffff0000, v146
	v_max_f32_e32 v140, v140, v140
	v_max_f32_e32 v141, v141, v141
	v_max_f32_e32 v140, 0x1e3ce508, v140
	v_max_f32_e32 v141, 0x1e3ce508, v141
	v_rcp_f32_e32 v140, v140
	v_rcp_f32_e32 v141, v141
	v_pk_mul_f32 v[72:73], v[72:73], v[132:133]
	v_lshlrev_b32_e32 v132, 16, v150
	v_and_b32_e32 v133, 0xffff0000, v150
	v_pk_mul_f32 v[132:133], v[140:141], v[132:133]
	v_lshlrev_b32_e32 v140, 16, v147
	v_and_b32_e32 v141, 0xffff0000, v147
	v_max_f32_e32 v140, v140, v140
	v_max_f32_e32 v141, v141, v141
	v_max_f32_e32 v140, 0x1e3ce508, v140
	v_max_f32_e32 v141, 0x1e3ce508, v141
	v_rcp_f32_e32 v140, v140
	v_rcp_f32_e32 v141, v141
	v_pk_mul_f32 v[66:67], v[66:67], v[132:133]
	v_lshlrev_b32_e32 v132, 16, v151
	v_and_b32_e32 v133, 0xffff0000, v151
	v_pk_mul_f32 v[132:133], v[140:141], v[132:133]
	v_lshlrev_b32_e32 v140, 16, v148
	v_pk_mul_f32 v[68:69], v[68:69], v[132:133]
	global_load_dwordx4 v[130:133], v[130:131], off offset:256
	v_max_f32_e32 v140, v140, v140
	v_max_f32_e32 v140, 0x1e3ce508, v140
	v_rcp_f32_e32 v146, v140
	v_and_b32_e32 v140, 0xffff0000, v148
	v_max_f32_e32 v140, v140, v140
	v_max_f32_e32 v140, 0x1e3ce508, v140
	v_rcp_f32_e32 v147, v140
	global_load_dwordx4 v[138:141], v[138:139], off offset:256
	v_lshlrev_b32_e32 v148, 16, v149
	v_and_b32_e32 v149, 0xffff0000, v149
	v_max_f32_e32 v148, v148, v148
	v_max_f32_e32 v149, v149, v149
	v_max_f32_e32 v148, 0x1e3ce508, v148
	v_max_f32_e32 v149, 0x1e3ce508, v149
	v_rcp_f32_e32 v148, v148
	v_rcp_f32_e32 v149, v149
	v_lshlrev_b32_e32 v150, 16, v152
	v_and_b32_e32 v151, 0xffff0000, v152
	v_pk_mul_f32 v[146:147], v[146:147], v[150:151]
	s_mov_b64 s[0:1], 0x160000
	v_pk_mul_f32 v[54:55], v[54:55], v[146:147]
	v_lshlrev_b32_e32 v146, 16, v153
	v_and_b32_e32 v147, 0xffff0000, v153
	v_pk_mul_f32 v[146:147], v[148:149], v[146:147]
	v_pk_mul_f32 v[154:155], v[156:157], v[154:155]
	s_waitcnt vmcnt(3)
; __device__ __forceinline__ float bf_lo(unsigned w) { return __uint_as_float(w << 16); }
; __device__ __forceinline__ float bf_hi(unsigned w) { return __uint_as_float(w & 0xffff0000u); }
;     __device__ __forceinline__ void mid(f32x4 (&acc)[2][2][4][2], const Unit& u, int wr, int wc, int fr, int fq) const {
;     ...
;             for (int m = 0; m < 4; ++m) { const size_t off = (size_t)(row0 + ai * HALF + m * 16) * 4096 + col0;
; #pragma unroll
;                 for (int bj = 0; bj < 2; ++bj) { const u32x4 ga = *(const u32x4*)(SGA + off + bj * HALF), gb = *(const u32x4*)(SGB + off + bj * HALF);
;                     const unsigned wa[4] = {ga.x, ga.y, ga.z, ga.w}, wb[4] = {gb.x, gb.y, gb.z, gb.w};
; #pragma unroll
;                     for (int p = 0; p < 4; ++p) { const float rl = bf_lo(wa[p]) * __builtin_amdgcn_rcpf(fmaxf(bf_lo(wb[p]), 1e-20f)), rh = bf_hi(wa[p]) * __builtin_amdgcn_rcpf(fmaxf(bf_hi(wb[p]), 1e-20f));
;                         acc[ai][bj][m][p >> 1][(p & 1) * 2] *= rl; acc[ai][bj][m][p >> 1][(p & 1) * 2 + 1] *= rh; } }
	v_lshlrev_b32_e32 v148, 16, v134
	v_and_b32_e32 v134, 0xffff0000, v134
	v_max_f32_e32 v148, v148, v148
	v_max_f32_e32 v134, v134, v134
	v_max_f32_e32 v148, 0x1e3ce508, v148
	v_max_f32_e32 v134, 0x1e3ce508, v134
	v_rcp_f32_e32 v148, v148
	v_rcp_f32_e32 v149, v134
	v_pk_mul_f32 v[56:57], v[56:57], v[146:147]
	v_lshl_add_u64 v[150:151], v[162:163], 0, s[0:1]
	v_pk_mul_f32 v[70:71], v[70:71], v[154:155]
	v_lshlrev_b32_e32 v134, 16, v135
	s_waitcnt vmcnt(2)
	v_lshlrev_b32_e32 v146, 16, v142
	v_and_b32_e32 v147, 0xffff0000, v142
	v_pk_mul_f32 v[146:147], v[148:149], v[146:147]
	v_and_b32_e32 v135, 0xffff0000, v135
	v_lshl_add_u64 v[154:155], s[12:13], 0, v[150:151]
	v_pk_mul_f32 v[42:43], v[42:43], v[146:147]
	v_max_f32_e32 v134, v134, v134
	v_max_f32_e32 v135, v135, v135
	global_load_dwordx4 v[146:149], v[154:155], off
	v_max_f32_e32 v134, 0x1e3ce508, v134
	v_max_f32_e32 v135, 0x1e3ce508, v135
	v_rcp_f32_e32 v134, v134
	v_rcp_f32_e32 v135, v135
	v_lshlrev_b32_e32 v142, 16, v143
	v_and_b32_e32 v143, 0xffff0000, v143
	s_mul_i32 s0, s50, s63
	v_pk_mul_f32 v[142:143], v[134:135], v[142:143]
	v_lshlrev_b32_e32 v134, 16, v136
	v_max_f32_e32 v134, v134, v134
	v_max_f32_e32 v134, 0x1e3ce508, v134
	v_rcp_f32_e32 v156, v134
	v_lshl_add_u64 v[134:135], s[10:11], 0, v[150:151]
	global_load_dwordx4 v[150:153], v[134:135], off
	v_and_b32_e32 v136, 0xffff0000, v136
	v_max_f32_e32 v136, v136, v136
	v_max_f32_e32 v136, 0x1e3ce508, v136
	v_rcp_f32_e32 v157, v136
	v_lshlrev_b32_e32 v136, 16, v137
	v_and_b32_e32 v137, 0xffff0000, v137
	v_max_f32_e32 v136, v136, v136
	v_max_f32_e32 v137, v137, v137
	v_max_f32_e32 v136, 0x1e3ce508, v136
	v_max_f32_e32 v137, 0x1e3ce508, v137
	v_rcp_f32_e32 v136, v136
	v_rcp_f32_e32 v137, v137
	v_pk_mul_f32 v[44:45], v[44:45], v[142:143]
	v_lshlrev_b32_e32 v142, 16, v144
	v_and_b32_e32 v143, 0xffff0000, v144
	v_pk_mul_f32 v[142:143], v[156:157], v[142:143]
	s_mul_hi_u32 s1, s50, s2
	v_pk_mul_f32 v[38:39], v[38:39], v[142:143]
	v_lshlrev_b32_e32 v142, 16, v145
	v_and_b32_e32 v143, 0xffff0000, v145
	v_pk_mul_f32 v[136:137], v[136:137], v[142:143]
	s_waitcnt vmcnt(3)
	v_lshlrev_b32_e32 v142, 16, v130
	v_and_b32_e32 v130, 0xffff0000, v130
	v_max_f32_e32 v142, v142, v142
	v_max_f32_e32 v130, v130, v130
	v_max_f32_e32 v142, 0x1e3ce508, v142
	v_max_f32_e32 v130, 0x1e3ce508, v130
	v_rcp_f32_e32 v142, v142
	v_rcp_f32_e32 v143, v130
	v_lshlrev_b32_e32 v130, 16, v131
	v_and_b32_e32 v131, 0xffff0000, v131
	v_pk_mul_f32 v[40:41], v[40:41], v[136:137]
	s_waitcnt vmcnt(2)
	v_lshlrev_b32_e32 v136, 16, v138
	v_and_b32_e32 v137, 0xffff0000, v138
	v_max_f32_e32 v130, v130, v130
	v_max_f32_e32 v131, v131, v131
	v_pk_mul_f32 v[136:137], v[142:143], v[136:137]
	v_max_f32_e32 v130, 0x1e3ce508, v130
	global_load_dwordx4 v[142:145], v[154:155], off offset:256
	v_max_f32_e32 v131, 0x1e3ce508, v131
	v_rcp_f32_e32 v130, v130
	v_rcp_f32_e32 v131, v131
	v_pk_mul_f32 v[22:23], v[22:23], v[136:137]
	v_lshlrev_b32_e32 v136, 16, v139
	v_and_b32_e32 v137, 0xffff0000, v139
	v_pk_mul_f32 v[130:131], v[130:131], v[136:137]
	v_lshlrev_b32_e32 v136, 16, v132
	v_max_f32_e32 v138, v136, v136
	global_load_dwordx4 v[134:137], v[134:135], off offset:256
	v_and_b32_e32 v132, 0xffff0000, v132
	v_max_f32_e32 v132, v132, v132
	v_max_f32_e32 v132, 0x1e3ce508, v132
	v_max_f32_e32 v138, 0x1e3ce508, v138
	v_rcp_f32_e32 v139, v132
	v_lshlrev_b32_e32 v132, 16, v133
	v_and_b32_e32 v133, 0xffff0000, v133
	v_rcp_f32_e32 v138, v138
	v_max_f32_e32 v132, v132, v132
	v_max_f32_e32 v133, v133, v133
	v_max_f32_e32 v132, 0x1e3ce508, v132
	v_max_f32_e32 v133, 0x1e3ce508, v133
	v_rcp_f32_e32 v132, v132
	v_rcp_f32_e32 v133, v133
	v_pk_mul_f32 v[24:25], v[24:25], v[130:131]
	v_lshlrev_b32_e32 v130, 16, v140
	v_and_b32_e32 v131, 0xffff0000, v140
	v_pk_mul_f32 v[130:131], v[138:139], v[130:131]
	s_add_i32 s1, s1, s0
	v_pk_mul_f32 v[130:131], v[14:15], v[130:131]
	v_lshlrev_b32_e32 v14, 16, v141
	v_and_b32_e32 v15, 0xffff0000, v141
	v_pk_mul_f32 v[14:15], v[132:133], v[14:15]
	s_waitcnt vmcnt(3)
; __device__ __forceinline__ float bf_lo(unsigned w) { return __uint_as_float(w << 16); }
; __device__ __forceinline__ float bf_hi(unsigned w) { return __uint_as_float(w & 0xffff0000u); }
;     __device__ bool next(int i, Unit& u) const { if (i > 1) return false; const int xcd = c & 7, idx = c >> 3; u.pm = 16 * i + 4 * (xcd >> 1) + (idx & 3); u.pn = 8 * (xcd & 1) + (idx >> 2); return true; }
;     __host__ __device__ bool next(int i, Unit& u) const {
;         const long L = (long)i * G + c; if (L >= nwg) return false;
;         int wgid = (int)L; { const int q = nwg / NXCD, r = nwg % NXCD, xcd = wgid % NXCD, off = wgid / NXCD; wgid = (xcd < r ? xcd * (q + 1) : r * (q + 1) + (xcd - r) * q) + off; }
;         const int nig = WGM * nN, gid = wgid / nig, fm = gid * WGM, gsz = (nM - fm) < WGM ? (nM - fm) : WGM;
;         u.pm = fm + ((wgid % nig) % gsz); u.pn = (wgid % nig) / gsz; return true;
;     __device__ __forceinline__ void mid(f32x4 (&acc)[2][2][4][2], const Unit& u, int wr, int wc, int fr, int fq) const {
;     ...
;             for (int m = 0; m < 4; ++m) { const size_t off = (size_t)(row0 + ai * HALF + m * 16) * 4096 + col0;
; #pragma unroll
;                 for (int bj = 0; bj < 2; ++bj) { const u32x4 ga = *(const u32x4*)(SGA + off + bj * HALF), gb = *(const u32x4*)(SGB + off + bj * HALF);
;                     const unsigned wa[4] = {ga.x, ga.y, ga.z, ga.w}, wb[4] = {gb.x, gb.y, gb.z, gb.w};
; #pragma unroll
;                     for (int p = 0; p < 4; ++p) { const float rl = bf_lo(wa[p]) * __builtin_amdgcn_rcpf(fmaxf(bf_lo(wb[p]), 1e-20f)), rh = bf_hi(wa[p]) * __builtin_amdgcn_rcpf(fmaxf(bf_hi(wb[p]), 1e-20f));
;                         acc[ai][bj][m][p >> 1][(p & 1) * 2] *= rl; acc[ai][bj][m][p >> 1][(p & 1) * 2 + 1] *= rh; } }
	v_lshlrev_b32_e32 v132, 16, v146
	v_max_f32_e32 v132, v132, v132
	v_max_f32_e32 v132, 0x1e3ce508, v132
	v_rcp_f32_e32 v138, v132
	v_and_b32_e32 v132, 0xffff0000, v146
	v_max_f32_e32 v132, v132, v132
	v_max_f32_e32 v132, 0x1e3ce508, v132
	v_rcp_f32_e32 v139, v132
	v_pk_mul_f32 v[132:133], v[16:17], v[14:15]
	v_lshlrev_b32_e32 v16, 16, v147
	v_and_b32_e32 v17, 0xffff0000, v147
	v_max_f32_e32 v16, v16, v16
	v_max_f32_e32 v17, v17, v17
	v_max_f32_e32 v16, 0x1e3ce508, v16
	v_max_f32_e32 v17, 0x1e3ce508, v17
	v_rcp_f32_e32 v16, v16
	v_rcp_f32_e32 v17, v17
	s_waitcnt vmcnt(2)
	v_lshlrev_b32_e32 v14, 16, v150
	v_and_b32_e32 v15, 0xffff0000, v150
	v_pk_mul_f32 v[14:15], v[138:139], v[14:15]
	s_mul_i32 s0, s50, s2
	v_pk_mul_f32 v[14:15], v[18:19], v[14:15]
	v_lshlrev_b32_e32 v18, 16, v151
	v_and_b32_e32 v19, 0xffff0000, v151
	v_pk_mul_f32 v[16:17], v[16:17], v[18:19]
	v_lshlrev_b32_e32 v18, 16, v148
	v_and_b32_e32 v19, 0xffff0000, v148
	v_max_f32_e32 v18, v18, v18
	v_max_f32_e32 v19, v19, v19
	v_max_f32_e32 v18, 0x1e3ce508, v18
	v_max_f32_e32 v19, 0x1e3ce508, v19
	v_rcp_f32_e32 v18, v18
	v_rcp_f32_e32 v19, v19
	v_pk_mul_f32 v[16:17], v[20:21], v[16:17]
	v_lshlrev_b32_e32 v20, 16, v152
	v_and_b32_e32 v21, 0xffff0000, v152
	v_pk_mul_f32 v[18:19], v[18:19], v[20:21]
	v_lshlrev_b32_e32 v20, 16, v149
	v_and_b32_e32 v21, 0xffff0000, v149
	v_max_f32_e32 v20, v20, v20
	v_max_f32_e32 v21, v21, v21
	v_max_f32_e32 v20, 0x1e3ce508, v20
	v_max_f32_e32 v21, 0x1e3ce508, v21
	v_rcp_f32_e32 v20, v20
	v_rcp_f32_e32 v21, v21
	v_pk_mul_f32 v[10:11], v[10:11], v[18:19]
	v_lshlrev_b32_e32 v18, 16, v153
	v_and_b32_e32 v19, 0xffff0000, v153
	v_pk_mul_f32 v[18:19], v[20:21], v[18:19]
	s_waitcnt vmcnt(1)
	v_lshlrev_b32_e32 v20, 16, v142
	v_and_b32_e32 v21, 0xffff0000, v142
	v_max_f32_e32 v20, v20, v20
	v_max_f32_e32 v21, v21, v21
	v_max_f32_e32 v20, 0x1e3ce508, v20
	v_max_f32_e32 v21, 0x1e3ce508, v21
	v_rcp_f32_e32 v20, v20
	v_rcp_f32_e32 v21, v21
	v_pk_mul_f32 v[12:13], v[12:13], v[18:19]
	s_waitcnt vmcnt(0)
	v_lshlrev_b32_e32 v18, 16, v134
	v_and_b32_e32 v19, 0xffff0000, v134
	v_pk_mul_f32 v[18:19], v[20:21], v[18:19]
	v_lshlrev_b32_e32 v20, 16, v143
	v_and_b32_e32 v21, 0xffff0000, v143
	v_max_f32_e32 v20, v20, v20
	v_max_f32_e32 v21, v21, v21
	v_max_f32_e32 v20, 0x1e3ce508, v20
	v_max_f32_e32 v21, 0x1e3ce508, v21
	v_rcp_f32_e32 v20, v20
	v_rcp_f32_e32 v21, v21
	v_pk_mul_f32 v[6:7], v[6:7], v[18:19]
	v_lshlrev_b32_e32 v18, 16, v135
	v_and_b32_e32 v19, 0xffff0000, v135
	v_pk_mul_f32 v[18:19], v[20:21], v[18:19]
	v_lshlrev_b32_e32 v20, 16, v144
	v_and_b32_e32 v21, 0xffff0000, v144
	v_max_f32_e32 v20, v20, v20
	v_max_f32_e32 v21, v21, v21
	v_max_f32_e32 v20, 0x1e3ce508, v20
	v_max_f32_e32 v21, 0x1e3ce508, v21
	v_rcp_f32_e32 v20, v20
	v_rcp_f32_e32 v21, v21
	v_pk_mul_f32 v[8:9], v[8:9], v[18:19]
	v_lshlrev_b32_e32 v18, 16, v136
	v_and_b32_e32 v19, 0xffff0000, v136
	v_pk_mul_f32 v[18:19], v[20:21], v[18:19]
	v_lshlrev_b32_e32 v20, 16, v145
	v_and_b32_e32 v21, 0xffff0000, v145
	v_max_f32_e32 v20, v20, v20
	v_max_f32_e32 v21, v21, v21
	v_max_f32_e32 v20, 0x1e3ce508, v20
	v_max_f32_e32 v21, 0x1e3ce508, v21
	v_rcp_f32_e32 v20, v20
	v_rcp_f32_e32 v21, v21
	v_pk_mul_f32 v[2:3], v[2:3], v[18:19]
	v_lshlrev_b32_e32 v18, 16, v137
	v_and_b32_e32 v19, 0xffff0000, v137
	v_pk_mul_f32 v[18:19], v[20:21], v[18:19]
	v_readlane_b32 s2, v238, 44
	v_pk_mul_f32 v[4:5], v[4:5], v[18:19]
	s_add_u32 s2, s0, s2
	s_addc_u32 s3, s1, s28
	v_cmp_gt_i64_e32 vcc, s[2:3], v[160:161]
	v_cmp_lt_i64_e64 s[0:1], s[2:3], v[158:159]
	s_cbranch_vccnz .LBB0_753
	s_ashr_i32 s3, s2, 31
	s_lshr_b32 s3, s3, 29
	s_add_i32 s4, s2, s3
	s_and_b32 s3, s4, -8
	s_sub_i32 s5, s2, s3
	s_cmp_gt_i32 s5, -1
	s_mov_b64 s[2:3], -1
	s_cbranch_scc0 .LBB0_750
	s_lshl_b32 s16, s5, 6
	s_mov_b64 s[2:3], 0

;     __device__ bool next(int i, Unit& u) const { if (i > 1) return false; const int xcd = c & 7, idx = c >> 3; u.pm = 16 * i + 4 * (xcd >> 1) + (idx & 3); u.pn = 8 * (xcd & 1) + (idx >> 2); return true; }
; template <class Epi, class Sched>
; __device__ __forceinline__ void gemm_phase_dual(PG8_LAS unsigned char* lds, const Gemm g  , const bf16_t* A0, const bf16_t* Bt0, int K0, const Sched& S, const Epi& E) {
;     ...
;         const bool has_next = S.next(ui + 1, nxt);
;         const char* nA = has_next ? (const char*)A0 + (size_t)nxt.pm * tstep : mA; const char* nB = has_next ? (const char*)Bt0 + (size_t)nxt.pn * tstep : mB;
;         PG8_KLOOP(nt1, mA, mB, nA, nB)
.LBB0_753:
	s_ashr_i32 s5, s4, 31
	s_lshl_b64 s[38:39], s[4:5], 21
	s_add_u32 s16, s29, s38
	s_addc_u32 s5, s42, s39
	s_and_b64 s[2:3], s[0:1], exec
	s_cselect_b32 s5, s5, s31
	s_cselect_b32 s33, s16, s30
	s_ashr_i32 s21, s20, 31
	s_lshl_b64 s[40:41], s[20:21], 21
	s_add_u32 s16, s43, s40
	s_addc_u32 s17, s44, s41
	s_and_b64 s[2:3], s[0:1], exec
	s_cselect_b32 s21, s17, s79
	s_cselect_b32 s36, s16, s78
	s_add_u32 s34, s70, s34
	s_addc_u32 s35, s71, s35
	s_mov_b32 s37, -2
	s_nop 0
.LBB0_754:
	ds_read_b128 v[18:21], v172
	ds_read_b128 v[134:137], v172 offset:1024
	ds_read_b128 v[138:141], v172 offset:2048
	ds_read_b128 v[142:145], v172 offset:3072
	ds_read_b128 v[146:149], v173
	ds_read_b128 v[150:153], v173 offset:1024
	ds_read_b128 v[154:157], v173 offset:2048
	ds_read_b128 v[178:181], v173 offset:3072
	s_add_u32 s2, s30, 0x100
	s_addc_u32 s3, s31, 0
	s_cmp_eq_u32 s37, 60
	s_cselect_b32 s26, s33, s2
	s_cselect_b32 s27, s5, s3
	s_cselect_b32 s24, s36, s34
	s_cselect_b32 s25, s21, s35
	s_add_u32 s16, s26, 0x80
	s_addc_u32 s17, s27, 0
	s_add_u32 s30, s30, 0x100080
	s_addc_u32 s31, s31, 0
	s_mov_b32 m0, s76
	ds_read_b128 v[182:185], v174
	ds_read_b128 v[186:189], v174 offset:1024
	ds_read_b128 v[190:193], v174 offset:2048
	ds_read_b128 v[194:197], v174 offset:3072
	ds_read_b128 v[198:201], v174 offset:4096
	ds_read_b128 v[202:205], v174 offset:5120
	ds_read_b128 v[206:209], v174 offset:6144
	ds_read_b128 v[210:213], v174 offset:7168
	s_nop 0
	global_load_lds_dwordx4 v1, s[30:31]
	s_mov_b32 m0, s77
	s_nop 0
	global_load_lds_dwordx4 v165, s[30:31]
	s_waitcnt vmcnt(8)
	s_waitcnt lgkmcnt(0)
	s_setprio 1
	s_waitcnt lgkmcnt(0)
	s_barrier
	v_mfma_f32_16x16x32_bf16 v[34:37], v[18:21], v[182:185], v[34:37]
	v_mfma_f32_16x16x32_bf16 v[30:33], v[138:141], v[182:185], v[30:33]
	v_mfma_f32_16x16x32_bf16 v[46:49], v[18:21], v[190:193], v[46:49]
	v_mfma_f32_16x16x32_bf16 v[62:65], v[138:141], v[190:193], v[62:65]
	v_mfma_f32_16x16x32_bf16 v[78:81], v[18:21], v[198:201], v[78:81]
	v_mfma_f32_16x16x32_bf16 v[90:93], v[138:141], v[198:201], v[90:93]
	v_mfma_f32_16x16x32_bf16 v[106:109], v[18:21], v[206:209], v[106:109]
	v_mfma_f32_16x16x32_bf16 v[114:117], v[138:141], v[206:209], v[114:117]
	v_mfma_f32_16x16x32_bf16 v[26:29], v[146:149], v[182:185], v[26:29]
	v_mfma_f32_16x16x32_bf16 v[50:53], v[154:157], v[182:185], v[50:53]
	v_mfma_f32_16x16x32_bf16 v[58:61], v[146:149], v[190:193], v[58:61]
	v_mfma_f32_16x16x32_bf16 v[82:85], v[154:157], v[190:193], v[82:85]
	v_mfma_f32_16x16x32_bf16 v[110:113], v[146:149], v[198:201], v[110:113]
	v_mfma_f32_16x16x32_bf16 v[118:121], v[154:157], v[198:201], v[118:121]
	v_mfma_f32_16x16x32_bf16 v[122:125], v[146:149], v[206:209], v[122:125]
	v_mfma_f32_16x16x32_bf16 v[126:129], v[154:157], v[206:209], v[126:129]
	v_mfma_f32_16x16x32_bf16 v[34:37], v[134:137], v[186:189], v[34:37]
	v_mfma_f32_16x16x32_bf16 v[30:33], v[142:145], v[186:189], v[30:33]
	v_mfma_f32_16x16x32_bf16 v[46:49], v[134:137], v[194:197], v[46:49]
	v_mfma_f32_16x16x32_bf16 v[62:65], v[142:145], v[194:197], v[62:65]
	v_mfma_f32_16x16x32_bf16 v[78:81], v[134:137], v[202:205], v[78:81]
	v_mfma_f32_16x16x32_bf16 v[90:93], v[142:145], v[202:205], v[90:93]
	v_mfma_f32_16x16x32_bf16 v[106:109], v[134:137], v[210:213], v[106:109]
	v_mfma_f32_16x16x32_bf16 v[114:117], v[142:145], v[210:213], v[114:117]
	v_mfma_f32_16x16x32_bf16 v[26:29], v[150:153], v[186:189], v[26:29]
	v_mfma_f32_16x16x32_bf16 v[50:53], v[178:181], v[186:189], v[50:53]
	v_mfma_f32_16x16x32_bf16 v[58:61], v[150:153], v[194:197], v[58:61]
	v_mfma_f32_16x16x32_bf16 v[82:85], v[178:181], v[194:197], v[82:85]
	v_mfma_f32_16x16x32_bf16 v[110:113], v[150:153], v[202:205], v[110:113]
	v_mfma_f32_16x16x32_bf16 v[118:121], v[178:181], v[202:205], v[118:121]
	v_mfma_f32_16x16x32_bf16 v[122:125], v[150:153], v[210:213], v[122:125]
	v_mfma_f32_16x16x32_bf16 v[126:129], v[178:181], v[210:213], v[126:129]
	s_setprio 0
	s_barrier
	s_mov_b32 m0, s80
	s_mov_b64 s[30:31], s[24:25]
	ds_read_b128 v[182:185], v174 offset:16384
	ds_read_b128 v[186:189], v174 offset:17408
	ds_read_b128 v[190:193], v174 offset:18432
	ds_read_b128 v[194:197], v174 offset:19456
	ds_read_b128 v[198:201], v174 offset:20480
	ds_read_b128 v[202:205], v174 offset:21504
	ds_read_b128 v[206:209], v174 offset:22528
	ds_read_b128 v[210:213], v174 offset:23552
	s_nop 0
	global_load_lds_dwordx4 v164, s[30:31]
	s_mov_b32 m0, s81
	s_nop 0
	global_load_lds_dwordx4 v166, s[30:31]
	s_add_u32 s30, s24, 0x100000
	s_addc_u32 s31, s25, 0
	s_mov_b32 m0, s82
	s_nop 0
	global_load_lds_dwordx4 v164, s[30:31]
	s_mov_b32 m0, s83
	s_nop 0
	global_load_lds_dwordx4 v166, s[30:31]
	s_mov_b64 s[30:31], s[26:27]
	s_mov_b32 m0, s46
	s_nop 0
	global_load_lds_dwordx4 v1, s[30:31]
	s_mov_b32 m0, s47
	s_nop 0
	global_load_lds_dwordx4 v165, s[30:31]
	s_waitcnt vmcnt(8)
	s_waitcnt lgkmcnt(0)
	s_setprio 1
	s_waitcnt lgkmcnt(0)
	s_barrier
	v_mfma_f32_16x16x32_bf16 v[102:105], v[18:21], v[182:185], v[102:105]
	v_mfma_f32_16x16x32_bf16 v[98:101], v[138:141], v[182:185], v[98:101]
	v_mfma_f32_16x16x32_bf16 v[74:77], v[18:21], v[190:193], v[74:77]
	v_mfma_f32_16x16x32_bf16 v[70:73], v[138:141], v[190:193], v[70:73]
	v_mfma_f32_16x16x32_bf16 v[42:45], v[18:21], v[198:201], v[42:45]
	v_mfma_f32_16x16x32_bf16 v[38:41], v[138:141], v[198:201], v[38:41]
	v_mfma_f32_16x16x32_bf16 v[14:17], v[18:21], v[206:209], v[14:17]
	v_mfma_f32_16x16x32_bf16 v[10:13], v[138:141], v[206:209], v[10:13]
	v_mfma_f32_16x16x32_bf16 v[18:21], v[146:149], v[182:185], v[94:97]
	v_mfma_f32_16x16x32_bf16 v[86:89], v[154:157], v[182:185], v[86:89]
	v_mfma_f32_16x16x32_bf16 v[66:69], v[146:149], v[190:193], v[66:69]
	v_mfma_f32_16x16x32_bf16 v[54:57], v[154:157], v[190:193], v[54:57]
	v_mfma_f32_16x16x32_bf16 v[22:25], v[146:149], v[198:201], v[22:25]
	v_mfma_f32_16x16x32_bf16 v[94:97], v[154:157], v[198:201], v[130:133]
	v_mfma_f32_16x16x32_bf16 v[6:9], v[146:149], v[206:209], v[6:9]
	v_mfma_f32_16x16x32_bf16 v[2:5], v[154:157], v[206:209], v[2:5]
	v_mfma_f32_16x16x32_bf16 v[102:105], v[134:137], v[186:189], v[102:105]
	v_mfma_f32_16x16x32_bf16 v[98:101], v[142:145], v[186:189], v[98:101]
	v_mfma_f32_16x16x32_bf16 v[74:77], v[134:137], v[194:197], v[74:77]
	v_mfma_f32_16x16x32_bf16 v[70:73], v[142:145], v[194:197], v[70:73]
	v_mfma_f32_16x16x32_bf16 v[42:45], v[134:137], v[202:205], v[42:45]
	v_mfma_f32_16x16x32_bf16 v[38:41], v[142:145], v[202:205], v[38:41]
	v_mfma_f32_16x16x32_bf16 v[14:17], v[134:137], v[210:213], v[14:17]
	v_mfma_f32_16x16x32_bf16 v[10:13], v[142:145], v[210:213], v[10:13]
	v_mfma_f32_16x16x32_bf16 v[86:89], v[178:181], v[186:189], v[86:89]
	v_mfma_f32_16x16x32_bf16 v[66:69], v[150:153], v[194:197], v[66:69]
	v_mfma_f32_16x16x32_bf16 v[54:57], v[178:181], v[194:197], v[54:57]
	v_mfma_f32_16x16x32_bf16 v[22:25], v[150:153], v[202:205], v[22:25]
	v_mfma_f32_16x16x32_bf16 v[130:133], v[178:181], v[202:205], v[94:97]
	v_mfma_f32_16x16x32_bf16 v[6:9], v[150:153], v[210:213], v[6:9]
	v_mfma_f32_16x16x32_bf16 v[2:5], v[178:181], v[210:213], v[2:5]
	v_mfma_f32_16x16x32_bf16 v[18:21], v[150:153], v[186:189], v[18:21]
	s_setprio 0
	s_barrier
	ds_read_b128 v[94:97], v175
	ds_read_b128 v[134:137], v175 offset:1024
	ds_read_b128 v[138:141], v175 offset:2048
	ds_read_b128 v[142:145], v175 offset:3072
	ds_read_b128 v[146:149], v176
	ds_read_b128 v[150:153], v176 offset:1024
	ds_read_b128 v[154:157], v176 offset:2048
	ds_read_b128 v[178:181], v176 offset:3072
	s_add_u32 s26, s26, 0x100000
	s_addc_u32 s27, s27, 0
	s_mov_b32 m0, s48
	ds_read_b128 v[182:185], v174 offset:32768
	ds_read_b128 v[186:189], v174 offset:33792
	ds_read_b128 v[190:193], v174 offset:34816
	ds_read_b128 v[194:197], v174 offset:35840
	ds_read_b128 v[198:201], v174 offset:36864
	ds_read_b128 v[202:205], v174 offset:37888
	ds_read_b128 v[206:209], v174 offset:38912
	ds_read_b128 v[210:213], v174 offset:39936
	s_nop 0
	global_load_lds_dwordx4 v1, s[26:27]
	s_mov_b32 m0, s49
	s_nop 0
	global_load_lds_dwordx4 v165, s[26:27]
	s_waitcnt vmcnt(8)
	s_waitcnt lgkmcnt(0)
	s_setprio 1
	s_waitcnt lgkmcnt(0)
	s_barrier
	v_mfma_f32_16x16x32_bf16 v[34:37], v[94:97], v[182:185], v[34:37]
	v_mfma_f32_16x16x32_bf16 v[30:33], v[138:141], v[182:185], v[30:33]
	v_mfma_f32_16x16x32_bf16 v[46:49], v[94:97], v[190:193], v[46:49]
	v_mfma_f32_16x16x32_bf16 v[62:65], v[138:141], v[190:193], v[62:65]
	v_mfma_f32_16x16x32_bf16 v[78:81], v[94:97], v[198:201], v[78:81]
	v_mfma_f32_16x16x32_bf16 v[90:93], v[138:141], v[198:201], v[90:93]
	v_mfma_f32_16x16x32_bf16 v[106:109], v[94:97], v[206:209], v[106:109]
	v_mfma_f32_16x16x32_bf16 v[114:117], v[138:141], v[206:209], v[114:117]
	v_mfma_f32_16x16x32_bf16 v[26:29], v[146:149], v[182:185], v[26:29]
	v_mfma_f32_16x16x32_bf16 v[50:53], v[154:157], v[182:185], v[50:53]
	v_mfma_f32_16x16x32_bf16 v[58:61], v[146:149], v[190:193], v[58:61]
	v_mfma_f32_16x16x32_bf16 v[82:85], v[154:157], v[190:193], v[82:85]
	v_mfma_f32_16x16x32_bf16 v[110:113], v[146:149], v[198:201], v[110:113]
	v_mfma_f32_16x16x32_bf16 v[118:121], v[154:157], v[198:201], v[118:121]
	v_mfma_f32_16x16x32_bf16 v[122:125], v[146:149], v[206:209], v[122:125]
	v_mfma_f32_16x16x32_bf16 v[126:129], v[154:157], v[206:209], v[126:129]
	v_mfma_f32_16x16x32_bf16 v[34:37], v[134:137], v[186:189], v[34:37]
	v_mfma_f32_16x16x32_bf16 v[30:33], v[142:145], v[186:189], v[30:33]
	v_mfma_f32_16x16x32_bf16 v[46:49], v[134:137], v[194:197], v[46:49]
	v_mfma_f32_16x16x32_bf16 v[62:65], v[142:145], v[194:197], v[62:65]
	v_mfma_f32_16x16x32_bf16 v[78:81], v[134:137], v[202:205], v[78:81]
	v_mfma_f32_16x16x32_bf16 v[90:93], v[142:145], v[202:205], v[90:93]
	v_mfma_f32_16x16x32_bf16 v[106:109], v[134:137], v[210:213], v[106:109]
	v_mfma_f32_16x16x32_bf16 v[114:117], v[142:145], v[210:213], v[114:117]
	v_mfma_f32_16x16x32_bf16 v[26:29], v[150:153], v[186:189], v[26:29]
	v_mfma_f32_16x16x32_bf16 v[50:53], v[178:181], v[186:189], v[50:53]
	v_mfma_f32_16x16x32_bf16 v[58:61], v[150:153], v[194:197], v[58:61]
	v_mfma_f32_16x16x32_bf16 v[82:85], v[178:181], v[194:197], v[82:85]
	v_mfma_f32_16x16x32_bf16 v[110:113], v[150:153], v[202:205], v[110:113]
	v_mfma_f32_16x16x32_bf16 v[118:121], v[178:181], v[202:205], v[118:121]
	v_mfma_f32_16x16x32_bf16 v[122:125], v[150:153], v[210:213], v[122:125]
	v_mfma_f32_16x16x32_bf16 v[126:129], v[178:181], v[210:213], v[126:129]
	s_setprio 0
	s_barrier
; #define PG8_BAR __builtin_amdgcn_s_barrier()
; #define PG8_BAR __builtin_amdgcn_s_barrier()
; template <class Epi, class Sched>
; __device__ __forceinline__ void gemm_phase_dual(PG8_LAS unsigned char* lds, const Gemm g  , const bf16_t* A0, const bf16_t* Bt0, int K0, const Sched& S, const Epi& E) {
;     ...
;         if (wr == 0) PG8_BAR;
	s_nop 0
	s_add_u32 s26, s24, 0x80
	s_mov_b32 m0, s84
	s_addc_u32 s27, s25, 0
	ds_read_b128 v[182:185], v174 offset:49152
	ds_read_b128 v[186:189], v174 offset:50176
	ds_read_b128 v[190:193], v174 offset:51200
	ds_read_b128 v[194:197], v174 offset:52224
	ds_read_b128 v[198:201], v174 offset:53248
	ds_read_b128 v[202:205], v174 offset:54272
	ds_read_b128 v[206:209], v174 offset:55296
	ds_read_b128 v[210:213], v174 offset:56320
	s_add_u32 s24, s24, 0x100080
	global_load_lds_dwordx4 v164, s[26:27]
	s_mov_b32 m0, s85
	s_addc_u32 s25, s25, 0
	global_load_lds_dwordx4 v166, s[26:27]
	s_mov_b32 m0, s86
	s_nop 0
	global_load_lds_dwordx4 v164, s[24:25]
	s_mov_b32 m0, s87
	s_nop 0
	global_load_lds_dwordx4 v166, s[24:25]
	s_mov_b32 m0, s57
	s_nop 0
	global_load_lds_dwordx4 v1, s[16:17]
	s_mov_b32 m0, s62
	s_nop 0
	global_load_lds_dwordx4 v165, s[16:17]
	s_waitcnt vmcnt(8)
	s_waitcnt lgkmcnt(0)
	s_setprio 1
	s_waitcnt lgkmcnt(0)
	s_barrier
	v_mfma_f32_16x16x32_bf16 v[18:21], v[146:149], v[182:185], v[18:21]
	v_mfma_f32_16x16x32_bf16 v[102:105], v[94:97], v[182:185], v[102:105]
	v_mfma_f32_16x16x32_bf16 v[74:77], v[94:97], v[190:193], v[74:77]
	v_mfma_f32_16x16x32_bf16 v[42:45], v[94:97], v[198:201], v[42:45]
	v_mfma_f32_16x16x32_bf16 v[14:17], v[94:97], v[206:209], v[14:17]
	v_mfma_f32_16x16x32_bf16 v[94:97], v[150:153], v[186:189], v[18:21]
	v_mfma_f32_16x16x32_bf16 v[18:21], v[154:157], v[182:185], v[86:89]
	v_mfma_f32_16x16x32_bf16 v[86:89], v[178:181], v[186:189], v[18:21]
	v_mfma_f32_16x16x32_bf16 v[18:21], v[146:149], v[190:193], v[66:69]
	v_mfma_f32_16x16x32_bf16 v[66:69], v[150:153], v[194:197], v[18:21]
	v_mfma_f32_16x16x32_bf16 v[18:21], v[154:157], v[190:193], v[54:57]
	v_mfma_f32_16x16x32_bf16 v[54:57], v[178:181], v[194:197], v[18:21]
	v_mfma_f32_16x16x32_bf16 v[18:21], v[146:149], v[198:201], v[22:25]
	v_mfma_f32_16x16x32_bf16 v[98:101], v[138:141], v[182:185], v[98:101]
	v_mfma_f32_16x16x32_bf16 v[70:73], v[138:141], v[190:193], v[70:73]
	v_mfma_f32_16x16x32_bf16 v[38:41], v[138:141], v[198:201], v[38:41]
	v_mfma_f32_16x16x32_bf16 v[10:13], v[138:141], v[206:209], v[10:13]
	v_mfma_f32_16x16x32_bf16 v[22:25], v[150:153], v[202:205], v[18:21]
	v_mfma_f32_16x16x32_bf16 v[18:21], v[154:157], v[198:201], v[130:133]
	v_mfma_f32_16x16x32_bf16 v[6:9], v[146:149], v[206:209], v[6:9]
	v_mfma_f32_16x16x32_bf16 v[2:5], v[154:157], v[206:209], v[2:5]
	v_mfma_f32_16x16x32_bf16 v[102:105], v[134:137], v[186:189], v[102:105]
	v_mfma_f32_16x16x32_bf16 v[98:101], v[142:145], v[186:189], v[98:101]
	v_mfma_f32_16x16x32_bf16 v[74:77], v[134:137], v[194:197], v[74:77]
	v_mfma_f32_16x16x32_bf16 v[70:73], v[142:145], v[194:197], v[70:73]
	v_mfma_f32_16x16x32_bf16 v[42:45], v[134:137], v[202:205], v[42:45]
	v_mfma_f32_16x16x32_bf16 v[38:41], v[142:145], v[202:205], v[38:41]
	v_mfma_f32_16x16x32_bf16 v[14:17], v[134:137], v[210:213], v[14:17]
	v_mfma_f32_16x16x32_bf16 v[10:13], v[142:145], v[210:213], v[10:13]
	v_mfma_f32_16x16x32_bf16 v[130:133], v[178:181], v[202:205], v[18:21]
	v_mfma_f32_16x16x32_bf16 v[6:9], v[150:153], v[210:213], v[6:9]
	v_mfma_f32_16x16x32_bf16 v[2:5], v[178:181], v[210:213], v[2:5]
	s_setprio 0
	s_barrier
	s_add_i32 s37, s37, 2
	s_add_u32 s34, s34, 0x100
	s_addc_u32 s35, s35, 0
	s_cmp_gt_u32 s37, 61
	s_mov_b64 s[30:31], s[2:3]
	s_cbranch_scc0 .LBB0_754
	s_and_b64 vcc, exec, s[18:19]
	s_cbranch_vccz .LBB0_757
	s_barrier

; #define PG8_STAGE(bufoff, gbase, voff) do { const char* _gb = (const char*)(gbase); asm volatile("" : "+s"(_gb)); _Pragma("unroll") for (int _i = 0; _i < 2; ++_i) { asm volatile("" : "+v"((voff)[_i])); \
;         __builtin_amdgcn_global_load_lds((const unsigned*)(_gb + (voff)[_i]), (PG8_LAS unsigned*)(lds + (bufoff) + ldsw + _i * 8192), 16, 0, 0); } } while (0)
; #define PG8_LDA(dst, b, h) do { _Pragma("unroll") for (int m = 0; m < 4; ++m) _Pragma("unroll") for (int k = 0; k < 2; ++k) dst[m][k] = *(const PG8_LAS bf16x8*)(lds + PG8_SA(b, h) + aoff + m * 2048 + k * 1024); } while (0)
; #define PG8_LDB(dst, b, h) do { _Pragma("unroll") for (int n = 0; n < 2; ++n) _Pragma("unroll") for (int k = 0; k < 2; ++k) dst[n][k] = *(const PG8_LAS bf16x8*)(lds + PG8_SB(b, h) + boff + n * 2048 + k * 1024); } while (0)
; #define PG8_WAIT_V(n) asm volatile("s_waitcnt vmcnt(" #n ")" ::: "memory")
; #define PG8_WAIT_L(n) asm volatile("s_waitcnt lgkmcnt(" #n ")" ::: "memory")
; #define PG8_BAR __builtin_amdgcn_s_barrier()
; #define PG8_SCHED __builtin_amdgcn_sched_barrier(0)
; #define PG8_STAGE(bufoff, gbase, voff) do { const char* _gb = (const char*)(gbase); asm volatile("" : "+s"(_gb)); _Pragma("unroll") for (int _i = 0; _i < 2; ++_i) { asm volatile("" : "+v"((voff)[_i])); \
;         __builtin_amdgcn_global_load_lds((const unsigned*)(_gb + (voff)[_i]), (PG8_LAS unsigned*)(lds + (bufoff) + ldsw + _i * 8192), 16, 0, 0); } } while (0)
; #define PG8_LDA(dst, b, h) do { _Pragma("unroll") for (int m = 0; m < 4; ++m) _Pragma("unroll") for (int k = 0; k < 2; ++k) dst[m][k] = *(const PG8_LAS bf16x8*)(lds + PG8_SA(b, h) + aoff + m * 2048 + k * 1024); } while (0)
; #define PG8_BAR __builtin_amdgcn_s_barrier()
; template <class Epi, class Sched, bool ALIGN_EPI = false, bool SP2 = false>
; __device__ __forceinline__ void gemm_phase(PG8_LAS unsigned char* lds, const Gemm g, const Sched& S, const Epi& E) {
;     ...
;             if constexpr (SP2) {
;             PG8_LDB(B0, 0, 0); PG8_LDB(B1, 0, 1); PG8_SCHED; PG8_LDA(At, 0, 0); PG8_STAGE(PG8_SA(1, 1), a1 + hstep, voffA);
;             PG8_WAIT_V(8); PG8_WAIT_L(0); PG8_BAR; PG8_MMA2(0); PG8_BAR; PG8_SCHED;
;             PG8_LDA(At, 0, 1); PG8_STAGE(PG8_SB(0, 0), b2, voffB); PG8_STAGE(PG8_SB(0, 1), b2 + hstep, voffB); PG8_STAGE(PG8_SA(0, 0), a2, voffA);
;             PG8_WAIT_V(8); PG8_WAIT_L(0); PG8_BAR; PG8_MMA2(1); PG8_BAR; PG8_SCHED;
.LBB0_833:
	ds_read_b128 v[130:133], v180
	ds_read_b128 v[134:137], v180 offset:1024
	ds_read_b128 v[138:141], v180 offset:2048
	ds_read_b128 v[142:145], v180 offset:3072
	ds_read_b128 v[146:149], v181
	ds_read_b128 v[150:153], v181 offset:1024
	ds_read_b128 v[154:157], v181 offset:2048
	ds_read_b128 v[158:161], v181 offset:3072
	s_add_u32 s24, s16, 0x100
	s_addc_u32 s25, s17, 0
	s_cmp_eq_u32 s87, 60
	s_cselect_b32 s28, s83, s24
	s_cselect_b32 s29, s55, s25
	s_cselect_b32 s26, s84, s85
	s_cselect_b32 s27, s53, s86
	s_add_u32 s2, s28, 0x80
	s_addc_u32 s3, s29, 0
	s_add_u32 s16, s16, 0x100080
	s_addc_u32 s17, s17, 0
	s_add_i32 m0, s69, 0xc000
	ds_read_b128 v[166:169], v182
	ds_read_b128 v[170:173], v182 offset:1024
	ds_read_b128 v[184:187], v182 offset:2048
	ds_read_b128 v[188:191], v182 offset:3072
	ds_read_b128 v[192:195], v182 offset:4096
	ds_read_b128 v[196:199], v182 offset:5120
	ds_read_b128 v[200:203], v182 offset:6144
	ds_read_b128 v[204:207], v182 offset:7168
	s_nop 0
	global_load_lds_dwordx4 v1, s[16:17]
	s_add_i32 m0, s69, 0xe000
	s_nop 0
	global_load_lds_dwordx4 v175, s[16:17]
	s_waitcnt vmcnt(8)
	s_waitcnt lgkmcnt(0)
	s_setprio 1
	s_waitcnt lgkmcnt(0)
	s_barrier
	v_mfma_f32_16x16x32_bf16 v[126:129], v[130:133], v[166:169], v[126:129]
	v_mfma_f32_16x16x32_bf16 v[122:125], v[138:141], v[166:169], v[122:125]
	v_mfma_f32_16x16x32_bf16 v[110:113], v[130:133], v[184:187], v[110:113]
	v_mfma_f32_16x16x32_bf16 v[106:109], v[138:141], v[184:187], v[106:109]
	v_mfma_f32_16x16x32_bf16 v[94:97], v[130:133], v[192:195], v[94:97]
	v_mfma_f32_16x16x32_bf16 v[90:93], v[138:141], v[192:195], v[90:93]
	v_mfma_f32_16x16x32_bf16 v[78:81], v[130:133], v[200:203], v[78:81]
	v_mfma_f32_16x16x32_bf16 v[74:77], v[138:141], v[200:203], v[74:77]
	v_mfma_f32_16x16x32_bf16 v[118:121], v[146:149], v[166:169], v[118:121]
	v_mfma_f32_16x16x32_bf16 v[114:117], v[154:157], v[166:169], v[114:117]
	v_mfma_f32_16x16x32_bf16 v[102:105], v[146:149], v[184:187], v[102:105]
	v_mfma_f32_16x16x32_bf16 v[98:101], v[154:157], v[184:187], v[98:101]
	v_mfma_f32_16x16x32_bf16 v[86:89], v[146:149], v[192:195], v[86:89]
	v_mfma_f32_16x16x32_bf16 v[82:85], v[154:157], v[192:195], v[82:85]
	v_mfma_f32_16x16x32_bf16 v[70:73], v[146:149], v[200:203], v[70:73]
	v_mfma_f32_16x16x32_bf16 v[66:69], v[154:157], v[200:203], v[66:69]
	v_mfma_f32_16x16x32_bf16 v[126:129], v[134:137], v[170:173], v[126:129]
	v_mfma_f32_16x16x32_bf16 v[122:125], v[142:145], v[170:173], v[122:125]
	v_mfma_f32_16x16x32_bf16 v[110:113], v[134:137], v[188:191], v[110:113]
	v_mfma_f32_16x16x32_bf16 v[106:109], v[142:145], v[188:191], v[106:109]
	v_mfma_f32_16x16x32_bf16 v[94:97], v[134:137], v[196:199], v[94:97]
	v_mfma_f32_16x16x32_bf16 v[90:93], v[142:145], v[196:199], v[90:93]
	v_mfma_f32_16x16x32_bf16 v[78:81], v[134:137], v[204:207], v[78:81]
	v_mfma_f32_16x16x32_bf16 v[74:77], v[142:145], v[204:207], v[74:77]
	v_mfma_f32_16x16x32_bf16 v[118:121], v[150:153], v[170:173], v[118:121]
	v_mfma_f32_16x16x32_bf16 v[114:117], v[158:161], v[170:173], v[114:117]
	v_mfma_f32_16x16x32_bf16 v[102:105], v[150:153], v[188:191], v[102:105]
	v_mfma_f32_16x16x32_bf16 v[98:101], v[158:161], v[188:191], v[98:101]
	v_mfma_f32_16x16x32_bf16 v[86:89], v[150:153], v[196:199], v[86:89]
	v_mfma_f32_16x16x32_bf16 v[82:85], v[158:161], v[196:199], v[82:85]
	v_mfma_f32_16x16x32_bf16 v[70:73], v[150:153], v[204:207], v[70:73]
	v_mfma_f32_16x16x32_bf16 v[66:69], v[158:161], v[204:207], v[66:69]
	s_setprio 0
	s_barrier
	s_add_i32 s88, s81, s73
	s_mov_b64 s[16:17], s[26:27]
	s_mov_b32 m0, s88
	ds_read_b128 v[166:169], v182 offset:16384
	ds_read_b128 v[170:173], v182 offset:17408
	ds_read_b128 v[184:187], v182 offset:18432
	ds_read_b128 v[188:191], v182 offset:19456
	ds_read_b128 v[192:195], v182 offset:20480
	ds_read_b128 v[196:199], v182 offset:21504
	ds_read_b128 v[200:203], v182 offset:22528
	ds_read_b128 v[204:207], v182 offset:23552
	s_nop 0
	global_load_lds_dwordx4 v174, s[16:17]
	s_add_i32 m0, s88, 0x2000
	s_nop 0
	global_load_lds_dwordx4 v176, s[16:17]
	s_add_u32 s16, s26, 0x100000
	s_addc_u32 s17, s27, 0
	s_add_i32 s88, s82, s73
	s_mov_b32 m0, s88
	s_nop 0
	global_load_lds_dwordx4 v174, s[16:17]
	s_add_i32 m0, s88, 0x2000
	s_nop 0
	global_load_lds_dwordx4 v176, s[16:17]
	s_mov_b64 s[16:17], s[28:29]
	s_mov_b32 m0, s69
	s_nop 0
	global_load_lds_dwordx4 v1, s[16:17]
	s_mov_b32 m0, s71
	s_nop 0
	global_load_lds_dwordx4 v175, s[16:17]
	s_waitcnt vmcnt(8)
	s_waitcnt lgkmcnt(0)
	s_setprio 1
	s_waitcnt lgkmcnt(0)
	s_barrier
	v_mfma_f32_16x16x32_bf16 v[62:65], v[130:133], v[166:169], v[62:65]
	v_mfma_f32_16x16x32_bf16 v[58:61], v[138:141], v[166:169], v[58:61]
	v_mfma_f32_16x16x32_bf16 v[46:49], v[130:133], v[184:187], v[46:49]
	v_mfma_f32_16x16x32_bf16 v[42:45], v[138:141], v[184:187], v[42:45]
	v_mfma_f32_16x16x32_bf16 v[30:33], v[130:133], v[192:195], v[30:33]
	v_mfma_f32_16x16x32_bf16 v[26:29], v[138:141], v[192:195], v[26:29]
	v_mfma_f32_16x16x32_bf16 v[14:17], v[130:133], v[200:203], v[14:17]
	v_mfma_f32_16x16x32_bf16 v[10:13], v[138:141], v[200:203], v[10:13]
	v_mfma_f32_16x16x32_bf16 v[54:57], v[146:149], v[166:169], v[54:57]
	v_mfma_f32_16x16x32_bf16 v[50:53], v[154:157], v[166:169], v[50:53]
	v_mfma_f32_16x16x32_bf16 v[38:41], v[146:149], v[184:187], v[38:41]
	v_mfma_f32_16x16x32_bf16 v[34:37], v[154:157], v[184:187], v[34:37]
	v_mfma_f32_16x16x32_bf16 v[22:25], v[146:149], v[192:195], v[22:25]
	v_mfma_f32_16x16x32_bf16 v[18:21], v[154:157], v[192:195], v[18:21]
	v_mfma_f32_16x16x32_bf16 v[6:9], v[146:149], v[200:203], v[6:9]
	v_mfma_f32_16x16x32_bf16 v[2:5], v[154:157], v[200:203], v[2:5]
	v_mfma_f32_16x16x32_bf16 v[62:65], v[134:137], v[170:173], v[62:65]
	v_mfma_f32_16x16x32_bf16 v[58:61], v[142:145], v[170:173], v[58:61]
	v_mfma_f32_16x16x32_bf16 v[46:49], v[134:137], v[188:191], v[46:49]
	v_mfma_f32_16x16x32_bf16 v[42:45], v[142:145], v[188:191], v[42:45]
	v_mfma_f32_16x16x32_bf16 v[30:33], v[134:137], v[196:199], v[30:33]
	v_mfma_f32_16x16x32_bf16 v[26:29], v[142:145], v[196:199], v[26:29]
	v_mfma_f32_16x16x32_bf16 v[14:17], v[134:137], v[204:207], v[14:17]
	v_mfma_f32_16x16x32_bf16 v[10:13], v[142:145], v[204:207], v[10:13]
	v_mfma_f32_16x16x32_bf16 v[54:57], v[150:153], v[170:173], v[54:57]
	v_mfma_f32_16x16x32_bf16 v[50:53], v[158:161], v[170:173], v[50:53]
	v_mfma_f32_16x16x32_bf16 v[38:41], v[150:153], v[188:191], v[38:41]
	v_mfma_f32_16x16x32_bf16 v[34:37], v[158:161], v[188:191], v[34:37]
	v_mfma_f32_16x16x32_bf16 v[22:25], v[150:153], v[196:199], v[22:25]
	v_mfma_f32_16x16x32_bf16 v[18:21], v[158:161], v[196:199], v[18:21]
	v_mfma_f32_16x16x32_bf16 v[6:9], v[150:153], v[204:207], v[6:9]
	v_mfma_f32_16x16x32_bf16 v[2:5], v[158:161], v[204:207], v[2:5]
	s_setprio 0
	s_barrier
; #define PG8_STAGE(bufoff, gbase, voff) do { const char* _gb = (const char*)(gbase); asm volatile("" : "+s"(_gb)); _Pragma("unroll") for (int _i = 0; _i < 2; ++_i) { asm volatile("" : "+v"((voff)[_i])); \
;         __builtin_amdgcn_global_load_lds((const unsigned*)(_gb + (voff)[_i]), (PG8_LAS unsigned*)(lds + (bufoff) + ldsw + _i * 8192), 16, 0, 0); } } while (0)
; #define PG8_LDA(dst, b, h) do { _Pragma("unroll") for (int m = 0; m < 4; ++m) _Pragma("unroll") for (int k = 0; k < 2; ++k) dst[m][k] = *(const PG8_LAS bf16x8*)(lds + PG8_SA(b, h) + aoff + m * 2048 + k * 1024); } while (0)
; #define PG8_LDB(dst, b, h) do { _Pragma("unroll") for (int n = 0; n < 2; ++n) _Pragma("unroll") for (int k = 0; k < 2; ++k) dst[n][k] = *(const PG8_LAS bf16x8*)(lds + PG8_SB(b, h) + boff + n * 2048 + k * 1024); } while (0)
; #define PG8_WAIT_V(n) asm volatile("s_waitcnt vmcnt(" #n ")" ::: "memory")
; #define PG8_WAIT_L(n) asm volatile("s_waitcnt lgkmcnt(" #n ")" ::: "memory")
; #define PG8_BAR __builtin_amdgcn_s_barrier()
; #define PG8_SCHED __builtin_amdgcn_sched_barrier(0)
; #define PG8_STAGE(bufoff, gbase, voff) do { const char* _gb = (const char*)(gbase); asm volatile("" : "+s"(_gb)); _Pragma("unroll") for (int _i = 0; _i < 2; ++_i) { asm volatile("" : "+v"((voff)[_i])); \
;         __builtin_amdgcn_global_load_lds((const unsigned*)(_gb + (voff)[_i]), (PG8_LAS unsigned*)(lds + (bufoff) + ldsw + _i * 8192), 16, 0, 0); } } while (0)
; #define PG8_LDA(dst, b, h) do { _Pragma("unroll") for (int m = 0; m < 4; ++m) _Pragma("unroll") for (int k = 0; k < 2; ++k) dst[m][k] = *(const PG8_LAS bf16x8*)(lds + PG8_SA(b, h) + aoff + m * 2048 + k * 1024); } while (0)
; #define PG8_WAIT_V(n) asm volatile("s_waitcnt vmcnt(" #n ")" ::: "memory")
; template <class Epi, class Sched, bool ALIGN_EPI = false, bool SP2 = false>
; __device__ __forceinline__ void gemm_phase(PG8_LAS unsigned char* lds, const Gemm g, const Sched& S, const Epi& E) {
;     ...
;             PG8_LDB(B0, 1, 0); PG8_LDB(B1, 1, 1); PG8_SCHED; PG8_LDA(At, 1, 0); PG8_STAGE(PG8_SA(0, 1), a2 + hstep, voffA);
;             PG8_WAIT_V(8); PG8_WAIT_L(0); PG8_BAR; PG8_MMA2(0); PG8_BAR; PG8_SCHED;
;             PG8_LDA(At, 1, 1); PG8_STAGE(PG8_SB(1, 0), b3, voffB); PG8_STAGE(PG8_SB(1, 1), b3 + hstep, voffB); PG8_STAGE(PG8_SA(1, 0), a3, voffA);
;             PG8_WAIT_V(8); PG8_WAIT_L(0); PG8_BAR; PG8_MMA2(1); PG8_BAR; PG8_SCHED;
	s_add_i32 s88, 0, 0x18000
	s_add_i32 s89, 0, 0x1c000
	v_add_u32_e32 v142, s88, v178
	v_add_u32_e32 v158, s89, v178
	ds_read_b128 v[130:133], v142
	ds_read_b128 v[134:137], v142 offset:1024
	ds_read_b128 v[138:141], v142 offset:2048
	ds_read_b128 v[142:145], v142 offset:3072
	ds_read_b128 v[146:149], v158
	ds_read_b128 v[150:153], v158 offset:1024
	ds_read_b128 v[154:157], v158 offset:2048
	ds_read_b128 v[158:161], v158 offset:3072
	s_add_u32 s16, s28, 0x100000
	s_addc_u32 s17, s29, 0
	s_mov_b32 m0, s74
	ds_read_b128 v[166:169], v182 offset:32768
	ds_read_b128 v[170:173], v182 offset:33792
	ds_read_b128 v[184:187], v182 offset:34816
	ds_read_b128 v[188:191], v182 offset:35840
	ds_read_b128 v[192:195], v182 offset:36864
	ds_read_b128 v[196:199], v182 offset:37888
	ds_read_b128 v[200:203], v182 offset:38912
	ds_read_b128 v[204:207], v182 offset:39936
	s_nop 0
	global_load_lds_dwordx4 v1, s[16:17]
	s_mov_b32 m0, s75
	s_nop 0
	global_load_lds_dwordx4 v175, s[16:17]
	s_waitcnt vmcnt(8)
	s_waitcnt lgkmcnt(0)
	s_setprio 1
	s_waitcnt lgkmcnt(0)
	s_barrier
	v_mfma_f32_16x16x32_bf16 v[126:129], v[130:133], v[166:169], v[126:129]
	v_mfma_f32_16x16x32_bf16 v[122:125], v[138:141], v[166:169], v[122:125]
	v_mfma_f32_16x16x32_bf16 v[110:113], v[130:133], v[184:187], v[110:113]
	v_mfma_f32_16x16x32_bf16 v[106:109], v[138:141], v[184:187], v[106:109]
	v_mfma_f32_16x16x32_bf16 v[94:97], v[130:133], v[192:195], v[94:97]
	v_mfma_f32_16x16x32_bf16 v[90:93], v[138:141], v[192:195], v[90:93]
	v_mfma_f32_16x16x32_bf16 v[78:81], v[130:133], v[200:203], v[78:81]
	v_mfma_f32_16x16x32_bf16 v[74:77], v[138:141], v[200:203], v[74:77]
	v_mfma_f32_16x16x32_bf16 v[118:121], v[146:149], v[166:169], v[118:121]
	v_mfma_f32_16x16x32_bf16 v[114:117], v[154:157], v[166:169], v[114:117]
	v_mfma_f32_16x16x32_bf16 v[102:105], v[146:149], v[184:187], v[102:105]
	v_mfma_f32_16x16x32_bf16 v[98:101], v[154:157], v[184:187], v[98:101]
	v_mfma_f32_16x16x32_bf16 v[86:89], v[146:149], v[192:195], v[86:89]
	v_mfma_f32_16x16x32_bf16 v[82:85], v[154:157], v[192:195], v[82:85]
	v_mfma_f32_16x16x32_bf16 v[70:73], v[146:149], v[200:203], v[70:73]
	v_mfma_f32_16x16x32_bf16 v[66:69], v[154:157], v[200:203], v[66:69]
	v_mfma_f32_16x16x32_bf16 v[126:129], v[134:137], v[170:173], v[126:129]
	v_mfma_f32_16x16x32_bf16 v[122:125], v[142:145], v[170:173], v[122:125]
	v_mfma_f32_16x16x32_bf16 v[110:113], v[134:137], v[188:191], v[110:113]
	v_mfma_f32_16x16x32_bf16 v[106:109], v[142:145], v[188:191], v[106:109]
	v_mfma_f32_16x16x32_bf16 v[94:97], v[134:137], v[196:199], v[94:97]
	v_mfma_f32_16x16x32_bf16 v[90:93], v[142:145], v[196:199], v[90:93]
	v_mfma_f32_16x16x32_bf16 v[78:81], v[134:137], v[204:207], v[78:81]
	v_mfma_f32_16x16x32_bf16 v[74:77], v[142:145], v[204:207], v[74:77]
	v_mfma_f32_16x16x32_bf16 v[118:121], v[150:153], v[170:173], v[118:121]
	v_mfma_f32_16x16x32_bf16 v[114:117], v[158:161], v[170:173], v[114:117]
	v_mfma_f32_16x16x32_bf16 v[102:105], v[150:153], v[188:191], v[102:105]
	v_mfma_f32_16x16x32_bf16 v[98:101], v[158:161], v[188:191], v[98:101]
	v_mfma_f32_16x16x32_bf16 v[86:89], v[150:153], v[196:199], v[86:89]
	v_mfma_f32_16x16x32_bf16 v[82:85], v[158:161], v[196:199], v[82:85]
	v_mfma_f32_16x16x32_bf16 v[70:73], v[150:153], v[204:207], v[70:73]
	v_mfma_f32_16x16x32_bf16 v[66:69], v[158:161], v[204:207], v[66:69]
	s_setprio 0
	s_barrier
	s_nop 0
	s_add_u32 s16, s26, 0x80
	s_addc_u32 s17, s27, 0
	s_add_i32 s28, s88, s73
	s_mov_b32 m0, s28
	ds_read_b128 v[166:169], v182 offset:49152
	ds_read_b128 v[170:173], v182 offset:50176
	ds_read_b128 v[184:187], v182 offset:51200
	ds_read_b128 v[188:191], v182 offset:52224
	ds_read_b128 v[192:195], v182 offset:53248
	ds_read_b128 v[196:199], v182 offset:54272
	ds_read_b128 v[200:203], v182 offset:55296
	ds_read_b128 v[204:207], v182 offset:56320
	s_nop 0
	global_load_lds_dwordx4 v174, s[16:17]
	s_add_i32 m0, s28, 0x2000
	s_nop 0
	global_load_lds_dwordx4 v176, s[16:17]
	s_add_u32 s16, s26, 0x100080
	s_addc_u32 s17, s27, 0
	s_add_i32 s26, s89, s73
	s_mov_b32 m0, s26
	s_nop 0
	global_load_lds_dwordx4 v174, s[16:17]
	s_add_i32 m0, s26, 0x2000
	s_nop 0
	global_load_lds_dwordx4 v176, s[16:17]
	s_mov_b32 m0, s77
	s_nop 0
	global_load_lds_dwordx4 v1, s[2:3]
	s_mov_b32 m0, s78
	s_nop 0
	global_load_lds_dwordx4 v175, s[2:3]
	s_waitcnt vmcnt(8)
	s_waitcnt lgkmcnt(0)
	s_setprio 1
	s_waitcnt lgkmcnt(0)
	s_barrier
	v_mfma_f32_16x16x32_bf16 v[62:65], v[130:133], v[166:169], v[62:65]
	v_mfma_f32_16x16x32_bf16 v[58:61], v[138:141], v[166:169], v[58:61]
	v_mfma_f32_16x16x32_bf16 v[46:49], v[130:133], v[184:187], v[46:49]
	v_mfma_f32_16x16x32_bf16 v[42:45], v[138:141], v[184:187], v[42:45]
	v_mfma_f32_16x16x32_bf16 v[30:33], v[130:133], v[192:195], v[30:33]
	v_mfma_f32_16x16x32_bf16 v[26:29], v[138:141], v[192:195], v[26:29]
	v_mfma_f32_16x16x32_bf16 v[14:17], v[130:133], v[200:203], v[14:17]
	v_mfma_f32_16x16x32_bf16 v[10:13], v[138:141], v[200:203], v[10:13]
	v_mfma_f32_16x16x32_bf16 v[54:57], v[146:149], v[166:169], v[54:57]
	v_mfma_f32_16x16x32_bf16 v[50:53], v[154:157], v[166:169], v[50:53]
	v_mfma_f32_16x16x32_bf16 v[38:41], v[146:149], v[184:187], v[38:41]
	v_mfma_f32_16x16x32_bf16 v[34:37], v[154:157], v[184:187], v[34:37]
	v_mfma_f32_16x16x32_bf16 v[22:25], v[146:149], v[192:195], v[22:25]
	v_mfma_f32_16x16x32_bf16 v[18:21], v[154:157], v[192:195], v[18:21]
	v_mfma_f32_16x16x32_bf16 v[6:9], v[146:149], v[200:203], v[6:9]
	v_mfma_f32_16x16x32_bf16 v[2:5], v[154:157], v[200:203], v[2:5]
	v_mfma_f32_16x16x32_bf16 v[62:65], v[134:137], v[170:173], v[62:65]
	v_mfma_f32_16x16x32_bf16 v[58:61], v[142:145], v[170:173], v[58:61]
	v_mfma_f32_16x16x32_bf16 v[46:49], v[134:137], v[188:191], v[46:49]
	v_mfma_f32_16x16x32_bf16 v[42:45], v[142:145], v[188:191], v[42:45]
	v_mfma_f32_16x16x32_bf16 v[30:33], v[134:137], v[196:199], v[30:33]
	v_mfma_f32_16x16x32_bf16 v[26:29], v[142:145], v[196:199], v[26:29]
	v_mfma_f32_16x16x32_bf16 v[14:17], v[134:137], v[204:207], v[14:17]
	v_mfma_f32_16x16x32_bf16 v[10:13], v[142:145], v[204:207], v[10:13]
	v_mfma_f32_16x16x32_bf16 v[54:57], v[150:153], v[170:173], v[54:57]
	v_mfma_f32_16x16x32_bf16 v[50:53], v[158:161], v[170:173], v[50:53]
	v_mfma_f32_16x16x32_bf16 v[38:41], v[150:153], v[188:191], v[38:41]
	v_mfma_f32_16x16x32_bf16 v[34:37], v[158:161], v[188:191], v[34:37]
	v_mfma_f32_16x16x32_bf16 v[22:25], v[150:153], v[196:199], v[22:25]
	v_mfma_f32_16x16x32_bf16 v[18:21], v[158:161], v[196:199], v[18:21]
	v_mfma_f32_16x16x32_bf16 v[6:9], v[150:153], v[204:207], v[6:9]
	v_mfma_f32_16x16x32_bf16 v[2:5], v[158:161], v[204:207], v[2:5]
	s_setprio 0
	s_barrier
	s_add_i32 s87, s87, 2
	s_add_u32 s85, s85, 0x100
	s_addc_u32 s86, s86, 0
	s_cmp_gt_u32 s87, 61
	s_mov_b64 s[16:17], s[24:25]
	s_cbranch_scc0 .LBB0_833
	s_and_b64 vcc, exec, s[12:13]
	s_cbranch_vccz .LBB0_836
	s_barrier

;     __device__ bool next(int i, Unit& u) const { if (i > 1) return false; const int xcd = c & 7, idx = c >> 3; u.pm = 16 * i + 4 * (xcd >> 1) + (idx & 3); u.pn = 8 * (xcd & 1) + (idx >> 2); return true; }
; #define PG8_STAGE(bufoff, gbase, voff) do { const char* _gb = (const char*)(gbase); asm volatile("" : "+s"(_gb)); _Pragma("unroll") for (int _i = 0; _i < 2; ++_i) { asm volatile("" : "+v"((voff)[_i])); \
;         __builtin_amdgcn_global_load_lds((const unsigned*)(_gb + (voff)[_i]), (PG8_LAS unsigned*)(lds + (bufoff) + ldsw + _i * 8192), 16, 0, 0); } } while (0)
; #define PG8_LDA(dst, b, h) do { _Pragma("unroll") for (int m = 0; m < 4; ++m) _Pragma("unroll") for (int k = 0; k < 2; ++k) dst[m][k] = *(const PG8_LAS bf16x8*)(lds + PG8_SA(b, h) + aoff + m * 2048 + k * 1024); } while (0)
; #define PG8_WAIT_V(n) asm volatile("s_waitcnt vmcnt(" #n ")" ::: "memory")
; #define PG8_WAIT_L(n) asm volatile("s_waitcnt lgkmcnt(" #n ")" ::: "memory")
; template <class Epi, class Sched, bool ALIGN_EPI = false, bool SP2 = false>
; __device__ __forceinline__ void gemm_phase(PG8_LAS unsigned char* lds, const Gemm g, const Sched& S, const Epi& E) {
;     ...
;         const bool has_next = S.next(ui + 1, nxt);
;         const char* nA = has_next ? (const char*)g.A + (size_t)nxt.pm * tstep : cA; const char* nB = has_next ? (const char*)g.Bt + (size_t)nxt.pn * tstep : cB;
;         for (int t = 0; t < nt; t += 2) {
;             const bool last = (t == nt - 2);
;             const char* a1 = cA + (size_t)(t + 1) * kstep;
;             const char* a2 = last ? nA : cA + (size_t)(t + 2) * kstep; const char* b2 = last ? nB : cB + (size_t)(t + 2) * kstep;
;             const char* a3 = a2 + kstep; const char* b3 = b2 + kstep;
;             if (last && has_next) S.a_ready(nxt);
;             if constexpr (SP2) {
;             PG8_LDB(B0, 0, 0); PG8_LDB(B1, 0, 1); PG8_SCHED; PG8_LDA(At, 0, 0); PG8_STAGE(PG8_SA(1, 1), a1 + hstep, voffA);
;             PG8_WAIT_V(8); PG8_WAIT_L(0); PG8_BAR; PG8_MMA2(0); PG8_BAR; PG8_SCHED;
;     ...
; #pragma unroll
;         for (int a = 0; a < 2; ++a)
; #pragma unroll
;             for (int b = 0; b < 2; ++b)
; #pragma unroll
;                 for (int m = 0; m < 4; ++m)
; #pragma unroll
;                     for (int n = 0; n < 2; ++n) acc[a][b][m][n] = (f32x4){0.f, 0.f, 0.f, 0.f};
;         cur = nxt; cA = nA; cB = nB; ++ui;
.LBB0_932:
	s_ashr_i32 s51, s50, 31
	s_lshl_b64 s[2:3], s[50:51], 21
	s_add_u32 s52, s26, s2
	s_addc_u32 s53, s27, s3
	s_and_b64 s[2:3], s[10:11], exec
	s_cselect_b32 s20, s53, s13
	s_cselect_b32 s21, s52, s12
	s_ashr_i32 s49, s48, 31
	s_lshl_b64 s[2:3], s[48:49], 21
	s_add_u32 s54, s28, s2
	s_addc_u32 s55, s29, s3
	s_and_b64 s[2:3], s[10:11], exec
	s_cselect_b32 s49, s55, s15
	s_cselect_b32 s51, s54, s14
	s_add_u32 s62, s14, 0x100
	v_mov_b32_e32 v38, 0
	s_addc_u32 s63, s15, 0
	s_mov_b32 s83, -2
	v_mov_b32_e32 v39, v38
	v_mov_b32_e32 v40, v38
	v_mov_b32_e32 v41, v38
	v_mov_b32_e32 v42, v38
	v_mov_b32_e32 v43, v38
	v_mov_b32_e32 v44, v38
	v_mov_b32_e32 v45, v38
	v_mov_b32_e32 v46, v38
	v_mov_b32_e32 v47, v38
	v_mov_b32_e32 v48, v38
	v_mov_b32_e32 v49, v38
	v_mov_b32_e32 v54, v38
	v_mov_b32_e32 v55, v38
	v_mov_b32_e32 v56, v38
	v_mov_b32_e32 v57, v38
	v_mov_b32_e32 v2, v38
	v_mov_b32_e32 v3, v38
	v_mov_b32_e32 v4, v38
	v_mov_b32_e32 v5, v38
	v_mov_b32_e32 v10, v38
	v_mov_b32_e32 v11, v38
	v_mov_b32_e32 v12, v38
	v_mov_b32_e32 v13, v38
	v_mov_b32_e32 v14, v38
	v_mov_b32_e32 v15, v38
	v_mov_b32_e32 v16, v38
	v_mov_b32_e32 v17, v38
	v_mov_b32_e32 v18, v38
	v_mov_b32_e32 v19, v38
	v_mov_b32_e32 v20, v38
	v_mov_b32_e32 v21, v38
	v_mov_b32_e32 v50, v38
	v_mov_b32_e32 v51, v38
	v_mov_b32_e32 v52, v38
	v_mov_b32_e32 v53, v38
	v_mov_b32_e32 v58, v38
	v_mov_b32_e32 v59, v38
	v_mov_b32_e32 v60, v38
	v_mov_b32_e32 v61, v38
	v_mov_b32_e32 v66, v38
	v_mov_b32_e32 v67, v38
	v_mov_b32_e32 v68, v38
	v_mov_b32_e32 v69, v38
	v_mov_b32_e32 v70, v38
	v_mov_b32_e32 v71, v38
	v_mov_b32_e32 v72, v38
	v_mov_b32_e32 v73, v38
	v_mov_b32_e32 v22, v38
	v_mov_b32_e32 v23, v38
	v_mov_b32_e32 v24, v38
	v_mov_b32_e32 v25, v38
	v_mov_b32_e32 v26, v38
	v_mov_b32_e32 v27, v38
	v_mov_b32_e32 v28, v38
	v_mov_b32_e32 v29, v38
	v_mov_b32_e32 v30, v38
	v_mov_b32_e32 v31, v38
	v_mov_b32_e32 v32, v38
	v_mov_b32_e32 v33, v38
	v_mov_b32_e32 v34, v38
	v_mov_b32_e32 v35, v38
	v_mov_b32_e32 v36, v38
	v_mov_b32_e32 v37, v38
	v_mov_b32_e32 v102, v38
	v_mov_b32_e32 v103, v38
	v_mov_b32_e32 v104, v38
	v_mov_b32_e32 v105, v38
	v_mov_b32_e32 v122, v38
	v_mov_b32_e32 v123, v38
	v_mov_b32_e32 v124, v38
	v_mov_b32_e32 v125, v38
	v_mov_b32_e32 v98, v38
	v_mov_b32_e32 v99, v38
	v_mov_b32_e32 v100, v38
	v_mov_b32_e32 v101, v38
	v_mov_b32_e32 v126, v38
	v_mov_b32_e32 v127, v38
	v_mov_b32_e32 v128, v38
	v_mov_b32_e32 v129, v38
	v_mov_b32_e32 v74, v38
	v_mov_b32_e32 v75, v38
	v_mov_b32_e32 v76, v38
	v_mov_b32_e32 v77, v38
	v_mov_b32_e32 v78, v38
	v_mov_b32_e32 v79, v38
	v_mov_b32_e32 v80, v38
	v_mov_b32_e32 v81, v38
	v_mov_b32_e32 v82, v38
	v_mov_b32_e32 v83, v38
	v_mov_b32_e32 v84, v38
	v_mov_b32_e32 v85, v38
	v_mov_b32_e32 v94, v38
	v_mov_b32_e32 v95, v38
	v_mov_b32_e32 v96, v38
	v_mov_b32_e32 v97, v38
	v_mov_b32_e32 v110, v38
	v_mov_b32_e32 v111, v38
	v_mov_b32_e32 v112, v38
	v_mov_b32_e32 v113, v38
	v_mov_b32_e32 v130, v38
	v_mov_b32_e32 v131, v38
	v_mov_b32_e32 v132, v38
	v_mov_b32_e32 v133, v38
	v_mov_b32_e32 v90, v38
	v_mov_b32_e32 v91, v38
	v_mov_b32_e32 v92, v38
	v_mov_b32_e32 v93, v38
	v_mov_b32_e32 v134, v38
	v_mov_b32_e32 v135, v38
	v_mov_b32_e32 v136, v38
	v_mov_b32_e32 v137, v38
	v_mov_b32_e32 v86, v38
	v_mov_b32_e32 v87, v38
	v_mov_b32_e32 v88, v38
	v_mov_b32_e32 v89, v38
	v_mov_b32_e32 v106, v38
	v_mov_b32_e32 v107, v38
	v_mov_b32_e32 v108, v38
	v_mov_b32_e32 v109, v38
	v_mov_b32_e32 v114, v38
	v_mov_b32_e32 v115, v38
	v_mov_b32_e32 v116, v38
	v_mov_b32_e32 v117, v38
	v_mov_b32_e32 v118, v38
	v_mov_b32_e32 v119, v38
	v_mov_b32_e32 v120, v38
	v_mov_b32_e32 v121, v38
	s_nop 0
.LBB0_933:
	v_add_u32_e32 v142, s78, v201
	v_add_u32_e32 v147, s79, v201
	s_nop 0
	ds_read_b128 v[6:9], v142
	ds_read_b128 v[62:65], v142 offset:1024
	ds_read_b128 v[138:141], v142 offset:2048
	ds_read_b128 v[142:145], v142 offset:3072
	ds_read_b128 v[164:167], v147
	ds_read_b128 v[168:171], v147 offset:1024
	ds_read_b128 v[172:175], v147 offset:2048
	ds_read_b128 v[176:179], v147 offset:3072
	s_add_u32 s14, s12, 0x100
	s_addc_u32 s15, s13, 0
	s_cmp_eq_u32 s83, 60
	s_cselect_b32 s18, s21, s14
	s_cselect_b32 s19, s20, s15
	s_cselect_b32 s16, s51, s62
	s_cselect_b32 s17, s49, s63
	s_add_u32 s2, s18, 0x80
	s_addc_u32 s3, s19, 0
	s_add_u32 s12, s12, 0x100080
	s_addc_u32 s13, s13, 0
	s_add_i32 m0, s33, 0xc000
	ds_read_b128 v[180:183], v219
	ds_read_b128 v[184:187], v219 offset:1024
	ds_read_b128 v[188:191], v219 offset:2048
	ds_read_b128 v[192:195], v219 offset:3072
	ds_read_b128 v[222:225], v219 offset:4096
	ds_read_b128 v[226:229], v219 offset:5120
	ds_read_b128 v[230:233], v219 offset:6144
	ds_read_b128 v[234:237], v219 offset:7168
	s_nop 0
	global_load_lds_dwordx4 v1, s[12:13]
	s_add_i32 m0, s33, 0xe000
	s_nop 0
	global_load_lds_dwordx4 v199, s[12:13]
	s_waitcnt vmcnt(8)
	s_waitcnt lgkmcnt(0)
	s_setprio 1
	s_waitcnt lgkmcnt(0)
	s_barrier
; #define PG8_STAGE(bufoff, gbase, voff) do { const char* _gb = (const char*)(gbase); asm volatile("" : "+s"(_gb)); _Pragma("unroll") for (int _i = 0; _i < 2; ++_i) { asm volatile("" : "+v"((voff)[_i])); \
;         __builtin_amdgcn_global_load_lds((const unsigned*)(_gb + (voff)[_i]), (PG8_LAS unsigned*)(lds + (bufoff) + ldsw + _i * 8192), 16, 0, 0); } } while (0)
; #define PG8_LDA(dst, b, h) do { _Pragma("unroll") for (int m = 0; m < 4; ++m) _Pragma("unroll") for (int k = 0; k < 2; ++k) dst[m][k] = *(const PG8_LAS bf16x8*)(lds + PG8_SA(b, h) + aoff + m * 2048 + k * 1024); } while (0)
; #define PG8_WAIT_V(n) asm volatile("s_waitcnt vmcnt(" #n ")" ::: "memory")
; #define PG8_WAIT_L(n) asm volatile("s_waitcnt lgkmcnt(" #n ")" ::: "memory")
; #define PG8_BAR __builtin_amdgcn_s_barrier()
; #define PG8_SCHED __builtin_amdgcn_sched_barrier(0)
; #define PG8_STAGE(bufoff, gbase, voff) do { const char* _gb = (const char*)(gbase); asm volatile("" : "+s"(_gb)); _Pragma("unroll") for (int _i = 0; _i < 2; ++_i) { asm volatile("" : "+v"((voff)[_i])); \
;         __builtin_amdgcn_global_load_lds((const unsigned*)(_gb + (voff)[_i]), (PG8_LAS unsigned*)(lds + (bufoff) + ldsw + _i * 8192), 16, 0, 0); } } while (0)
; #define PG8_LDA(dst, b, h) do { _Pragma("unroll") for (int m = 0; m < 4; ++m) _Pragma("unroll") for (int k = 0; k < 2; ++k) dst[m][k] = *(const PG8_LAS bf16x8*)(lds + PG8_SA(b, h) + aoff + m * 2048 + k * 1024); } while (0)
; #define PG8_WAIT_V(n) asm volatile("s_waitcnt vmcnt(" #n ")" ::: "memory")
; #define PG8_WAIT_L(n) asm volatile("s_waitcnt lgkmcnt(" #n ")" ::: "memory")
; #define PG8_BAR __builtin_amdgcn_s_barrier()
; #define PG8_SCHED __builtin_amdgcn_sched_barrier(0)
; template <class Epi, class Sched, bool ALIGN_EPI = false, bool SP2 = false>
; __device__ __forceinline__ void gemm_phase(PG8_LAS unsigned char* lds, const Gemm g, const Sched& S, const Epi& E) {
;     ...
;             PG8_WAIT_V(8); PG8_WAIT_L(0); PG8_BAR; PG8_MMA2(0); PG8_BAR; PG8_SCHED;
;             PG8_LDA(At, 0, 1); PG8_STAGE(PG8_SB(0, 0), b2, voffB); PG8_STAGE(PG8_SB(0, 1), b2 + hstep, voffB); PG8_STAGE(PG8_SA(0, 0), a2, voffA);
;             PG8_WAIT_V(8); PG8_WAIT_L(0); PG8_BAR; PG8_MMA2(1); PG8_BAR; PG8_SCHED;
	v_mfma_f32_16x16x32_bf16 v[118:121], v[6:9], v[180:183], v[118:121]
	v_mfma_f32_16x16x32_bf16 v[114:117], v[138:141], v[180:183], v[114:117]
	v_mfma_f32_16x16x32_bf16 v[106:109], v[6:9], v[188:191], v[106:109]
	v_mfma_f32_16x16x32_bf16 v[86:89], v[138:141], v[188:191], v[86:89]
	v_mfma_f32_16x16x32_bf16 v[134:137], v[6:9], v[222:225], v[134:137]
	v_mfma_f32_16x16x32_bf16 v[90:93], v[138:141], v[222:225], v[90:93]
	v_mfma_f32_16x16x32_bf16 v[130:133], v[6:9], v[230:233], v[130:133]
	v_mfma_f32_16x16x32_bf16 v[110:113], v[138:141], v[230:233], v[110:113]
	v_mfma_f32_16x16x32_bf16 v[94:97], v[164:167], v[180:183], v[94:97]
	v_mfma_f32_16x16x32_bf16 v[82:85], v[172:175], v[180:183], v[82:85]
	v_mfma_f32_16x16x32_bf16 v[78:81], v[164:167], v[188:191], v[78:81]
	v_mfma_f32_16x16x32_bf16 v[74:77], v[172:175], v[188:191], v[74:77]
	v_mfma_f32_16x16x32_bf16 v[126:129], v[164:167], v[222:225], v[126:129]
	v_mfma_f32_16x16x32_bf16 v[98:101], v[172:175], v[222:225], v[98:101]
	v_mfma_f32_16x16x32_bf16 v[122:125], v[164:167], v[230:233], v[122:125]
	v_mfma_f32_16x16x32_bf16 v[102:105], v[172:175], v[230:233], v[102:105]
	v_mfma_f32_16x16x32_bf16 v[118:121], v[62:65], v[184:187], v[118:121]
	v_mfma_f32_16x16x32_bf16 v[114:117], v[142:145], v[184:187], v[114:117]
	v_mfma_f32_16x16x32_bf16 v[106:109], v[62:65], v[192:195], v[106:109]
	v_mfma_f32_16x16x32_bf16 v[86:89], v[142:145], v[192:195], v[86:89]
	v_mfma_f32_16x16x32_bf16 v[134:137], v[62:65], v[226:229], v[134:137]
	v_mfma_f32_16x16x32_bf16 v[90:93], v[142:145], v[226:229], v[90:93]
	v_mfma_f32_16x16x32_bf16 v[130:133], v[62:65], v[234:237], v[130:133]
	v_mfma_f32_16x16x32_bf16 v[110:113], v[142:145], v[234:237], v[110:113]
	v_mfma_f32_16x16x32_bf16 v[94:97], v[168:171], v[184:187], v[94:97]
	v_mfma_f32_16x16x32_bf16 v[82:85], v[176:179], v[184:187], v[82:85]
	v_mfma_f32_16x16x32_bf16 v[78:81], v[168:171], v[192:195], v[78:81]
	v_mfma_f32_16x16x32_bf16 v[74:77], v[176:179], v[192:195], v[74:77]
	v_mfma_f32_16x16x32_bf16 v[126:129], v[168:171], v[226:229], v[126:129]
	v_mfma_f32_16x16x32_bf16 v[98:101], v[176:179], v[226:229], v[98:101]
	v_mfma_f32_16x16x32_bf16 v[122:125], v[168:171], v[234:237], v[122:125]
	v_mfma_f32_16x16x32_bf16 v[102:105], v[176:179], v[234:237], v[102:105]
	s_setprio 0
	s_barrier
	s_add_i32 s84, s78, s25
	s_mov_b64 s[12:13], s[16:17]
	s_mov_b32 m0, s84
	ds_read_b128 v[180:183], v219 offset:16384
	ds_read_b128 v[184:187], v219 offset:17408
	ds_read_b128 v[188:191], v219 offset:18432
	ds_read_b128 v[192:195], v219 offset:19456
	ds_read_b128 v[222:225], v219 offset:20480
	ds_read_b128 v[226:229], v219 offset:21504
	ds_read_b128 v[230:233], v219 offset:22528
	ds_read_b128 v[234:237], v219 offset:23552
	s_nop 0
	global_load_lds_dwordx4 v198, s[12:13]
	s_add_i32 m0, s84, 0x2000
	s_nop 0
	global_load_lds_dwordx4 v200, s[12:13]
	s_add_u32 s12, s16, 0x100000
	s_addc_u32 s13, s17, 0
	s_add_i32 s84, s79, s25
	s_mov_b32 m0, s84
	s_nop 0
	global_load_lds_dwordx4 v198, s[12:13]
	s_add_i32 m0, s84, 0x2000
	s_nop 0
	global_load_lds_dwordx4 v200, s[12:13]
	s_mov_b64 s[12:13], s[18:19]
	s_mov_b32 m0, s33
	s_nop 0
	global_load_lds_dwordx4 v1, s[12:13]
	s_mov_b32 m0, s45
	s_nop 0
	global_load_lds_dwordx4 v199, s[12:13]
	s_waitcnt vmcnt(8)
	s_waitcnt lgkmcnt(0)
	s_setprio 1
	s_waitcnt lgkmcnt(0)
	s_barrier
	v_mfma_f32_16x16x32_bf16 v[34:37], v[6:9], v[180:183], v[34:37]
	v_mfma_f32_16x16x32_bf16 v[30:33], v[138:141], v[180:183], v[30:33]
	v_mfma_f32_16x16x32_bf16 v[26:29], v[6:9], v[188:191], v[26:29]
	v_mfma_f32_16x16x32_bf16 v[22:25], v[138:141], v[188:191], v[22:25]
	v_mfma_f32_16x16x32_bf16 v[70:73], v[6:9], v[222:225], v[70:73]
	v_mfma_f32_16x16x32_bf16 v[66:69], v[138:141], v[222:225], v[66:69]
	v_mfma_f32_16x16x32_bf16 v[50:53], v[138:141], v[230:233], v[50:53]
	v_mfma_f32_16x16x32_bf16 v[18:21], v[164:167], v[180:183], v[18:21]
	v_mfma_f32_16x16x32_bf16 v[14:17], v[172:175], v[180:183], v[14:17]
	v_mfma_f32_16x16x32_bf16 v[10:13], v[164:167], v[188:191], v[10:13]
	v_mfma_f32_16x16x32_bf16 v[2:5], v[172:175], v[188:191], v[2:5]
	v_mfma_f32_16x16x32_bf16 v[54:57], v[164:167], v[222:225], v[54:57]
	v_mfma_f32_16x16x32_bf16 v[46:49], v[172:175], v[222:225], v[46:49]
	v_mfma_f32_16x16x32_bf16 v[42:45], v[164:167], v[230:233], v[42:45]
	v_mfma_f32_16x16x32_bf16 v[38:41], v[172:175], v[230:233], v[38:41]
	v_mfma_f32_16x16x32_bf16 v[34:37], v[62:65], v[184:187], v[34:37]
	v_mfma_f32_16x16x32_bf16 v[30:33], v[142:145], v[184:187], v[30:33]
	v_mfma_f32_16x16x32_bf16 v[26:29], v[62:65], v[192:195], v[26:29]
	v_mfma_f32_16x16x32_bf16 v[22:25], v[142:145], v[192:195], v[22:25]
	v_mfma_f32_16x16x32_bf16 v[70:73], v[62:65], v[226:229], v[70:73]
	v_mfma_f32_16x16x32_bf16 v[66:69], v[142:145], v[226:229], v[66:69]
	v_mfma_f32_16x16x32_bf16 v[6:9], v[6:9], v[230:233], v[58:61]
	v_mfma_f32_16x16x32_bf16 v[50:53], v[142:145], v[234:237], v[50:53]
	v_mfma_f32_16x16x32_bf16 v[18:21], v[168:171], v[184:187], v[18:21]
	v_mfma_f32_16x16x32_bf16 v[14:17], v[176:179], v[184:187], v[14:17]
	v_mfma_f32_16x16x32_bf16 v[10:13], v[168:171], v[192:195], v[10:13]
	v_mfma_f32_16x16x32_bf16 v[2:5], v[176:179], v[192:195], v[2:5]
	v_mfma_f32_16x16x32_bf16 v[54:57], v[168:171], v[226:229], v[54:57]
	v_mfma_f32_16x16x32_bf16 v[46:49], v[176:179], v[226:229], v[46:49]
	v_mfma_f32_16x16x32_bf16 v[42:45], v[168:171], v[234:237], v[42:45]
	v_mfma_f32_16x16x32_bf16 v[38:41], v[176:179], v[234:237], v[38:41]
	v_mfma_f32_16x16x32_bf16 v[6:9], v[62:65], v[234:237], v[6:9]
	s_setprio 0
	s_barrier
; #define PG8_STAGE(bufoff, gbase, voff) do { const char* _gb = (const char*)(gbase); asm volatile("" : "+s"(_gb)); _Pragma("unroll") for (int _i = 0; _i < 2; ++_i) { asm volatile("" : "+v"((voff)[_i])); \
;         __builtin_amdgcn_global_load_lds((const unsigned*)(_gb + (voff)[_i]), (PG8_LAS unsigned*)(lds + (bufoff) + ldsw + _i * 8192), 16, 0, 0); } } while (0)
; #define PG8_LDA(dst, b, h) do { _Pragma("unroll") for (int m = 0; m < 4; ++m) _Pragma("unroll") for (int k = 0; k < 2; ++k) dst[m][k] = *(const PG8_LAS bf16x8*)(lds + PG8_SA(b, h) + aoff + m * 2048 + k * 1024); } while (0)
; #define PG8_LDB(dst, b, h) do { _Pragma("unroll") for (int n = 0; n < 2; ++n) _Pragma("unroll") for (int k = 0; k < 2; ++k) dst[n][k] = *(const PG8_LAS bf16x8*)(lds + PG8_SB(b, h) + boff + n * 2048 + k * 1024); } while (0)
; #define PG8_WAIT_V(n) asm volatile("s_waitcnt vmcnt(" #n ")" ::: "memory")
; #define PG8_WAIT_L(n) asm volatile("s_waitcnt lgkmcnt(" #n ")" ::: "memory")
; #define PG8_BAR __builtin_amdgcn_s_barrier()
; #define PG8_SCHED __builtin_amdgcn_sched_barrier(0)
; #define PG8_STAGE(bufoff, gbase, voff) do { const char* _gb = (const char*)(gbase); asm volatile("" : "+s"(_gb)); _Pragma("unroll") for (int _i = 0; _i < 2; ++_i) { asm volatile("" : "+v"((voff)[_i])); \
;         __builtin_amdgcn_global_load_lds((const unsigned*)(_gb + (voff)[_i]), (PG8_LAS unsigned*)(lds + (bufoff) + ldsw + _i * 8192), 16, 0, 0); } } while (0)
; #define PG8_LDA(dst, b, h) do { _Pragma("unroll") for (int m = 0; m < 4; ++m) _Pragma("unroll") for (int k = 0; k < 2; ++k) dst[m][k] = *(const PG8_LAS bf16x8*)(lds + PG8_SA(b, h) + aoff + m * 2048 + k * 1024); } while (0)
; #define PG8_WAIT_V(n) asm volatile("s_waitcnt vmcnt(" #n ")" ::: "memory")
; template <class Epi, class Sched, bool ALIGN_EPI = false, bool SP2 = false>
; __device__ __forceinline__ void gemm_phase(PG8_LAS unsigned char* lds, const Gemm g, const Sched& S, const Epi& E) {
;     ...
;             PG8_LDB(B0, 1, 0); PG8_LDB(B1, 1, 1); PG8_SCHED; PG8_LDA(At, 1, 0); PG8_STAGE(PG8_SA(0, 1), a2 + hstep, voffA);
;             PG8_WAIT_V(8); PG8_WAIT_L(0); PG8_BAR; PG8_MMA2(0); PG8_BAR; PG8_SCHED;
;             PG8_LDA(At, 1, 1); PG8_STAGE(PG8_SB(1, 0), b3, voffB); PG8_STAGE(PG8_SB(1, 1), b3 + hstep, voffB); PG8_STAGE(PG8_SA(1, 0), a3, voffA);
;             PG8_WAIT_V(8); PG8_WAIT_L(0); PG8_BAR; PG8_MMA2(1); PG8_BAR; PG8_SCHED;
	s_add_i32 s84, 0, 0x18000
	s_add_i32 s85, 0, 0x1c000
	v_add_u32_e32 v142, s84, v201
	v_add_u32_e32 v147, s85, v201
	ds_read_b128 v[58:61], v142
	ds_read_b128 v[62:65], v142 offset:1024
	ds_read_b128 v[138:141], v142 offset:2048
	ds_read_b128 v[142:145], v142 offset:3072
	ds_read_b128 v[164:167], v147
	ds_read_b128 v[168:171], v147 offset:1024
	ds_read_b128 v[172:175], v147 offset:2048
	ds_read_b128 v[176:179], v147 offset:3072
	s_add_u32 s12, s18, 0x100000
	s_addc_u32 s13, s19, 0
	s_mov_b32 m0, s47
	ds_read_b128 v[180:183], v219 offset:32768
	ds_read_b128 v[184:187], v219 offset:33792
	ds_read_b128 v[188:191], v219 offset:34816
	ds_read_b128 v[192:195], v219 offset:35840
	ds_read_b128 v[222:225], v219 offset:36864
	ds_read_b128 v[226:229], v219 offset:37888
	ds_read_b128 v[230:233], v219 offset:38912
	ds_read_b128 v[234:237], v219 offset:39936
	s_nop 0
	global_load_lds_dwordx4 v1, s[12:13]
	s_mov_b32 m0, s87
	s_nop 0
	global_load_lds_dwordx4 v199, s[12:13]
	s_waitcnt vmcnt(8)
	s_waitcnt lgkmcnt(0)
	s_setprio 1
	s_waitcnt lgkmcnt(0)
	s_barrier
	v_mfma_f32_16x16x32_bf16 v[118:121], v[58:61], v[180:183], v[118:121]
	v_mfma_f32_16x16x32_bf16 v[114:117], v[138:141], v[180:183], v[114:117]
	v_mfma_f32_16x16x32_bf16 v[106:109], v[58:61], v[188:191], v[106:109]
	v_mfma_f32_16x16x32_bf16 v[86:89], v[138:141], v[188:191], v[86:89]
	v_mfma_f32_16x16x32_bf16 v[134:137], v[58:61], v[222:225], v[134:137]
	v_mfma_f32_16x16x32_bf16 v[90:93], v[138:141], v[222:225], v[90:93]
	v_mfma_f32_16x16x32_bf16 v[130:133], v[58:61], v[230:233], v[130:133]
	v_mfma_f32_16x16x32_bf16 v[110:113], v[138:141], v[230:233], v[110:113]
	v_mfma_f32_16x16x32_bf16 v[94:97], v[164:167], v[180:183], v[94:97]
	v_mfma_f32_16x16x32_bf16 v[82:85], v[172:175], v[180:183], v[82:85]
	v_mfma_f32_16x16x32_bf16 v[78:81], v[164:167], v[188:191], v[78:81]
	v_mfma_f32_16x16x32_bf16 v[74:77], v[172:175], v[188:191], v[74:77]
	v_mfma_f32_16x16x32_bf16 v[126:129], v[164:167], v[222:225], v[126:129]
	v_mfma_f32_16x16x32_bf16 v[98:101], v[172:175], v[222:225], v[98:101]
	v_mfma_f32_16x16x32_bf16 v[122:125], v[164:167], v[230:233], v[122:125]
	v_mfma_f32_16x16x32_bf16 v[102:105], v[172:175], v[230:233], v[102:105]
	v_mfma_f32_16x16x32_bf16 v[118:121], v[62:65], v[184:187], v[118:121]
	v_mfma_f32_16x16x32_bf16 v[114:117], v[142:145], v[184:187], v[114:117]
	v_mfma_f32_16x16x32_bf16 v[106:109], v[62:65], v[192:195], v[106:109]
	v_mfma_f32_16x16x32_bf16 v[86:89], v[142:145], v[192:195], v[86:89]
	v_mfma_f32_16x16x32_bf16 v[134:137], v[62:65], v[226:229], v[134:137]
	v_mfma_f32_16x16x32_bf16 v[90:93], v[142:145], v[226:229], v[90:93]
	v_mfma_f32_16x16x32_bf16 v[130:133], v[62:65], v[234:237], v[130:133]
	v_mfma_f32_16x16x32_bf16 v[110:113], v[142:145], v[234:237], v[110:113]
	v_mfma_f32_16x16x32_bf16 v[94:97], v[168:171], v[184:187], v[94:97]
	v_mfma_f32_16x16x32_bf16 v[82:85], v[176:179], v[184:187], v[82:85]
	v_mfma_f32_16x16x32_bf16 v[78:81], v[168:171], v[192:195], v[78:81]
	v_mfma_f32_16x16x32_bf16 v[74:77], v[176:179], v[192:195], v[74:77]
	v_mfma_f32_16x16x32_bf16 v[126:129], v[168:171], v[226:229], v[126:129]
	v_mfma_f32_16x16x32_bf16 v[98:101], v[176:179], v[226:229], v[98:101]
	v_mfma_f32_16x16x32_bf16 v[122:125], v[168:171], v[234:237], v[122:125]
	v_mfma_f32_16x16x32_bf16 v[102:105], v[176:179], v[234:237], v[102:105]
	s_setprio 0
	s_barrier
	s_nop 0
	s_add_u32 s12, s16, 0x80
	s_addc_u32 s13, s17, 0
	s_add_i32 s18, s84, s25
	s_mov_b32 m0, s18
	ds_read_b128 v[180:183], v219 offset:49152
	ds_read_b128 v[184:187], v219 offset:50176
	ds_read_b128 v[188:191], v219 offset:51200
	ds_read_b128 v[192:195], v219 offset:52224
	ds_read_b128 v[222:225], v219 offset:53248
	ds_read_b128 v[226:229], v219 offset:54272
	ds_read_b128 v[230:233], v219 offset:55296
	ds_read_b128 v[234:237], v219 offset:56320
	s_nop 0
	global_load_lds_dwordx4 v198, s[12:13]
	s_add_i32 m0, s18, 0x2000
	s_nop 0
	global_load_lds_dwordx4 v200, s[12:13]
	s_add_u32 s12, s16, 0x100080
	s_addc_u32 s13, s17, 0
	s_add_i32 s16, s85, s25
	s_mov_b32 m0, s16
	s_nop 0
	global_load_lds_dwordx4 v198, s[12:13]
	s_add_i32 m0, s16, 0x2000
	s_nop 0
	global_load_lds_dwordx4 v200, s[12:13]
	s_mov_b32 m0, s71
	s_nop 0
	global_load_lds_dwordx4 v1, s[2:3]
	s_mov_b32 m0, s72
	s_nop 0
	global_load_lds_dwordx4 v199, s[2:3]
	s_waitcnt vmcnt(8)
	s_waitcnt lgkmcnt(0)
	s_setprio 1
	s_waitcnt lgkmcnt(0)
	s_barrier
	v_mfma_f32_16x16x32_bf16 v[6:9], v[58:61], v[230:233], v[6:9]
	v_mfma_f32_16x16x32_bf16 v[34:37], v[58:61], v[180:183], v[34:37]
	v_mfma_f32_16x16x32_bf16 v[26:29], v[58:61], v[188:191], v[26:29]
	v_mfma_f32_16x16x32_bf16 v[70:73], v[58:61], v[222:225], v[70:73]
	v_mfma_f32_16x16x32_bf16 v[58:61], v[62:65], v[234:237], v[6:9]
	v_mfma_f32_16x16x32_bf16 v[6:9], v[138:141], v[230:233], v[50:53]
	v_mfma_f32_16x16x32_bf16 v[50:53], v[142:145], v[234:237], v[6:9]
	v_mfma_f32_16x16x32_bf16 v[6:9], v[164:167], v[180:183], v[18:21]
	v_mfma_f32_16x16x32_bf16 v[18:21], v[168:171], v[184:187], v[6:9]
	v_mfma_f32_16x16x32_bf16 v[6:9], v[172:175], v[180:183], v[14:17]
	v_mfma_f32_16x16x32_bf16 v[14:17], v[176:179], v[184:187], v[6:9]
	v_mfma_f32_16x16x32_bf16 v[6:9], v[164:167], v[188:191], v[10:13]
	v_mfma_f32_16x16x32_bf16 v[10:13], v[168:171], v[192:195], v[6:9]
	v_mfma_f32_16x16x32_bf16 v[6:9], v[164:167], v[222:225], v[54:57]
	v_mfma_f32_16x16x32_bf16 v[54:57], v[168:171], v[226:229], v[6:9]
	v_mfma_f32_16x16x32_bf16 v[6:9], v[172:175], v[222:225], v[46:49]
	v_mfma_f32_16x16x32_bf16 v[46:49], v[176:179], v[226:229], v[6:9]
	v_mfma_f32_16x16x32_bf16 v[6:9], v[164:167], v[230:233], v[42:45]
	v_mfma_f32_16x16x32_bf16 v[30:33], v[138:141], v[180:183], v[30:33]
	v_mfma_f32_16x16x32_bf16 v[22:25], v[138:141], v[188:191], v[22:25]
	v_mfma_f32_16x16x32_bf16 v[66:69], v[138:141], v[222:225], v[66:69]
	v_mfma_f32_16x16x32_bf16 v[2:5], v[172:175], v[188:191], v[2:5]
	v_mfma_f32_16x16x32_bf16 v[42:45], v[168:171], v[234:237], v[6:9]
	v_mfma_f32_16x16x32_bf16 v[6:9], v[172:175], v[230:233], v[38:41]
	v_mfma_f32_16x16x32_bf16 v[34:37], v[62:65], v[184:187], v[34:37]
	v_mfma_f32_16x16x32_bf16 v[30:33], v[142:145], v[184:187], v[30:33]
	v_mfma_f32_16x16x32_bf16 v[26:29], v[62:65], v[192:195], v[26:29]
	v_mfma_f32_16x16x32_bf16 v[22:25], v[142:145], v[192:195], v[22:25]
	v_mfma_f32_16x16x32_bf16 v[70:73], v[62:65], v[226:229], v[70:73]
	v_mfma_f32_16x16x32_bf16 v[66:69], v[142:145], v[226:229], v[66:69]
	v_mfma_f32_16x16x32_bf16 v[2:5], v[176:179], v[192:195], v[2:5]
	v_mfma_f32_16x16x32_bf16 v[38:41], v[176:179], v[234:237], v[6:9]
	s_setprio 0
	s_barrier
	s_add_i32 s83, s83, 2
	s_add_u32 s62, s62, 0x100
	s_addc_u32 s63, s63, 0
	s_cmp_gt_u32 s83, 61
	s_mov_b64 s[12:13], s[14:15]
	s_cbranch_scc0 .LBB0_933
	s_and_b64 vcc, exec, s[38:39]
	s_cbranch_vccz .LBB0_936
	s_barrier

; #define PG8_STAGE(bufoff, gbase, voff) do { const char* _gb = (const char*)(gbase); asm volatile("" : "+s"(_gb)); _Pragma("unroll") for (int _i = 0; _i < 2; ++_i) { asm volatile("" : "+v"((voff)[_i])); \
;         __builtin_amdgcn_global_load_lds((const unsigned*)(_gb + (voff)[_i]), (PG8_LAS unsigned*)(lds + (bufoff) + ldsw + _i * 8192), 16, 0, 0); } } while (0)
; #define PG8_LDA(dst, b, h) do { _Pragma("unroll") for (int m = 0; m < 4; ++m) _Pragma("unroll") for (int k = 0; k < 2; ++k) dst[m][k] = *(const PG8_LAS bf16x8*)(lds + PG8_SA(b, h) + aoff + m * 2048 + k * 1024); } while (0)
; #define PG8_LDB(dst, b, h) do { _Pragma("unroll") for (int n = 0; n < 2; ++n) _Pragma("unroll") for (int k = 0; k < 2; ++k) dst[n][k] = *(const PG8_LAS bf16x8*)(lds + PG8_SB(b, h) + boff + n * 2048 + k * 1024); } while (0)
; #define PG8_WAIT_V(n) asm volatile("s_waitcnt vmcnt(" #n ")" ::: "memory")
; #define PG8_WAIT_L(n) asm volatile("s_waitcnt lgkmcnt(" #n ")" ::: "memory")
; #define PG8_BAR __builtin_amdgcn_s_barrier()
; #define PG8_SCHED __builtin_amdgcn_sched_barrier(0)
; #define PG8_STAGE(bufoff, gbase, voff) do { const char* _gb = (const char*)(gbase); asm volatile("" : "+s"(_gb)); _Pragma("unroll") for (int _i = 0; _i < 2; ++_i) { asm volatile("" : "+v"((voff)[_i])); \
;         __builtin_amdgcn_global_load_lds((const unsigned*)(_gb + (voff)[_i]), (PG8_LAS unsigned*)(lds + (bufoff) + ldsw + _i * 8192), 16, 0, 0); } } while (0)
; #define PG8_WAIT_V(n) asm volatile("s_waitcnt vmcnt(" #n ")" ::: "memory")
; #define PG8_WAIT_L(n) asm volatile("s_waitcnt lgkmcnt(" #n ")" ::: "memory")
; template <class Epi, class Sched, bool ALIGN_EPI = false, bool SP2 = false>
; __device__ __forceinline__ void gemm_phase(PG8_LAS unsigned char* lds, const Gemm g, const Sched& S, const Epi& E) {
;     ...
;             if constexpr (SP2) {
;             PG8_LDB(B0, 0, 0); PG8_LDB(B1, 0, 1); PG8_SCHED; PG8_LDA(At, 0, 0); PG8_STAGE(PG8_SA(1, 1), a1 + hstep, voffA);
;             PG8_WAIT_V(8); PG8_WAIT_L(0); PG8_BAR; PG8_MMA2(0); PG8_BAR; PG8_SCHED;
;     ...
; #pragma unroll
;         for (int a = 0; a < 2; ++a)
; #pragma unroll
;             for (int b = 0; b < 2; ++b)
; #pragma unroll
;                 for (int m = 0; m < 4; ++m)
; #pragma unroll
;                     for (int n = 0; n < 2; ++n) acc[a][b][m][n] = (f32x4){0.f, 0.f, 0.f, 0.f};
;         cur = nxt; cA = nA; cB = nB; ++ui;
.LBB0_1124:
	s_add_u32 s51, s2, 0x100
	v_mov_b32_e32 v2, 0
	s_addc_u32 s52, s3, 0
	s_mov_b32 s53, -2
	s_waitcnt lgkmcnt(0)
	v_mov_b32_e32 v3, v2
	v_mov_b32_e32 v4, v2
	v_mov_b32_e32 v5, v2
	v_mov_b32_e32 v6, v2
	v_mov_b32_e32 v7, v2
	v_mov_b32_e32 v8, v2
	v_mov_b32_e32 v9, v2
	v_mov_b32_e32 v18, v2
	v_mov_b32_e32 v19, v2
	v_mov_b32_e32 v20, v2
	v_mov_b32_e32 v21, v2
	v_mov_b32_e32 v22, v2
	v_mov_b32_e32 v23, v2
	v_mov_b32_e32 v24, v2
	v_mov_b32_e32 v25, v2
	v_mov_b32_e32 v34, v2
	v_mov_b32_e32 v35, v2
	v_mov_b32_e32 v36, v2
	v_mov_b32_e32 v37, v2
	v_mov_b32_e32 v38, v2
	v_mov_b32_e32 v39, v2
	v_mov_b32_e32 v40, v2
	v_mov_b32_e32 v41, v2
	v_mov_b32_e32 v50, v2
	v_mov_b32_e32 v51, v2
	v_mov_b32_e32 v52, v2
	v_mov_b32_e32 v53, v2
	v_mov_b32_e32 v54, v2
	v_mov_b32_e32 v55, v2
	v_mov_b32_e32 v56, v2
	v_mov_b32_e32 v57, v2
	v_mov_b32_e32 v10, v2
	v_mov_b32_e32 v11, v2
	v_mov_b32_e32 v12, v2
	v_mov_b32_e32 v13, v2
	v_mov_b32_e32 v14, v2
	v_mov_b32_e32 v15, v2
	v_mov_b32_e32 v16, v2
	v_mov_b32_e32 v17, v2
	v_mov_b32_e32 v26, v2
	v_mov_b32_e32 v27, v2
	v_mov_b32_e32 v28, v2
	v_mov_b32_e32 v29, v2
	v_mov_b32_e32 v30, v2
	v_mov_b32_e32 v31, v2
	v_mov_b32_e32 v32, v2
	v_mov_b32_e32 v33, v2
	v_mov_b32_e32 v42, v2
	v_mov_b32_e32 v43, v2
	v_mov_b32_e32 v44, v2
	v_mov_b32_e32 v45, v2
	v_mov_b32_e32 v46, v2
	v_mov_b32_e32 v47, v2
	v_mov_b32_e32 v48, v2
	v_mov_b32_e32 v49, v2
	v_mov_b32_e32 v58, v2
	v_mov_b32_e32 v59, v2
	v_mov_b32_e32 v60, v2
	v_mov_b32_e32 v61, v2
	v_mov_b32_e32 v62, v2
	v_mov_b32_e32 v63, v2
	v_mov_b32_e32 v64, v2
	v_mov_b32_e32 v65, v2
	v_mov_b32_e32 v66, v2
	v_mov_b32_e32 v67, v2
	v_mov_b32_e32 v68, v2
	v_mov_b32_e32 v69, v2
	v_mov_b32_e32 v70, v2
	v_mov_b32_e32 v71, v2
	v_mov_b32_e32 v72, v2
	v_mov_b32_e32 v73, v2
	v_mov_b32_e32 v82, v2
	v_mov_b32_e32 v83, v2
	v_mov_b32_e32 v84, v2
	v_mov_b32_e32 v85, v2
	v_mov_b32_e32 v86, v2
	v_mov_b32_e32 v87, v2
	v_mov_b32_e32 v88, v2
	v_mov_b32_e32 v89, v2
	v_mov_b32_e32 v98, v2
	v_mov_b32_e32 v99, v2
	v_mov_b32_e32 v100, v2
	v_mov_b32_e32 v101, v2
	v_mov_b32_e32 v102, v2
	v_mov_b32_e32 v103, v2
	v_mov_b32_e32 v104, v2
	v_mov_b32_e32 v105, v2
	v_mov_b32_e32 v114, v2
	v_mov_b32_e32 v115, v2
	v_mov_b32_e32 v116, v2
	v_mov_b32_e32 v117, v2
	v_mov_b32_e32 v118, v2
	v_mov_b32_e32 v119, v2
	v_mov_b32_e32 v120, v2
	v_mov_b32_e32 v121, v2
	v_mov_b32_e32 v74, v2
	v_mov_b32_e32 v75, v2
	v_mov_b32_e32 v76, v2
	v_mov_b32_e32 v77, v2
	v_mov_b32_e32 v78, v2
	v_mov_b32_e32 v79, v2
	v_mov_b32_e32 v80, v2
	v_mov_b32_e32 v81, v2
	v_mov_b32_e32 v90, v2
	v_mov_b32_e32 v91, v2
	v_mov_b32_e32 v92, v2
	v_mov_b32_e32 v93, v2
	v_mov_b32_e32 v94, v2
	v_mov_b32_e32 v95, v2
	v_mov_b32_e32 v96, v2
	v_mov_b32_e32 v97, v2
	v_mov_b32_e32 v106, v2
	v_mov_b32_e32 v107, v2
	v_mov_b32_e32 v108, v2
	v_mov_b32_e32 v109, v2
	v_mov_b32_e32 v110, v2
	v_mov_b32_e32 v111, v2
	v_mov_b32_e32 v112, v2
	v_mov_b32_e32 v113, v2
	v_mov_b32_e32 v122, v2
	v_mov_b32_e32 v123, v2
	v_mov_b32_e32 v124, v2
	v_mov_b32_e32 v125, v2
	v_mov_b32_e32 v126, v2
	v_mov_b32_e32 v127, v2
	v_mov_b32_e32 v128, v2
	v_mov_b32_e32 v129, v2
	s_nop 0
.LBB0_1125:
	ds_read_b128 v[130:133], v162
	ds_read_b128 v[134:137], v162 offset:1024
	ds_read_b128 v[138:141], v162 offset:2048
	ds_read_b128 v[142:145], v162 offset:3072
	ds_read_b128 v[150:153], v163
	ds_read_b128 v[166:169], v163 offset:1024
	ds_read_b128 v[170:173], v163 offset:2048
	ds_read_b128 v[174:177], v163 offset:3072
	s_add_u32 s20, s16, 0x100
	s_addc_u32 s21, s17, 0
	s_cmpk_eq_i32 s53, 0xbc
	s_cselect_b32 s26, s6, s20
	s_cselect_b32 s27, s7, s21
	s_cselect_b32 s24, s18, s51
	s_cselect_b32 s25, s19, s52
	s_add_u32 s2, s26, 0x80
	s_addc_u32 s3, s27, 0
	s_add_u32 s16, s16, 0x300080
	s_addc_u32 s17, s17, 0
	s_add_i32 m0, s34, 0xc000
	ds_read_b128 v[178:181], v164
	ds_read_b128 v[182:185], v164 offset:1024
	ds_read_b128 v[186:189], v164 offset:2048
	ds_read_b128 v[190:193], v164 offset:3072
	ds_read_b128 v[194:197], v164 offset:4096
	ds_read_b128 v[198:201], v164 offset:5120
	ds_read_b128 v[202:205], v164 offset:6144
	ds_read_b128 v[206:209], v164 offset:7168
	s_nop 0
	global_load_lds_dwordx4 v1, s[16:17]
	s_add_i32 m0, s34, 0xe000
	s_nop 0
	global_load_lds_dwordx4 v157, s[16:17]
	s_waitcnt vmcnt(8)
	s_waitcnt lgkmcnt(0)
	s_setprio 1
	s_waitcnt lgkmcnt(0)
	s_barrier
	v_mfma_f32_16x16x32_bf16 v[126:129], v[130:133], v[178:181], v[126:129]
	v_mfma_f32_16x16x32_bf16 v[122:125], v[138:141], v[178:181], v[122:125]
	v_mfma_f32_16x16x32_bf16 v[110:113], v[130:133], v[186:189], v[110:113]
	v_mfma_f32_16x16x32_bf16 v[106:109], v[138:141], v[186:189], v[106:109]
	v_mfma_f32_16x16x32_bf16 v[94:97], v[130:133], v[194:197], v[94:97]
	v_mfma_f32_16x16x32_bf16 v[90:93], v[138:141], v[194:197], v[90:93]
	v_mfma_f32_16x16x32_bf16 v[78:81], v[130:133], v[202:205], v[78:81]
	v_mfma_f32_16x16x32_bf16 v[74:77], v[138:141], v[202:205], v[74:77]
	v_mfma_f32_16x16x32_bf16 v[118:121], v[150:153], v[178:181], v[118:121]
	v_mfma_f32_16x16x32_bf16 v[114:117], v[170:173], v[178:181], v[114:117]
	v_mfma_f32_16x16x32_bf16 v[102:105], v[150:153], v[186:189], v[102:105]
	v_mfma_f32_16x16x32_bf16 v[98:101], v[170:173], v[186:189], v[98:101]
	v_mfma_f32_16x16x32_bf16 v[86:89], v[150:153], v[194:197], v[86:89]
	v_mfma_f32_16x16x32_bf16 v[82:85], v[170:173], v[194:197], v[82:85]
	v_mfma_f32_16x16x32_bf16 v[70:73], v[150:153], v[202:205], v[70:73]
	v_mfma_f32_16x16x32_bf16 v[66:69], v[170:173], v[202:205], v[66:69]
	v_mfma_f32_16x16x32_bf16 v[126:129], v[134:137], v[182:185], v[126:129]
	v_mfma_f32_16x16x32_bf16 v[122:125], v[142:145], v[182:185], v[122:125]
	v_mfma_f32_16x16x32_bf16 v[110:113], v[134:137], v[190:193], v[110:113]
	v_mfma_f32_16x16x32_bf16 v[106:109], v[142:145], v[190:193], v[106:109]
	v_mfma_f32_16x16x32_bf16 v[94:97], v[134:137], v[198:201], v[94:97]
	v_mfma_f32_16x16x32_bf16 v[90:93], v[142:145], v[198:201], v[90:93]
	v_mfma_f32_16x16x32_bf16 v[78:81], v[134:137], v[206:209], v[78:81]
	v_mfma_f32_16x16x32_bf16 v[74:77], v[142:145], v[206:209], v[74:77]
	v_mfma_f32_16x16x32_bf16 v[118:121], v[166:169], v[182:185], v[118:121]
	v_mfma_f32_16x16x32_bf16 v[114:117], v[174:177], v[182:185], v[114:117]
	v_mfma_f32_16x16x32_bf16 v[102:105], v[166:169], v[190:193], v[102:105]
	v_mfma_f32_16x16x32_bf16 v[98:101], v[174:177], v[190:193], v[98:101]
	v_mfma_f32_16x16x32_bf16 v[86:89], v[166:169], v[198:201], v[86:89]
	v_mfma_f32_16x16x32_bf16 v[82:85], v[174:177], v[198:201], v[82:85]
	v_mfma_f32_16x16x32_bf16 v[70:73], v[166:169], v[206:209], v[70:73]
	v_mfma_f32_16x16x32_bf16 v[66:69], v[174:177], v[206:209], v[66:69]
	s_setprio 0
	s_barrier
; #define PG8_STAGE(bufoff, gbase, voff) do { const char* _gb = (const char*)(gbase); asm volatile("" : "+s"(_gb)); _Pragma("unroll") for (int _i = 0; _i < 2; ++_i) { asm volatile("" : "+v"((voff)[_i])); \
;         __builtin_amdgcn_global_load_lds((const unsigned*)(_gb + (voff)[_i]), (PG8_LAS unsigned*)(lds + (bufoff) + ldsw + _i * 8192), 16, 0, 0); } } while (0)
; #define PG8_LDA(dst, b, h) do { _Pragma("unroll") for (int m = 0; m < 4; ++m) _Pragma("unroll") for (int k = 0; k < 2; ++k) dst[m][k] = *(const PG8_LAS bf16x8*)(lds + PG8_SA(b, h) + aoff + m * 2048 + k * 1024); } while (0)
; #define PG8_LDB(dst, b, h) do { _Pragma("unroll") for (int n = 0; n < 2; ++n) _Pragma("unroll") for (int k = 0; k < 2; ++k) dst[n][k] = *(const PG8_LAS bf16x8*)(lds + PG8_SB(b, h) + boff + n * 2048 + k * 1024); } while (0)
; #define PG8_WAIT_V(n) asm volatile("s_waitcnt vmcnt(" #n ")" ::: "memory")
; #define PG8_WAIT_L(n) asm volatile("s_waitcnt lgkmcnt(" #n ")" ::: "memory")
; #define PG8_BAR __builtin_amdgcn_s_barrier()
; #define PG8_SCHED __builtin_amdgcn_sched_barrier(0)
; #define PG8_STAGE(bufoff, gbase, voff) do { const char* _gb = (const char*)(gbase); asm volatile("" : "+s"(_gb)); _Pragma("unroll") for (int _i = 0; _i < 2; ++_i) { asm volatile("" : "+v"((voff)[_i])); \
;         __builtin_amdgcn_global_load_lds((const unsigned*)(_gb + (voff)[_i]), (PG8_LAS unsigned*)(lds + (bufoff) + ldsw + _i * 8192), 16, 0, 0); } } while (0)
; #define PG8_LDA(dst, b, h) do { _Pragma("unroll") for (int m = 0; m < 4; ++m) _Pragma("unroll") for (int k = 0; k < 2; ++k) dst[m][k] = *(const PG8_LAS bf16x8*)(lds + PG8_SA(b, h) + aoff + m * 2048 + k * 1024); } while (0)
; #define PG8_WAIT_V(n) asm volatile("s_waitcnt vmcnt(" #n ")" ::: "memory")
; #define PG8_WAIT_L(n) asm volatile("s_waitcnt lgkmcnt(" #n ")" ::: "memory")
; template <class Epi, class Sched, bool ALIGN_EPI = false, bool SP2 = false>
; __device__ __forceinline__ void gemm_phase(PG8_LAS unsigned char* lds, const Gemm g, const Sched& S, const Epi& E) {
;     ...
;             PG8_LDA(At, 0, 1); PG8_STAGE(PG8_SB(0, 0), b2, voffB); PG8_STAGE(PG8_SB(0, 1), b2 + hstep, voffB); PG8_STAGE(PG8_SA(0, 0), a2, voffA);
;             PG8_WAIT_V(8); PG8_WAIT_L(0); PG8_BAR; PG8_MMA2(1); PG8_BAR; PG8_SCHED;
;             PG8_LDB(B0, 1, 0); PG8_LDB(B1, 1, 1); PG8_SCHED; PG8_LDA(At, 1, 0); PG8_STAGE(PG8_SA(0, 1), a2 + hstep, voffA);
	s_add_i32 s54, s43, s33
	s_mov_b64 s[16:17], s[24:25]
	s_mov_b32 m0, s54
	ds_read_b128 v[178:181], v164 offset:16384
	ds_read_b128 v[182:185], v164 offset:17408
	ds_read_b128 v[186:189], v164 offset:18432
	ds_read_b128 v[190:193], v164 offset:19456
	ds_read_b128 v[194:197], v164 offset:20480
	ds_read_b128 v[198:201], v164 offset:21504
	ds_read_b128 v[202:205], v164 offset:22528
	ds_read_b128 v[206:209], v164 offset:23552
	s_nop 0
	global_load_lds_dwordx4 v156, s[16:17]
	s_add_i32 m0, s54, 0x2000
	s_nop 0
	global_load_lds_dwordx4 v158, s[16:17]
	s_add_u32 s16, s24, 0x300000
	s_addc_u32 s17, s25, 0
	s_add_i32 s54, s44, s33
	s_mov_b32 m0, s54
	s_nop 0
	global_load_lds_dwordx4 v156, s[16:17]
	s_add_i32 m0, s54, 0x2000
	s_nop 0
	global_load_lds_dwordx4 v158, s[16:17]
	s_mov_b64 s[16:17], s[26:27]
	s_mov_b32 m0, s34
	s_nop 0
	global_load_lds_dwordx4 v1, s[16:17]
	s_mov_b32 m0, s35
	s_nop 0
	global_load_lds_dwordx4 v157, s[16:17]
	s_waitcnt vmcnt(8)
	s_waitcnt lgkmcnt(0)
	s_setprio 1
	s_waitcnt lgkmcnt(0)
	s_barrier
	v_mfma_f32_16x16x32_bf16 v[62:65], v[130:133], v[178:181], v[62:65]
	v_mfma_f32_16x16x32_bf16 v[58:61], v[138:141], v[178:181], v[58:61]
	v_mfma_f32_16x16x32_bf16 v[46:49], v[130:133], v[186:189], v[46:49]
	v_mfma_f32_16x16x32_bf16 v[42:45], v[138:141], v[186:189], v[42:45]
	v_mfma_f32_16x16x32_bf16 v[30:33], v[130:133], v[194:197], v[30:33]
	v_mfma_f32_16x16x32_bf16 v[26:29], v[138:141], v[194:197], v[26:29]
	v_mfma_f32_16x16x32_bf16 v[14:17], v[130:133], v[202:205], v[14:17]
	v_mfma_f32_16x16x32_bf16 v[10:13], v[138:141], v[202:205], v[10:13]
	v_mfma_f32_16x16x32_bf16 v[54:57], v[150:153], v[178:181], v[54:57]
	v_mfma_f32_16x16x32_bf16 v[50:53], v[170:173], v[178:181], v[50:53]
	v_mfma_f32_16x16x32_bf16 v[38:41], v[150:153], v[186:189], v[38:41]
	v_mfma_f32_16x16x32_bf16 v[34:37], v[170:173], v[186:189], v[34:37]
	v_mfma_f32_16x16x32_bf16 v[22:25], v[150:153], v[194:197], v[22:25]
	v_mfma_f32_16x16x32_bf16 v[18:21], v[170:173], v[194:197], v[18:21]
	v_mfma_f32_16x16x32_bf16 v[6:9], v[150:153], v[202:205], v[6:9]
	v_mfma_f32_16x16x32_bf16 v[2:5], v[170:173], v[202:205], v[2:5]
	v_mfma_f32_16x16x32_bf16 v[62:65], v[134:137], v[182:185], v[62:65]
	v_mfma_f32_16x16x32_bf16 v[58:61], v[142:145], v[182:185], v[58:61]
	v_mfma_f32_16x16x32_bf16 v[46:49], v[134:137], v[190:193], v[46:49]
	v_mfma_f32_16x16x32_bf16 v[42:45], v[142:145], v[190:193], v[42:45]
	v_mfma_f32_16x16x32_bf16 v[30:33], v[134:137], v[198:201], v[30:33]
	v_mfma_f32_16x16x32_bf16 v[26:29], v[142:145], v[198:201], v[26:29]
	v_mfma_f32_16x16x32_bf16 v[14:17], v[134:137], v[206:209], v[14:17]
	v_mfma_f32_16x16x32_bf16 v[10:13], v[142:145], v[206:209], v[10:13]
	v_mfma_f32_16x16x32_bf16 v[54:57], v[166:169], v[182:185], v[54:57]
	v_mfma_f32_16x16x32_bf16 v[50:53], v[174:177], v[182:185], v[50:53]
	v_mfma_f32_16x16x32_bf16 v[38:41], v[166:169], v[190:193], v[38:41]
	v_mfma_f32_16x16x32_bf16 v[34:37], v[174:177], v[190:193], v[34:37]
	v_mfma_f32_16x16x32_bf16 v[22:25], v[166:169], v[198:201], v[22:25]
	v_mfma_f32_16x16x32_bf16 v[18:21], v[174:177], v[198:201], v[18:21]
	v_mfma_f32_16x16x32_bf16 v[6:9], v[166:169], v[206:209], v[6:9]
	v_mfma_f32_16x16x32_bf16 v[2:5], v[174:177], v[206:209], v[2:5]
	s_setprio 0
	s_barrier
	s_add_i32 s54, 0, 0x18000
	s_add_i32 s55, 0, 0x1c000
	v_add_u32_e32 v142, s54, v160
	v_add_u32_e32 v154, s55, v160
	ds_read_b128 v[130:133], v142
	ds_read_b128 v[134:137], v142 offset:1024
	ds_read_b128 v[138:141], v142 offset:2048
	ds_read_b128 v[142:145], v142 offset:3072
	ds_read_b128 v[150:153], v154
	ds_read_b128 v[166:169], v154 offset:1024
	ds_read_b128 v[170:173], v154 offset:2048
	ds_read_b128 v[174:177], v154 offset:3072
	s_add_u32 s16, s26, 0x300000
	s_addc_u32 s17, s27, 0
	s_mov_b32 m0, s36
	ds_read_b128 v[178:181], v164 offset:32768
	ds_read_b128 v[182:185], v164 offset:33792
	ds_read_b128 v[186:189], v164 offset:34816
	ds_read_b128 v[190:193], v164 offset:35840
	ds_read_b128 v[194:197], v164 offset:36864
	ds_read_b128 v[198:201], v164 offset:37888
	ds_read_b128 v[202:205], v164 offset:38912
	ds_read_b128 v[206:209], v164 offset:39936
	s_nop 0
	global_load_lds_dwordx4 v1, s[16:17]
	s_mov_b32 m0, s37
	s_nop 0
	global_load_lds_dwordx4 v157, s[16:17]
	s_waitcnt vmcnt(8)
	s_waitcnt lgkmcnt(0)
	s_setprio 1
	s_waitcnt lgkmcnt(0)
	s_barrier
; #define PG8_STAGE(bufoff, gbase, voff) do { const char* _gb = (const char*)(gbase); asm volatile("" : "+s"(_gb)); _Pragma("unroll") for (int _i = 0; _i < 2; ++_i) { asm volatile("" : "+v"((voff)[_i])); \
;         __builtin_amdgcn_global_load_lds((const unsigned*)(_gb + (voff)[_i]), (PG8_LAS unsigned*)(lds + (bufoff) + ldsw + _i * 8192), 16, 0, 0); } } while (0)
; #define PG8_LDA(dst, b, h) do { _Pragma("unroll") for (int m = 0; m < 4; ++m) _Pragma("unroll") for (int k = 0; k < 2; ++k) dst[m][k] = *(const PG8_LAS bf16x8*)(lds + PG8_SA(b, h) + aoff + m * 2048 + k * 1024); } while (0)
; #define PG8_WAIT_V(n) asm volatile("s_waitcnt vmcnt(" #n ")" ::: "memory")
; #define PG8_WAIT_L(n) asm volatile("s_waitcnt lgkmcnt(" #n ")" ::: "memory")
; #define PG8_BAR __builtin_amdgcn_s_barrier()
; #define PG8_SCHED __builtin_amdgcn_sched_barrier(0)
; #define PG8_STAGE(bufoff, gbase, voff) do { const char* _gb = (const char*)(gbase); asm volatile("" : "+s"(_gb)); _Pragma("unroll") for (int _i = 0; _i < 2; ++_i) { asm volatile("" : "+v"((voff)[_i])); \
;         __builtin_amdgcn_global_load_lds((const unsigned*)(_gb + (voff)[_i]), (PG8_LAS unsigned*)(lds + (bufoff) + ldsw + _i * 8192), 16, 0, 0); } } while (0)
; #define PG8_LDA(dst, b, h) do { _Pragma("unroll") for (int m = 0; m < 4; ++m) _Pragma("unroll") for (int k = 0; k < 2; ++k) dst[m][k] = *(const PG8_LAS bf16x8*)(lds + PG8_SA(b, h) + aoff + m * 2048 + k * 1024); } while (0)
; #define PG8_WAIT_V(n) asm volatile("s_waitcnt vmcnt(" #n ")" ::: "memory")
; #define PG8_WAIT_L(n) asm volatile("s_waitcnt lgkmcnt(" #n ")" ::: "memory")
; #define PG8_BAR __builtin_amdgcn_s_barrier()
; #define PG8_SCHED __builtin_amdgcn_sched_barrier(0)
; template <class Epi, class Sched, bool ALIGN_EPI = false, bool SP2 = false>
; __device__ __forceinline__ void gemm_phase(PG8_LAS unsigned char* lds, const Gemm g, const Sched& S, const Epi& E) {
;     ...
;             PG8_WAIT_V(8); PG8_WAIT_L(0); PG8_BAR; PG8_MMA2(0); PG8_BAR; PG8_SCHED;
;             PG8_LDA(At, 1, 1); PG8_STAGE(PG8_SB(1, 0), b3, voffB); PG8_STAGE(PG8_SB(1, 1), b3 + hstep, voffB); PG8_STAGE(PG8_SA(1, 0), a3, voffA);
;             PG8_WAIT_V(8); PG8_WAIT_L(0); PG8_BAR; PG8_MMA2(1); PG8_BAR; PG8_SCHED;
	v_mfma_f32_16x16x32_bf16 v[126:129], v[130:133], v[178:181], v[126:129]
	v_mfma_f32_16x16x32_bf16 v[122:125], v[138:141], v[178:181], v[122:125]
	v_mfma_f32_16x16x32_bf16 v[110:113], v[130:133], v[186:189], v[110:113]
	v_mfma_f32_16x16x32_bf16 v[106:109], v[138:141], v[186:189], v[106:109]
	v_mfma_f32_16x16x32_bf16 v[94:97], v[130:133], v[194:197], v[94:97]
	v_mfma_f32_16x16x32_bf16 v[90:93], v[138:141], v[194:197], v[90:93]
	v_mfma_f32_16x16x32_bf16 v[78:81], v[130:133], v[202:205], v[78:81]
	v_mfma_f32_16x16x32_bf16 v[74:77], v[138:141], v[202:205], v[74:77]
	v_mfma_f32_16x16x32_bf16 v[118:121], v[150:153], v[178:181], v[118:121]
	v_mfma_f32_16x16x32_bf16 v[114:117], v[170:173], v[178:181], v[114:117]
	v_mfma_f32_16x16x32_bf16 v[102:105], v[150:153], v[186:189], v[102:105]
	v_mfma_f32_16x16x32_bf16 v[98:101], v[170:173], v[186:189], v[98:101]
	v_mfma_f32_16x16x32_bf16 v[86:89], v[150:153], v[194:197], v[86:89]
	v_mfma_f32_16x16x32_bf16 v[82:85], v[170:173], v[194:197], v[82:85]
	v_mfma_f32_16x16x32_bf16 v[70:73], v[150:153], v[202:205], v[70:73]
	v_mfma_f32_16x16x32_bf16 v[66:69], v[170:173], v[202:205], v[66:69]
	v_mfma_f32_16x16x32_bf16 v[126:129], v[134:137], v[182:185], v[126:129]
	v_mfma_f32_16x16x32_bf16 v[122:125], v[142:145], v[182:185], v[122:125]
	v_mfma_f32_16x16x32_bf16 v[110:113], v[134:137], v[190:193], v[110:113]
	v_mfma_f32_16x16x32_bf16 v[106:109], v[142:145], v[190:193], v[106:109]
	v_mfma_f32_16x16x32_bf16 v[94:97], v[134:137], v[198:201], v[94:97]
	v_mfma_f32_16x16x32_bf16 v[90:93], v[142:145], v[198:201], v[90:93]
	v_mfma_f32_16x16x32_bf16 v[78:81], v[134:137], v[206:209], v[78:81]
	v_mfma_f32_16x16x32_bf16 v[74:77], v[142:145], v[206:209], v[74:77]
	v_mfma_f32_16x16x32_bf16 v[118:121], v[166:169], v[182:185], v[118:121]
	v_mfma_f32_16x16x32_bf16 v[114:117], v[174:177], v[182:185], v[114:117]
	v_mfma_f32_16x16x32_bf16 v[102:105], v[166:169], v[190:193], v[102:105]
	v_mfma_f32_16x16x32_bf16 v[98:101], v[174:177], v[190:193], v[98:101]
	v_mfma_f32_16x16x32_bf16 v[86:89], v[166:169], v[198:201], v[86:89]
	v_mfma_f32_16x16x32_bf16 v[82:85], v[174:177], v[198:201], v[82:85]
	v_mfma_f32_16x16x32_bf16 v[70:73], v[166:169], v[206:209], v[70:73]
	v_mfma_f32_16x16x32_bf16 v[66:69], v[174:177], v[206:209], v[66:69]
	s_setprio 0
	s_barrier
	s_nop 0
	s_add_u32 s16, s24, 0x80
	s_addc_u32 s17, s25, 0
	s_add_i32 s26, s54, s33
	s_mov_b32 m0, s26
	ds_read_b128 v[178:181], v164 offset:49152
	ds_read_b128 v[182:185], v164 offset:50176
	ds_read_b128 v[186:189], v164 offset:51200
	ds_read_b128 v[190:193], v164 offset:52224
	ds_read_b128 v[194:197], v164 offset:53248
	ds_read_b128 v[198:201], v164 offset:54272
	ds_read_b128 v[202:205], v164 offset:55296
	ds_read_b128 v[206:209], v164 offset:56320
	s_nop 0
	global_load_lds_dwordx4 v156, s[16:17]
	s_add_i32 m0, s26, 0x2000
	s_nop 0
	global_load_lds_dwordx4 v158, s[16:17]
	s_add_u32 s16, s24, 0x300080
	s_addc_u32 s17, s25, 0
	s_add_i32 s24, s55, s33
	s_mov_b32 m0, s24
	s_nop 0
	global_load_lds_dwordx4 v156, s[16:17]
	s_add_i32 m0, s24, 0x2000
	s_nop 0
	global_load_lds_dwordx4 v158, s[16:17]
	s_mov_b32 m0, s39
	s_nop 0
	global_load_lds_dwordx4 v1, s[2:3]
	s_mov_b32 m0, s40
	s_nop 0
	global_load_lds_dwordx4 v157, s[2:3]
	s_waitcnt vmcnt(8)
	s_waitcnt lgkmcnt(0)
	s_setprio 1
	s_waitcnt lgkmcnt(0)
	s_barrier
	v_mfma_f32_16x16x32_bf16 v[62:65], v[130:133], v[178:181], v[62:65]
	v_mfma_f32_16x16x32_bf16 v[58:61], v[138:141], v[178:181], v[58:61]
	v_mfma_f32_16x16x32_bf16 v[46:49], v[130:133], v[186:189], v[46:49]
	v_mfma_f32_16x16x32_bf16 v[42:45], v[138:141], v[186:189], v[42:45]
	v_mfma_f32_16x16x32_bf16 v[30:33], v[130:133], v[194:197], v[30:33]
	v_mfma_f32_16x16x32_bf16 v[26:29], v[138:141], v[194:197], v[26:29]
	v_mfma_f32_16x16x32_bf16 v[14:17], v[130:133], v[202:205], v[14:17]
	v_mfma_f32_16x16x32_bf16 v[10:13], v[138:141], v[202:205], v[10:13]
	v_mfma_f32_16x16x32_bf16 v[54:57], v[150:153], v[178:181], v[54:57]
	v_mfma_f32_16x16x32_bf16 v[50:53], v[170:173], v[178:181], v[50:53]
	v_mfma_f32_16x16x32_bf16 v[38:41], v[150:153], v[186:189], v[38:41]
	v_mfma_f32_16x16x32_bf16 v[34:37], v[170:173], v[186:189], v[34:37]
	v_mfma_f32_16x16x32_bf16 v[22:25], v[150:153], v[194:197], v[22:25]
	v_mfma_f32_16x16x32_bf16 v[18:21], v[170:173], v[194:197], v[18:21]
	v_mfma_f32_16x16x32_bf16 v[6:9], v[150:153], v[202:205], v[6:9]
	v_mfma_f32_16x16x32_bf16 v[2:5], v[170:173], v[202:205], v[2:5]
	v_mfma_f32_16x16x32_bf16 v[62:65], v[134:137], v[182:185], v[62:65]
	v_mfma_f32_16x16x32_bf16 v[58:61], v[142:145], v[182:185], v[58:61]
	v_mfma_f32_16x16x32_bf16 v[46:49], v[134:137], v[190:193], v[46:49]
	v_mfma_f32_16x16x32_bf16 v[42:45], v[142:145], v[190:193], v[42:45]
	v_mfma_f32_16x16x32_bf16 v[30:33], v[134:137], v[198:201], v[30:33]
	v_mfma_f32_16x16x32_bf16 v[26:29], v[142:145], v[198:201], v[26:29]
	v_mfma_f32_16x16x32_bf16 v[14:17], v[134:137], v[206:209], v[14:17]
	v_mfma_f32_16x16x32_bf16 v[10:13], v[142:145], v[206:209], v[10:13]
	v_mfma_f32_16x16x32_bf16 v[54:57], v[166:169], v[182:185], v[54:57]
	v_mfma_f32_16x16x32_bf16 v[50:53], v[174:177], v[182:185], v[50:53]
	v_mfma_f32_16x16x32_bf16 v[38:41], v[166:169], v[190:193], v[38:41]
	v_mfma_f32_16x16x32_bf16 v[34:37], v[174:177], v[190:193], v[34:37]
	v_mfma_f32_16x16x32_bf16 v[22:25], v[166:169], v[198:201], v[22:25]
	v_mfma_f32_16x16x32_bf16 v[18:21], v[174:177], v[198:201], v[18:21]
	v_mfma_f32_16x16x32_bf16 v[6:9], v[166:169], v[206:209], v[6:9]
	v_mfma_f32_16x16x32_bf16 v[2:5], v[174:177], v[206:209], v[2:5]
	s_setprio 0
	s_barrier
	s_add_i32 s53, s53, 2
	s_add_u32 s51, s51, 0x100
	s_addc_u32 s52, s52, 0
	s_cmpk_gt_u32 s53, 0xbd
	s_mov_b64 s[16:17], s[20:21]
	s_cbranch_scc0 .LBB0_1125
	s_and_b64 vcc, exec, s[14:15]
	s_cbranch_vccz .LBB0_1128
	s_barrier

; #define PG8_STAGE(bufoff, gbase, voff) do { const char* _gb = (const char*)(gbase); asm volatile("" : "+s"(_gb)); _Pragma("unroll") for (int _i = 0; _i < 2; ++_i) { asm volatile("" : "+v"((voff)[_i])); \
;         __builtin_amdgcn_global_load_lds((const unsigned*)(_gb + (voff)[_i]), (PG8_LAS unsigned*)(lds + (bufoff) + ldsw + _i * 8192), 16, 0, 0); } } while (0)
; #define PG8_LDA(dst, b, h) do { _Pragma("unroll") for (int m = 0; m < 4; ++m) _Pragma("unroll") for (int k = 0; k < 2; ++k) dst[m][k] = *(const PG8_LAS bf16x8*)(lds + PG8_SA(b, h) + aoff + m * 2048 + k * 1024); } while (0)
; #define PG8_LDB(dst, b, h) do { _Pragma("unroll") for (int n = 0; n < 2; ++n) _Pragma("unroll") for (int k = 0; k < 2; ++k) dst[n][k] = *(const PG8_LAS bf16x8*)(lds + PG8_SB(b, h) + boff + n * 2048 + k * 1024); } while (0)
; #define PG8_WAIT_V(n) asm volatile("s_waitcnt vmcnt(" #n ")" ::: "memory")
; #define PG8_WAIT_L(n) asm volatile("s_waitcnt lgkmcnt(" #n ")" ::: "memory")
; #define PG8_BAR __builtin_amdgcn_s_barrier()
; #define PG8_SCHED __builtin_amdgcn_sched_barrier(0)
; #define PG8_STAGE(bufoff, gbase, voff) do { const char* _gb = (const char*)(gbase); asm volatile("" : "+s"(_gb)); _Pragma("unroll") for (int _i = 0; _i < 2; ++_i) { asm volatile("" : "+v"((voff)[_i])); \
;         __builtin_amdgcn_global_load_lds((const unsigned*)(_gb + (voff)[_i]), (PG8_LAS unsigned*)(lds + (bufoff) + ldsw + _i * 8192), 16, 0, 0); } } while (0)
; #define PG8_LDA(dst, b, h) do { _Pragma("unroll") for (int m = 0; m < 4; ++m) _Pragma("unroll") for (int k = 0; k < 2; ++k) dst[m][k] = *(const PG8_LAS bf16x8*)(lds + PG8_SA(b, h) + aoff + m * 2048 + k * 1024); } while (0)
; #define PG8_BAR __builtin_amdgcn_s_barrier()
; template <class Epi, class Sched, bool ALIGN_EPI = false, bool SP2 = false>
; __device__ __forceinline__ void gemm_phase(PG8_LAS unsigned char* lds, const Gemm g, const Sched& S, const Epi& E) {
;     ...
;             if constexpr (SP2) {
;             PG8_LDB(B0, 0, 0); PG8_LDB(B1, 0, 1); PG8_SCHED; PG8_LDA(At, 0, 0); PG8_STAGE(PG8_SA(1, 1), a1 + hstep, voffA);
;             PG8_WAIT_V(8); PG8_WAIT_L(0); PG8_BAR; PG8_MMA2(0); PG8_BAR; PG8_SCHED;
;             PG8_LDA(At, 0, 1); PG8_STAGE(PG8_SB(0, 0), b2, voffB); PG8_STAGE(PG8_SB(0, 1), b2 + hstep, voffB); PG8_STAGE(PG8_SA(0, 0), a2, voffA);
;             PG8_WAIT_V(8); PG8_WAIT_L(0); PG8_BAR; PG8_MMA2(1); PG8_BAR; PG8_SCHED;
.LBB0_1217:
	ds_read_b128 v[128:131], v175
	ds_read_b128 v[132:135], v175 offset:1024
	ds_read_b128 v[136:139], v175 offset:2048
	ds_read_b128 v[140:143], v175 offset:3072
	ds_read_b128 v[152:155], v176
	ds_read_b128 v[156:159], v176 offset:1024
	ds_read_b128 v[160:163], v176 offset:2048
	ds_read_b128 v[184:187], v176 offset:3072
	s_add_u32 s28, s6, 0x100
	s_addc_u32 s29, s7, 0
	s_cmpk_eq_i32 s58, 0xbc
	s_cselect_b32 s36, s57, s28
	s_cselect_b32 s37, s56, s29
	s_cselect_b32 s34, s8, s4
	s_cselect_b32 s35, s9, s5
	s_add_u32 s30, s36, 0x80
	s_addc_u32 s31, s37, 0
	s_add_u32 s6, s6, 0x300080
	s_addc_u32 s7, s7, 0
	s_add_i32 m0, s41, 0xc000
	ds_read_b128 v[188:191], v177
	ds_read_b128 v[192:195], v177 offset:1024
	ds_read_b128 v[196:199], v177 offset:2048
	ds_read_b128 v[200:203], v177 offset:3072
	ds_read_b128 v[204:207], v177 offset:4096
	ds_read_b128 v[208:211], v177 offset:5120
	ds_read_b128 v[212:215], v177 offset:6144
	ds_read_b128 v[216:219], v177 offset:7168
	s_nop 0
	global_load_lds_dwordx4 v167, s[6:7]
	s_add_i32 m0, s41, 0xe000
	s_nop 0
	global_load_lds_dwordx4 v171, s[6:7]
	s_waitcnt vmcnt(8)
	s_waitcnt lgkmcnt(0)
	s_setprio 1
	s_waitcnt lgkmcnt(0)
	s_barrier
	v_mfma_f32_16x16x32_bf16 v[124:127], v[128:131], v[188:191], v[124:127]
	v_mfma_f32_16x16x32_bf16 v[120:123], v[136:139], v[188:191], v[120:123]
	v_mfma_f32_16x16x32_bf16 v[108:111], v[128:131], v[196:199], v[108:111]
	v_mfma_f32_16x16x32_bf16 v[104:107], v[136:139], v[196:199], v[104:107]
	v_mfma_f32_16x16x32_bf16 v[92:95], v[128:131], v[204:207], v[92:95]
	v_mfma_f32_16x16x32_bf16 v[88:91], v[136:139], v[204:207], v[88:91]
	v_mfma_f32_16x16x32_bf16 v[76:79], v[128:131], v[212:215], v[76:79]
	v_mfma_f32_16x16x32_bf16 v[72:75], v[136:139], v[212:215], v[72:75]
	v_mfma_f32_16x16x32_bf16 v[116:119], v[152:155], v[188:191], v[116:119]
	v_mfma_f32_16x16x32_bf16 v[112:115], v[160:163], v[188:191], v[112:115]
	v_mfma_f32_16x16x32_bf16 v[100:103], v[152:155], v[196:199], v[100:103]
	v_mfma_f32_16x16x32_bf16 v[96:99], v[160:163], v[196:199], v[96:99]
	v_mfma_f32_16x16x32_bf16 v[84:87], v[152:155], v[204:207], v[84:87]
	v_mfma_f32_16x16x32_bf16 v[80:83], v[160:163], v[204:207], v[80:83]
	v_mfma_f32_16x16x32_bf16 v[68:71], v[152:155], v[212:215], v[68:71]
	v_mfma_f32_16x16x32_bf16 v[64:67], v[160:163], v[212:215], v[64:67]
	v_mfma_f32_16x16x32_bf16 v[124:127], v[132:135], v[192:195], v[124:127]
	v_mfma_f32_16x16x32_bf16 v[120:123], v[140:143], v[192:195], v[120:123]
	v_mfma_f32_16x16x32_bf16 v[108:111], v[132:135], v[200:203], v[108:111]
	v_mfma_f32_16x16x32_bf16 v[104:107], v[140:143], v[200:203], v[104:107]
	v_mfma_f32_16x16x32_bf16 v[92:95], v[132:135], v[208:211], v[92:95]
	v_mfma_f32_16x16x32_bf16 v[88:91], v[140:143], v[208:211], v[88:91]
	v_mfma_f32_16x16x32_bf16 v[76:79], v[132:135], v[216:219], v[76:79]
	v_mfma_f32_16x16x32_bf16 v[72:75], v[140:143], v[216:219], v[72:75]
	v_mfma_f32_16x16x32_bf16 v[116:119], v[156:159], v[192:195], v[116:119]
	v_mfma_f32_16x16x32_bf16 v[112:115], v[184:187], v[192:195], v[112:115]
	v_mfma_f32_16x16x32_bf16 v[100:103], v[156:159], v[200:203], v[100:103]
	v_mfma_f32_16x16x32_bf16 v[96:99], v[184:187], v[200:203], v[96:99]
	v_mfma_f32_16x16x32_bf16 v[84:87], v[156:159], v[208:211], v[84:87]
	v_mfma_f32_16x16x32_bf16 v[80:83], v[184:187], v[208:211], v[80:83]
	v_mfma_f32_16x16x32_bf16 v[68:71], v[156:159], v[216:219], v[68:71]
	v_mfma_f32_16x16x32_bf16 v[64:67], v[184:187], v[216:219], v[64:67]
	s_setprio 0
	s_barrier
	s_add_i32 s59, s49, s39
	s_mov_b64 s[6:7], s[34:35]
	s_mov_b32 m0, s59
	ds_read_b128 v[188:191], v177 offset:16384
	ds_read_b128 v[192:195], v177 offset:17408
	ds_read_b128 v[196:199], v177 offset:18432
	ds_read_b128 v[200:203], v177 offset:19456
	ds_read_b128 v[204:207], v177 offset:20480
	ds_read_b128 v[208:211], v177 offset:21504
	ds_read_b128 v[212:215], v177 offset:22528
	ds_read_b128 v[216:219], v177 offset:23552
	s_nop 0
	global_load_lds_dwordx4 v169, s[6:7]
	s_add_i32 m0, s59, 0x2000
	s_nop 0
	global_load_lds_dwordx4 v172, s[6:7]
	s_add_u32 s6, s34, 0x300000
	s_addc_u32 s7, s35, 0
	s_add_i32 s59, s50, s39
	s_mov_b32 m0, s59
	s_nop 0
	global_load_lds_dwordx4 v169, s[6:7]
	s_add_i32 m0, s59, 0x2000
	s_nop 0
	global_load_lds_dwordx4 v172, s[6:7]
	s_mov_b64 s[6:7], s[36:37]
	s_mov_b32 m0, s41
	s_nop 0
	global_load_lds_dwordx4 v167, s[6:7]
	s_mov_b32 m0, s42
	s_nop 0
	global_load_lds_dwordx4 v171, s[6:7]
	s_waitcnt vmcnt(8)
	s_waitcnt lgkmcnt(0)
	s_setprio 1
	s_waitcnt lgkmcnt(0)
	s_barrier
	v_mfma_f32_16x16x32_bf16 v[60:63], v[128:131], v[188:191], v[60:63]
	v_mfma_f32_16x16x32_bf16 v[56:59], v[136:139], v[188:191], v[56:59]
	v_mfma_f32_16x16x32_bf16 v[44:47], v[128:131], v[196:199], v[44:47]
	v_mfma_f32_16x16x32_bf16 v[40:43], v[136:139], v[196:199], v[40:43]
	v_mfma_f32_16x16x32_bf16 v[28:31], v[128:131], v[204:207], v[28:31]
	v_mfma_f32_16x16x32_bf16 v[24:27], v[136:139], v[204:207], v[24:27]
	v_mfma_f32_16x16x32_bf16 v[12:15], v[128:131], v[212:215], v[12:15]
	v_mfma_f32_16x16x32_bf16 v[8:11], v[136:139], v[212:215], v[8:11]
	v_mfma_f32_16x16x32_bf16 v[52:55], v[152:155], v[188:191], v[52:55]
	v_mfma_f32_16x16x32_bf16 v[48:51], v[160:163], v[188:191], v[48:51]
	v_mfma_f32_16x16x32_bf16 v[36:39], v[152:155], v[196:199], v[36:39]
	v_mfma_f32_16x16x32_bf16 v[32:35], v[160:163], v[196:199], v[32:35]
	v_mfma_f32_16x16x32_bf16 v[20:23], v[152:155], v[204:207], v[20:23]
	v_mfma_f32_16x16x32_bf16 v[16:19], v[160:163], v[204:207], v[16:19]
	v_mfma_f32_16x16x32_bf16 v[4:7], v[152:155], v[212:215], v[4:7]
	v_mfma_f32_16x16x32_bf16 v[0:3], v[160:163], v[212:215], v[0:3]
	v_mfma_f32_16x16x32_bf16 v[60:63], v[132:135], v[192:195], v[60:63]
	v_mfma_f32_16x16x32_bf16 v[56:59], v[140:143], v[192:195], v[56:59]
	v_mfma_f32_16x16x32_bf16 v[44:47], v[132:135], v[200:203], v[44:47]
	v_mfma_f32_16x16x32_bf16 v[40:43], v[140:143], v[200:203], v[40:43]
	v_mfma_f32_16x16x32_bf16 v[28:31], v[132:135], v[208:211], v[28:31]
	v_mfma_f32_16x16x32_bf16 v[24:27], v[140:143], v[208:211], v[24:27]
	v_mfma_f32_16x16x32_bf16 v[12:15], v[132:135], v[216:219], v[12:15]
	v_mfma_f32_16x16x32_bf16 v[8:11], v[140:143], v[216:219], v[8:11]
	v_mfma_f32_16x16x32_bf16 v[52:55], v[156:159], v[192:195], v[52:55]
	v_mfma_f32_16x16x32_bf16 v[48:51], v[184:187], v[192:195], v[48:51]
	v_mfma_f32_16x16x32_bf16 v[36:39], v[156:159], v[200:203], v[36:39]
	v_mfma_f32_16x16x32_bf16 v[32:35], v[184:187], v[200:203], v[32:35]
	v_mfma_f32_16x16x32_bf16 v[20:23], v[156:159], v[208:211], v[20:23]
	v_mfma_f32_16x16x32_bf16 v[16:19], v[184:187], v[208:211], v[16:19]
	v_mfma_f32_16x16x32_bf16 v[4:7], v[156:159], v[216:219], v[4:7]
	v_mfma_f32_16x16x32_bf16 v[0:3], v[184:187], v[216:219], v[0:3]
	s_setprio 0
	s_barrier
; #define PG8_STAGE(bufoff, gbase, voff) do { const char* _gb = (const char*)(gbase); asm volatile("" : "+s"(_gb)); _Pragma("unroll") for (int _i = 0; _i < 2; ++_i) { asm volatile("" : "+v"((voff)[_i])); \
;         __builtin_amdgcn_global_load_lds((const unsigned*)(_gb + (voff)[_i]), (PG8_LAS unsigned*)(lds + (bufoff) + ldsw + _i * 8192), 16, 0, 0); } } while (0)
; #define PG8_LDA(dst, b, h) do { _Pragma("unroll") for (int m = 0; m < 4; ++m) _Pragma("unroll") for (int k = 0; k < 2; ++k) dst[m][k] = *(const PG8_LAS bf16x8*)(lds + PG8_SA(b, h) + aoff + m * 2048 + k * 1024); } while (0)
; #define PG8_LDB(dst, b, h) do { _Pragma("unroll") for (int n = 0; n < 2; ++n) _Pragma("unroll") for (int k = 0; k < 2; ++k) dst[n][k] = *(const PG8_LAS bf16x8*)(lds + PG8_SB(b, h) + boff + n * 2048 + k * 1024); } while (0)
; #define PG8_WAIT_V(n) asm volatile("s_waitcnt vmcnt(" #n ")" ::: "memory")
; #define PG8_WAIT_L(n) asm volatile("s_waitcnt lgkmcnt(" #n ")" ::: "memory")
; #define PG8_BAR __builtin_amdgcn_s_barrier()
; #define PG8_SCHED __builtin_amdgcn_sched_barrier(0)
; #define PG8_STAGE(bufoff, gbase, voff) do { const char* _gb = (const char*)(gbase); asm volatile("" : "+s"(_gb)); _Pragma("unroll") for (int _i = 0; _i < 2; ++_i) { asm volatile("" : "+v"((voff)[_i])); \
;         __builtin_amdgcn_global_load_lds((const unsigned*)(_gb + (voff)[_i]), (PG8_LAS unsigned*)(lds + (bufoff) + ldsw + _i * 8192), 16, 0, 0); } } while (0)
; #define PG8_LDA(dst, b, h) do { _Pragma("unroll") for (int m = 0; m < 4; ++m) _Pragma("unroll") for (int k = 0; k < 2; ++k) dst[m][k] = *(const PG8_LAS bf16x8*)(lds + PG8_SA(b, h) + aoff + m * 2048 + k * 1024); } while (0)
; #define PG8_WAIT_V(n) asm volatile("s_waitcnt vmcnt(" #n ")" ::: "memory")
; template <class Epi, class Sched, bool ALIGN_EPI = false, bool SP2 = false>
; __device__ __forceinline__ void gemm_phase(PG8_LAS unsigned char* lds, const Gemm g, const Sched& S, const Epi& E) {
;     ...
;             PG8_LDB(B0, 1, 0); PG8_LDB(B1, 1, 1); PG8_SCHED; PG8_LDA(At, 1, 0); PG8_STAGE(PG8_SA(0, 1), a2 + hstep, voffA);
;             PG8_WAIT_V(8); PG8_WAIT_L(0); PG8_BAR; PG8_MMA2(0); PG8_BAR; PG8_SCHED;
;             PG8_LDA(At, 1, 1); PG8_STAGE(PG8_SB(1, 0), b3, voffB); PG8_STAGE(PG8_SB(1, 1), b3 + hstep, voffB); PG8_STAGE(PG8_SA(1, 0), a3, voffA);
;             PG8_WAIT_V(8); PG8_WAIT_L(0); PG8_BAR; PG8_MMA2(1); PG8_BAR; PG8_SCHED;
	s_add_i32 s59, 0, 0x18000
	s_add_i32 s60, 0, 0x1c000
	v_add_u32_e32 v140, s59, v174
	v_add_u32_e32 v164, s60, v174
	ds_read_b128 v[128:131], v140
	ds_read_b128 v[132:135], v140 offset:1024
	ds_read_b128 v[136:139], v140 offset:2048
	ds_read_b128 v[140:143], v140 offset:3072
	ds_read_b128 v[152:155], v164
	ds_read_b128 v[156:159], v164 offset:1024
	ds_read_b128 v[160:163], v164 offset:2048
	ds_read_b128 v[184:187], v164 offset:3072
	s_add_u32 s6, s36, 0x300000
	s_addc_u32 s7, s37, 0
	s_mov_b32 m0, s43
	ds_read_b128 v[188:191], v177 offset:32768
	ds_read_b128 v[192:195], v177 offset:33792
	ds_read_b128 v[196:199], v177 offset:34816
	ds_read_b128 v[200:203], v177 offset:35840
	ds_read_b128 v[204:207], v177 offset:36864
	ds_read_b128 v[208:211], v177 offset:37888
	ds_read_b128 v[212:215], v177 offset:38912
	ds_read_b128 v[216:219], v177 offset:39936
	s_nop 0
	global_load_lds_dwordx4 v167, s[6:7]
	s_mov_b32 m0, s44
	s_nop 0
	global_load_lds_dwordx4 v171, s[6:7]
	s_waitcnt vmcnt(8)
	s_waitcnt lgkmcnt(0)
	s_setprio 1
	s_waitcnt lgkmcnt(0)
	s_barrier
	v_mfma_f32_16x16x32_bf16 v[124:127], v[128:131], v[188:191], v[124:127]
	v_mfma_f32_16x16x32_bf16 v[120:123], v[136:139], v[188:191], v[120:123]
	v_mfma_f32_16x16x32_bf16 v[108:111], v[128:131], v[196:199], v[108:111]
	v_mfma_f32_16x16x32_bf16 v[104:107], v[136:139], v[196:199], v[104:107]
	v_mfma_f32_16x16x32_bf16 v[92:95], v[128:131], v[204:207], v[92:95]
	v_mfma_f32_16x16x32_bf16 v[88:91], v[136:139], v[204:207], v[88:91]
	v_mfma_f32_16x16x32_bf16 v[76:79], v[128:131], v[212:215], v[76:79]
	v_mfma_f32_16x16x32_bf16 v[72:75], v[136:139], v[212:215], v[72:75]
	v_mfma_f32_16x16x32_bf16 v[116:119], v[152:155], v[188:191], v[116:119]
	v_mfma_f32_16x16x32_bf16 v[112:115], v[160:163], v[188:191], v[112:115]
	v_mfma_f32_16x16x32_bf16 v[100:103], v[152:155], v[196:199], v[100:103]
	v_mfma_f32_16x16x32_bf16 v[96:99], v[160:163], v[196:199], v[96:99]
	v_mfma_f32_16x16x32_bf16 v[84:87], v[152:155], v[204:207], v[84:87]
	v_mfma_f32_16x16x32_bf16 v[80:83], v[160:163], v[204:207], v[80:83]
	v_mfma_f32_16x16x32_bf16 v[68:71], v[152:155], v[212:215], v[68:71]
	v_mfma_f32_16x16x32_bf16 v[64:67], v[160:163], v[212:215], v[64:67]
	v_mfma_f32_16x16x32_bf16 v[124:127], v[132:135], v[192:195], v[124:127]
	v_mfma_f32_16x16x32_bf16 v[120:123], v[140:143], v[192:195], v[120:123]
	v_mfma_f32_16x16x32_bf16 v[108:111], v[132:135], v[200:203], v[108:111]
	v_mfma_f32_16x16x32_bf16 v[104:107], v[140:143], v[200:203], v[104:107]
	v_mfma_f32_16x16x32_bf16 v[92:95], v[132:135], v[208:211], v[92:95]
	v_mfma_f32_16x16x32_bf16 v[88:91], v[140:143], v[208:211], v[88:91]
	v_mfma_f32_16x16x32_bf16 v[76:79], v[132:135], v[216:219], v[76:79]
	v_mfma_f32_16x16x32_bf16 v[72:75], v[140:143], v[216:219], v[72:75]
	v_mfma_f32_16x16x32_bf16 v[116:119], v[156:159], v[192:195], v[116:119]
	v_mfma_f32_16x16x32_bf16 v[112:115], v[184:187], v[192:195], v[112:115]
	v_mfma_f32_16x16x32_bf16 v[100:103], v[156:159], v[200:203], v[100:103]
	v_mfma_f32_16x16x32_bf16 v[96:99], v[184:187], v[200:203], v[96:99]
	v_mfma_f32_16x16x32_bf16 v[84:87], v[156:159], v[208:211], v[84:87]
	v_mfma_f32_16x16x32_bf16 v[80:83], v[184:187], v[208:211], v[80:83]
	v_mfma_f32_16x16x32_bf16 v[68:71], v[156:159], v[216:219], v[68:71]
	v_mfma_f32_16x16x32_bf16 v[64:67], v[184:187], v[216:219], v[64:67]
	s_setprio 0
	s_barrier
	s_nop 0
	s_add_u32 s6, s34, 0x80
	s_addc_u32 s7, s35, 0
	s_add_i32 s36, s59, s39
	s_mov_b32 m0, s36
	ds_read_b128 v[188:191], v177 offset:49152
	ds_read_b128 v[192:195], v177 offset:50176
	ds_read_b128 v[196:199], v177 offset:51200
	ds_read_b128 v[200:203], v177 offset:52224
	ds_read_b128 v[204:207], v177 offset:53248
	ds_read_b128 v[208:211], v177 offset:54272
	ds_read_b128 v[212:215], v177 offset:55296
	ds_read_b128 v[216:219], v177 offset:56320
	s_nop 0
	global_load_lds_dwordx4 v169, s[6:7]
	s_add_i32 m0, s36, 0x2000
	s_nop 0
	global_load_lds_dwordx4 v172, s[6:7]
	s_add_u32 s6, s34, 0x300080
	s_addc_u32 s7, s35, 0
	s_add_i32 s34, s60, s39
	s_mov_b32 m0, s34
	s_nop 0
	global_load_lds_dwordx4 v169, s[6:7]
	s_add_i32 m0, s34, 0x2000
	s_nop 0
	global_load_lds_dwordx4 v172, s[6:7]
	s_mov_b32 m0, s47
	s_nop 0
	global_load_lds_dwordx4 v167, s[30:31]
	s_mov_b32 m0, s48
	s_nop 0
	global_load_lds_dwordx4 v171, s[30:31]
	s_waitcnt vmcnt(8)
	s_waitcnt lgkmcnt(0)
	s_setprio 1
	s_waitcnt lgkmcnt(0)
	s_barrier
	v_mfma_f32_16x16x32_bf16 v[60:63], v[128:131], v[188:191], v[60:63]
	v_mfma_f32_16x16x32_bf16 v[56:59], v[136:139], v[188:191], v[56:59]
	v_mfma_f32_16x16x32_bf16 v[44:47], v[128:131], v[196:199], v[44:47]
	v_mfma_f32_16x16x32_bf16 v[40:43], v[136:139], v[196:199], v[40:43]
	v_mfma_f32_16x16x32_bf16 v[28:31], v[128:131], v[204:207], v[28:31]
	v_mfma_f32_16x16x32_bf16 v[24:27], v[136:139], v[204:207], v[24:27]
	v_mfma_f32_16x16x32_bf16 v[12:15], v[128:131], v[212:215], v[12:15]
	v_mfma_f32_16x16x32_bf16 v[8:11], v[136:139], v[212:215], v[8:11]
	v_mfma_f32_16x16x32_bf16 v[52:55], v[152:155], v[188:191], v[52:55]
	v_mfma_f32_16x16x32_bf16 v[48:51], v[160:163], v[188:191], v[48:51]
	v_mfma_f32_16x16x32_bf16 v[36:39], v[152:155], v[196:199], v[36:39]
	v_mfma_f32_16x16x32_bf16 v[32:35], v[160:163], v[196:199], v[32:35]
	v_mfma_f32_16x16x32_bf16 v[20:23], v[152:155], v[204:207], v[20:23]
	v_mfma_f32_16x16x32_bf16 v[16:19], v[160:163], v[204:207], v[16:19]
	v_mfma_f32_16x16x32_bf16 v[4:7], v[152:155], v[212:215], v[4:7]
	v_mfma_f32_16x16x32_bf16 v[0:3], v[160:163], v[212:215], v[0:3]
	v_mfma_f32_16x16x32_bf16 v[60:63], v[132:135], v[192:195], v[60:63]
	v_mfma_f32_16x16x32_bf16 v[56:59], v[140:143], v[192:195], v[56:59]
	v_mfma_f32_16x16x32_bf16 v[44:47], v[132:135], v[200:203], v[44:47]
	v_mfma_f32_16x16x32_bf16 v[40:43], v[140:143], v[200:203], v[40:43]
	v_mfma_f32_16x16x32_bf16 v[28:31], v[132:135], v[208:211], v[28:31]
	v_mfma_f32_16x16x32_bf16 v[24:27], v[140:143], v[208:211], v[24:27]
	v_mfma_f32_16x16x32_bf16 v[12:15], v[132:135], v[216:219], v[12:15]
	v_mfma_f32_16x16x32_bf16 v[8:11], v[140:143], v[216:219], v[8:11]
	v_mfma_f32_16x16x32_bf16 v[52:55], v[156:159], v[192:195], v[52:55]
	v_mfma_f32_16x16x32_bf16 v[48:51], v[184:187], v[192:195], v[48:51]
	v_mfma_f32_16x16x32_bf16 v[36:39], v[156:159], v[200:203], v[36:39]
	v_mfma_f32_16x16x32_bf16 v[32:35], v[184:187], v[200:203], v[32:35]
	v_mfma_f32_16x16x32_bf16 v[20:23], v[156:159], v[208:211], v[20:23]
	v_mfma_f32_16x16x32_bf16 v[16:19], v[184:187], v[208:211], v[16:19]
	v_mfma_f32_16x16x32_bf16 v[4:7], v[156:159], v[216:219], v[4:7]
	v_mfma_f32_16x16x32_bf16 v[0:3], v[184:187], v[216:219], v[0:3]
	s_setprio 0
	s_barrier
	s_add_i32 s58, s58, 2
	s_add_u32 s4, s4, 0x100
	s_addc_u32 s5, s5, 0
	s_cmpk_gt_u32 s58, 0xbd
	s_mov_b64 s[6:7], s[28:29]
	s_cbranch_scc0 .LBB0_1217
	s_and_b64 vcc, exec, s[18:19]
	s_cbranch_vccz .LBB0_1220
	s_barrier
